# GEMM phases: one static priority raise for the trailing half-workgroup; all per-segment s_setprio raise/drop removed from the K-loops
# baseline (speedup 1.0000x reference)
.LBB0_114:
	s_add_u32 s44, s22, 0x28400000
	s_addc_u32 s45, s23, 0
	s_add_u32 s33, s22, 0x2cc00000
	s_addc_u32 s90, s23, 0
	s_add_u32 s46, s22, 0x37000000
	s_addc_u32 s47, s23, 0
	s_add_u32 s0, s22, 0x41400000
	s_addc_u32 s1, s23, 0
	s_add_u32 s48, s22, 0x45c00000
	s_addc_u32 s49, s23, 0
	s_cmp_lt_i32 s68, 2
	s_cselect_b64 s[4:5], -1, 0
	s_cmp_gt_i32 s69, 1
	s_cselect_b64 s[8:9], -1, 0
	v_writelane_b32 v249, s68, 39
	s_and_b64 s[4:5], s[4:5], s[8:9]
	s_andn2_b64 vcc, exec, s[4:5]
	v_writelane_b32 v249, s69, 40
	v_writelane_b32 v249, s70, 41
	v_writelane_b32 v249, s71, 42
	s_cbranch_vccnz .LBB0_323
	s_cmpk_lt_i32 s2, 0x900
	s_cselect_b64 s[4:5], -1, 0
	s_cmpk_gt_i32 s2, 0x8ff
	s_setprio 0
	v_readfirstlane_b32 s16, v0
	s_cbranch_scc1 .LBB0_117
	s_ashr_i32 s8, s2, 31
	s_lshr_b32 s8, s8, 29
	s_add_i32 s8, s2, s8
	s_ashr_i32 s9, s8, 3
	s_and_b32 s8, s8, -8
	s_sub_i32 s8, s2, s8
	s_cmp_lt_i32 s8, 0
	s_movk_i32 s10, 0x121
	s_cselect_b32 s10, s10, 0x120
	s_mul_i32 s8, s8, s10
	s_add_i32 s8, s8, s9
	s_mul_hi_i32 s9, s8, 0x38e38e39
	s_lshr_b32 s10, s9, 31
	s_ashr_i32 s9, s9, 6
	s_add_i32 s9, s9, s10
	s_mul_i32 s10, s9, 9
	s_mulk_i32 s9, 0x120
	s_sub_i32 s8, s8, s9
	s_sext_i32_i16 s9, s8
	s_mulk_i32 s9, 0x1c72
	s_lshr_b32 s11, s9, 31
	s_lshr_b32 s9, s9, 16
	s_add_i32 s9, s9, s11
	s_mul_i32 s11, s9, 9
	s_sub_i32 s8, s8, s11
	s_sext_i32_i16 s8, s8
	s_add_i32 s12, s10, s8
	s_sext_i32_i16 s10, s9

.LBB0_120:
	s_mov_b64 s[64:65], 0x80
	s_and_b32 s11, s5, 3
	s_add_i32 m0, s73, 0x18000
	v_lshl_add_u64 v[8:9], v[8:9], 0, s[64:65]
	s_ashr_i32 s72, s3, 31
	s_ashr_i32 s91, s2, 31
	s_lshl_b32 s5, s4, 6
	s_lshl_b32 s13, s4, 13
	s_lshl_b32 s17, s11, 12
	s_waitcnt vmcnt(2)
	s_barrier
	global_load_lds_dwordx4 v[8:9], off
	v_lshl_add_u64 v[6:7], v[6:7], 0, s[64:65]
	s_add_i32 m0, s73, 0x1a000
	s_add_i32 s89, s73, 0x8000
	s_add_i32 s68, s73, 0xa000
	global_load_lds_dwordx4 v[6:7], off
	v_lshl_add_u64 v[2:3], v[2:3], 0, s[64:65]
	s_mov_b32 m0, s89
	s_add_u32 s4, s14, 0x100080
	v_writelane_b32 v249, s5, 55
	global_load_lds_dwordx4 v[2:3], off
	v_lshl_add_u64 v[2:3], v[4:5], 0, s[64:65]
	s_mov_b32 m0, s68
	s_addc_u32 s5, s15, 0
	global_load_lds_dwordx4 v[2:3], off
	s_add_i32 m0, s73, 0x1c000
	v_lshl_add_u64 v[2:3], s[4:5], 0, v[140:141]
	global_load_lds_dwordx4 v[2:3], off
	v_lshl_add_u64 v[2:3], s[4:5], 0, v[144:145]
	s_add_i32 m0, s73, 0x1e000
	v_bfe_u32 v1, v0, 4, 2
	global_load_lds_dwordx4 v[2:3], off
	v_lshlrev_b32_e32 v2, 3, v1
	v_lshlrev_b32_e32 v3, 4, v1
	v_lshlrev_b32_e32 v4, 6, v0
	s_movk_i32 s4, 0x3c0
	v_lshlrev_b32_e32 v5, 2, v0
	v_and_or_b32 v4, v4, s4, v3
	v_and_b32_e32 v5, 32, v5
	v_lshl_or_b32 v158, s11, 5, v2
	v_lshlrev_b32_e32 v2, 10, v0
	v_bitop3_b32 v155, s17, v4, v5 bitop3:0xf6
	v_and_b32_e32 v2, 0x60000, v2
	v_lshlrev_b32_e32 v4, 13, v12
	v_lshlrev_b32_e32 v6, 1, v0
	v_or3_b32 v2, v10, v2, v4
	v_and_b32_e32 v146, 32, v6
	s_cmpk_lt_u32 s16, 0x100
	s_cbranch_scc1 .Lstatprio_1
	s_setprio 1
.Lstatprio_1:
	v_add_u32_e32 v160, v2, v11
	v_lshlrev_b32_e32 v2, 6, v13
	v_and_b32_e32 v148, 15, v0
	v_lshl_add_u64 v[156:157], s[6:7], 0, v[146:147]
	s_cselect_b64 s[6:7], -1, 0
	v_and_b32_e32 v2, 0xe0000, v2
	v_lshl_or_b32 v3, v148, 6, v3
	s_waitcnt vmcnt(6)
	v_writelane_b32 v249, s6, 56
	s_cmp_eq_u32 s11, 0
	v_or3_b32 v2, v10, v2, v4
	v_bitop3_b32 v3, v3, s13, v5 bitop3:0xde
	v_writelane_b32 v249, s7, 57
	s_cselect_b64 s[6:7], -1, 0
	v_add_u32_e32 v162, v2, v11
	s_add_i32 s69, 0, 0x10000
	s_add_i32 s70, 0, 0x14000
	v_mbcnt_lo_u32_b32 v2, -1, 0
	v_cmp_gt_u32_e64 s[4:5], 2, v1
	v_or_b32_e32 v150, 16, v148
	v_or_b32_e32 v152, 32, v148
	v_or_b32_e32 v154, 48, v148
	v_or_b32_e32 v1, 0x800, v148
	v_or_b32_e32 v149, 0x810, v148
	v_or_b32_e32 v151, 0x820, v148
	v_or_b32_e32 v153, 0x830, v148
	v_writelane_b32 v249, s6, 58
	v_or_b32_e32 v159, 0x80, v158
	v_mov_b32_e32 v161, v147
	v_mov_b32_e32 v163, v147
	v_mov_b64_e32 v[164:165], 0x900
	v_mov_b64_e32 v[166:167], 0x8ff
	v_add_u32_e32 v176, s69, v155
	v_add_u32_e32 v177, s70, v155
	v_add_u32_e32 v178, 0, v3
	s_mov_b32 s71, 0x108000
	s_movk_i32 s74, 0x840
	s_movk_i32 s75, 0xe000
	s_mov_b32 s78, 0x16000000
	s_movk_i32 s79, 0x1000
	s_movk_i32 s80, 0x7fff
	s_mov_b32 s81, 0x40000
	s_mov_b32 s82, 0x12000000
	s_mov_b32 s34, 0x3e0293ee
	v_mov_b64_e32 v[168:169], 0x800
	v_mbcnt_hi_u32_b32 v179, -1, v2
	s_mov_b32 s83, 0
	s_barrier
	v_writelane_b32 v249, s7, 59
	s_branch .LBB0_123

.LBB0_125:
	s_ashr_i32 s77, s76, 31
	s_lshl_b64 s[18:19], s[76:77], 21
	s_add_u32 s58, s86, s18
	s_addc_u32 s59, s87, s19
	s_and_b64 s[18:19], s[6:7], exec
	s_cselect_b32 s11, s59, s9
	s_cselect_b32 s13, s58, s8
	s_ashr_i32 s17, s16, 31
	s_lshl_b64 s[18:19], s[16:17], 21
	s_add_u32 s36, s96, s18
	s_addc_u32 s37, s97, s19
	s_and_b64 s[18:19], s[6:7], exec
	s_cselect_b32 s17, s37, s15
	s_cselect_b32 s20, s36, s14
	s_add_u32 s8, s8, 0x100080
	s_addc_u32 s9, s9, 0
	s_add_u32 s21, s14, 0x100
	s_addc_u32 s28, s15, 0
	s_mov_b32 s29, -2
	ds_read_b128 v[130:133], v176
	ds_read_b128 v[134:137], v176 offset:1024
	ds_read_b128 v[170:173], v176 offset:2048
	ds_read_b128 v[180:183], v176 offset:3072
	ds_read_b128 v[184:187], v177
	ds_read_b128 v[188:191], v177 offset:1024
	ds_read_b128 v[192:195], v177 offset:2048
	ds_read_b128 v[198:201], v177 offset:3072
	s_add_u32 s14, s8, 0xfff00080
	s_addc_u32 s15, s9, -1
	s_cmp_eq_u32 s29, 60
	s_cselect_b32 s19, s11, s15
	s_cselect_b32 s18, s13, s14
	s_cselect_b32 s15, s17, s28
	s_cselect_b32 s14, s20, s21
	s_add_i32 m0, s73, 0xc000
	ds_read_b128 v[202:205], v178
	ds_read_b128 v[206:209], v178 offset:1024
	ds_read_b128 v[210:213], v178 offset:2048
	ds_read_b128 v[214:217], v178 offset:3072
	ds_read_b128 v[218:221], v178 offset:4096
	ds_read_b128 v[222:225], v178 offset:5120
	ds_read_b128 v[226:229], v178 offset:6144
	ds_read_b128 v[230:233], v178 offset:7168
	global_load_lds_dwordx4 v160, s[8:9]
	s_add_i32 m0, s73, 0xe000
	s_nop 0
	global_load_lds_dwordx4 v162, s[8:9]
	s_waitcnt vmcnt(8)
	s_waitcnt lgkmcnt(0)
	s_barrier
	v_mfma_f32_16x16x32_bf16 v[126:129], v[130:133], v[202:205], 0
	v_mfma_f32_16x16x32_bf16 v[122:125], v[170:173], v[202:205], 0
	v_mfma_f32_16x16x32_bf16 v[110:113], v[130:133], v[210:213], 0
	v_mfma_f32_16x16x32_bf16 v[106:109], v[170:173], v[210:213], 0
	v_mfma_f32_16x16x32_bf16 v[94:97], v[130:133], v[218:221], 0
	v_mfma_f32_16x16x32_bf16 v[90:93], v[170:173], v[218:221], 0
	v_mfma_f32_16x16x32_bf16 v[78:81], v[130:133], v[226:229], 0
	v_mfma_f32_16x16x32_bf16 v[74:77], v[170:173], v[226:229], 0
	v_mfma_f32_16x16x32_bf16 v[126:129], v[134:137], v[206:209], v[126:129]
	v_mfma_f32_16x16x32_bf16 v[122:125], v[180:183], v[206:209], v[122:125]
	v_mfma_f32_16x16x32_bf16 v[110:113], v[134:137], v[214:217], v[110:113]
	v_mfma_f32_16x16x32_bf16 v[106:109], v[180:183], v[214:217], v[106:109]
	v_mfma_f32_16x16x32_bf16 v[94:97], v[134:137], v[222:225], v[94:97]
	v_mfma_f32_16x16x32_bf16 v[90:93], v[180:183], v[222:225], v[90:93]
	v_mfma_f32_16x16x32_bf16 v[78:81], v[134:137], v[230:233], v[78:81]
	v_mfma_f32_16x16x32_bf16 v[74:77], v[180:183], v[230:233], v[74:77]
	v_mfma_f32_16x16x32_bf16 v[118:121], v[184:187], v[202:205], 0
	v_mfma_f32_16x16x32_bf16 v[114:117], v[192:195], v[202:205], 0
	v_mfma_f32_16x16x32_bf16 v[102:105], v[184:187], v[210:213], 0
	v_mfma_f32_16x16x32_bf16 v[98:101], v[192:195], v[210:213], 0
	v_mfma_f32_16x16x32_bf16 v[86:89], v[184:187], v[218:221], 0
	v_mfma_f32_16x16x32_bf16 v[82:85], v[192:195], v[218:221], 0
	v_mfma_f32_16x16x32_bf16 v[70:73], v[184:187], v[226:229], 0
	v_mfma_f32_16x16x32_bf16 v[66:69], v[192:195], v[226:229], 0
	v_mfma_f32_16x16x32_bf16 v[118:121], v[188:191], v[206:209], v[118:121]
	v_mfma_f32_16x16x32_bf16 v[114:117], v[198:201], v[206:209], v[114:117]
	v_mfma_f32_16x16x32_bf16 v[102:105], v[188:191], v[214:217], v[102:105]
	v_mfma_f32_16x16x32_bf16 v[98:101], v[198:201], v[214:217], v[98:101]
	v_mfma_f32_16x16x32_bf16 v[86:89], v[188:191], v[222:225], v[86:89]
	v_mfma_f32_16x16x32_bf16 v[82:85], v[198:201], v[222:225], v[82:85]
	v_mfma_f32_16x16x32_bf16 v[70:73], v[188:191], v[230:233], v[70:73]
	v_mfma_f32_16x16x32_bf16 v[66:69], v[198:201], v[230:233], v[66:69]
	s_barrier
	s_add_i32 s30, s69, s35
	s_mov_b32 m0, s30
	ds_read_b128 v[202:205], v178 offset:16384
	ds_read_b128 v[206:209], v178 offset:17408
	ds_read_b128 v[210:213], v178 offset:18432
	ds_read_b128 v[214:217], v178 offset:19456
	ds_read_b128 v[218:221], v178 offset:20480
	ds_read_b128 v[222:225], v178 offset:21504
	ds_read_b128 v[226:229], v178 offset:22528
	ds_read_b128 v[230:233], v178 offset:23552
	global_load_lds_dwordx4 v140, s[14:15]
	s_add_i32 m0, s30, 0x2000
	s_add_u32 s30, s14, 0x100000
	s_addc_u32 s31, s15, 0
	s_add_i32 s38, s70, s35
	global_load_lds_dwordx4 v144, s[14:15]
	s_mov_b32 m0, s38
	global_load_lds_dwordx4 v140, s[30:31]
	s_add_i32 m0, s38, 0x2000
	s_nop 0
	global_load_lds_dwordx4 v144, s[30:31]
	s_mov_b32 m0, s73
	s_nop 0
	global_load_lds_dwordx4 v138, s[18:19]
	s_mov_b32 m0, s66
	s_nop 0
	global_load_lds_dwordx4 v142, s[18:19]
	s_waitcnt vmcnt(8)
	s_waitcnt lgkmcnt(0)
	s_barrier
	v_mfma_f32_16x16x32_bf16 v[62:65], v[130:133], v[202:205], 0
	v_mfma_f32_16x16x32_bf16 v[58:61], v[170:173], v[202:205], 0
	v_mfma_f32_16x16x32_bf16 v[46:49], v[130:133], v[210:213], 0
	v_mfma_f32_16x16x32_bf16 v[42:45], v[170:173], v[210:213], 0
	v_mfma_f32_16x16x32_bf16 v[30:33], v[130:133], v[218:221], 0
	v_mfma_f32_16x16x32_bf16 v[26:29], v[170:173], v[218:221], 0
	v_mfma_f32_16x16x32_bf16 v[14:17], v[130:133], v[226:229], 0
	v_mfma_f32_16x16x32_bf16 v[10:13], v[170:173], v[226:229], 0
	v_mfma_f32_16x16x32_bf16 v[62:65], v[134:137], v[206:209], v[62:65]
	v_mfma_f32_16x16x32_bf16 v[58:61], v[180:183], v[206:209], v[58:61]
	v_mfma_f32_16x16x32_bf16 v[46:49], v[134:137], v[214:217], v[46:49]
	v_mfma_f32_16x16x32_bf16 v[42:45], v[180:183], v[214:217], v[42:45]
	v_mfma_f32_16x16x32_bf16 v[30:33], v[134:137], v[222:225], v[30:33]
	v_mfma_f32_16x16x32_bf16 v[26:29], v[180:183], v[222:225], v[26:29]
	v_mfma_f32_16x16x32_bf16 v[14:17], v[134:137], v[230:233], v[14:17]
	v_mfma_f32_16x16x32_bf16 v[10:13], v[180:183], v[230:233], v[10:13]
	v_mfma_f32_16x16x32_bf16 v[54:57], v[184:187], v[202:205], 0
	v_mfma_f32_16x16x32_bf16 v[50:53], v[192:195], v[202:205], 0
	v_mfma_f32_16x16x32_bf16 v[38:41], v[184:187], v[210:213], 0
	v_mfma_f32_16x16x32_bf16 v[34:37], v[192:195], v[210:213], 0
	v_mfma_f32_16x16x32_bf16 v[22:25], v[184:187], v[218:221], 0
	v_mfma_f32_16x16x32_bf16 v[18:21], v[192:195], v[218:221], 0
	v_mfma_f32_16x16x32_bf16 v[6:9], v[184:187], v[226:229], 0
	v_mfma_f32_16x16x32_bf16 v[2:5], v[192:195], v[226:229], 0
	v_mfma_f32_16x16x32_bf16 v[54:57], v[188:191], v[206:209], v[54:57]
	v_mfma_f32_16x16x32_bf16 v[50:53], v[198:201], v[206:209], v[50:53]
	v_mfma_f32_16x16x32_bf16 v[38:41], v[188:191], v[214:217], v[38:41]
	v_mfma_f32_16x16x32_bf16 v[34:37], v[198:201], v[214:217], v[34:37]
	v_mfma_f32_16x16x32_bf16 v[22:25], v[188:191], v[222:225], v[22:25]
	v_mfma_f32_16x16x32_bf16 v[18:21], v[198:201], v[222:225], v[18:21]
	v_mfma_f32_16x16x32_bf16 v[6:9], v[188:191], v[230:233], v[6:9]
	v_mfma_f32_16x16x32_bf16 v[2:5], v[198:201], v[230:233], v[2:5]
	s_barrier
	s_add_i32 s30, 0, 0x18000
	v_add_u32_e32 v146, s30, v155
	s_add_i32 s31, 0, 0x1c000
	ds_read_b128 v[130:133], v146
	ds_read_b128 v[134:137], v146 offset:1024
	ds_read_b128 v[170:173], v146 offset:2048
	ds_read_b128 v[180:183], v146 offset:3072
	v_add_u32_e32 v146, s31, v155
	ds_read_b128 v[184:187], v146
	ds_read_b128 v[188:191], v146 offset:1024
	ds_read_b128 v[192:195], v146 offset:2048
	ds_read_b128 v[198:201], v146 offset:3072
	s_add_u32 s18, s18, 0x100000
	s_addc_u32 s19, s19, 0
	s_mov_b32 m0, s67
	ds_read_b128 v[202:205], v178 offset:32768
	ds_read_b128 v[206:209], v178 offset:33792
	ds_read_b128 v[210:213], v178 offset:34816
	ds_read_b128 v[214:217], v178 offset:35840
	ds_read_b128 v[218:221], v178 offset:36864
	ds_read_b128 v[222:225], v178 offset:37888
	ds_read_b128 v[226:229], v178 offset:38912
	ds_read_b128 v[230:233], v178 offset:39936
	global_load_lds_dwordx4 v138, s[18:19]
	s_mov_b32 m0, s88
	s_nop 0
	global_load_lds_dwordx4 v142, s[18:19]
	s_waitcnt vmcnt(8)
	s_waitcnt lgkmcnt(0)
	s_barrier
	v_mfma_f32_16x16x32_bf16 v[126:129], v[130:133], v[202:205], v[126:129]
	v_mfma_f32_16x16x32_bf16 v[122:125], v[170:173], v[202:205], v[122:125]
	v_mfma_f32_16x16x32_bf16 v[110:113], v[130:133], v[210:213], v[110:113]
	v_mfma_f32_16x16x32_bf16 v[106:109], v[170:173], v[210:213], v[106:109]
	v_mfma_f32_16x16x32_bf16 v[94:97], v[130:133], v[218:221], v[94:97]
	v_mfma_f32_16x16x32_bf16 v[90:93], v[170:173], v[218:221], v[90:93]
	v_mfma_f32_16x16x32_bf16 v[78:81], v[130:133], v[226:229], v[78:81]
	v_mfma_f32_16x16x32_bf16 v[74:77], v[170:173], v[226:229], v[74:77]
	v_mfma_f32_16x16x32_bf16 v[126:129], v[134:137], v[206:209], v[126:129]
	v_mfma_f32_16x16x32_bf16 v[122:125], v[180:183], v[206:209], v[122:125]
	v_mfma_f32_16x16x32_bf16 v[110:113], v[134:137], v[214:217], v[110:113]
	v_mfma_f32_16x16x32_bf16 v[106:109], v[180:183], v[214:217], v[106:109]
	v_mfma_f32_16x16x32_bf16 v[94:97], v[134:137], v[222:225], v[94:97]
	v_mfma_f32_16x16x32_bf16 v[90:93], v[180:183], v[222:225], v[90:93]
	v_mfma_f32_16x16x32_bf16 v[78:81], v[134:137], v[230:233], v[78:81]
	v_mfma_f32_16x16x32_bf16 v[74:77], v[180:183], v[230:233], v[74:77]
	v_mfma_f32_16x16x32_bf16 v[118:121], v[184:187], v[202:205], v[118:121]
	v_mfma_f32_16x16x32_bf16 v[114:117], v[192:195], v[202:205], v[114:117]
	v_mfma_f32_16x16x32_bf16 v[102:105], v[184:187], v[210:213], v[102:105]
	v_mfma_f32_16x16x32_bf16 v[98:101], v[192:195], v[210:213], v[98:101]
	v_mfma_f32_16x16x32_bf16 v[86:89], v[184:187], v[218:221], v[86:89]
	v_mfma_f32_16x16x32_bf16 v[82:85], v[192:195], v[218:221], v[82:85]
	v_mfma_f32_16x16x32_bf16 v[70:73], v[184:187], v[226:229], v[70:73]
	v_mfma_f32_16x16x32_bf16 v[66:69], v[192:195], v[226:229], v[66:69]
	v_mfma_f32_16x16x32_bf16 v[118:121], v[188:191], v[206:209], v[118:121]
	v_mfma_f32_16x16x32_bf16 v[114:117], v[198:201], v[206:209], v[114:117]
	v_mfma_f32_16x16x32_bf16 v[102:105], v[188:191], v[214:217], v[102:105]
	v_mfma_f32_16x16x32_bf16 v[98:101], v[198:201], v[214:217], v[98:101]
	v_mfma_f32_16x16x32_bf16 v[86:89], v[188:191], v[222:225], v[86:89]
	v_mfma_f32_16x16x32_bf16 v[82:85], v[198:201], v[222:225], v[82:85]
	v_mfma_f32_16x16x32_bf16 v[70:73], v[188:191], v[230:233], v[70:73]
	v_mfma_f32_16x16x32_bf16 v[66:69], v[198:201], v[230:233], v[66:69]
	s_barrier
	s_add_u32 s14, s14, 0x80
	s_addc_u32 s15, s15, 0
	s_add_i32 m0, s35, 0x18000
	ds_read_b128 v[202:205], v178 offset:49152
	ds_read_b128 v[206:209], v178 offset:50176
	ds_read_b128 v[210:213], v178 offset:51200
	ds_read_b128 v[214:217], v178 offset:52224
	ds_read_b128 v[218:221], v178 offset:53248
	ds_read_b128 v[222:225], v178 offset:54272
	ds_read_b128 v[226:229], v178 offset:55296
	ds_read_b128 v[230:233], v178 offset:56320
	global_load_lds_dwordx4 v140, s[14:15]
	s_add_i32 m0, s35, 0x1a000
	s_add_u32 s18, s18, 0xfff00080
	global_load_lds_dwordx4 v144, s[14:15]
	s_addc_u32 s19, s19, -1
	s_add_u32 s14, s14, 0x100000
	s_addc_u32 s15, s15, 0
	s_add_i32 m0, s35, 0x1c000
	s_nop 0
	global_load_lds_dwordx4 v140, s[14:15]
	s_add_i32 m0, s35, 0x1e000
	s_nop 0
	global_load_lds_dwordx4 v144, s[14:15]
	s_mov_b32 m0, s89
	s_nop 0
	global_load_lds_dwordx4 v138, s[18:19]
	s_mov_b32 m0, s68
	s_nop 0
	global_load_lds_dwordx4 v142, s[18:19]
	s_waitcnt vmcnt(8)
	s_waitcnt lgkmcnt(0)
	s_barrier
	v_mfma_f32_16x16x32_bf16 v[62:65], v[130:133], v[202:205], v[62:65]
	v_mfma_f32_16x16x32_bf16 v[58:61], v[170:173], v[202:205], v[58:61]
	v_mfma_f32_16x16x32_bf16 v[46:49], v[130:133], v[210:213], v[46:49]
	v_mfma_f32_16x16x32_bf16 v[42:45], v[170:173], v[210:213], v[42:45]
	v_mfma_f32_16x16x32_bf16 v[30:33], v[130:133], v[218:221], v[30:33]
	v_mfma_f32_16x16x32_bf16 v[26:29], v[170:173], v[218:221], v[26:29]
	v_mfma_f32_16x16x32_bf16 v[14:17], v[130:133], v[226:229], v[14:17]
	v_mfma_f32_16x16x32_bf16 v[10:13], v[170:173], v[226:229], v[10:13]
	v_mfma_f32_16x16x32_bf16 v[62:65], v[134:137], v[206:209], v[62:65]
	v_mfma_f32_16x16x32_bf16 v[58:61], v[180:183], v[206:209], v[58:61]
	v_mfma_f32_16x16x32_bf16 v[46:49], v[134:137], v[214:217], v[46:49]
	v_mfma_f32_16x16x32_bf16 v[42:45], v[180:183], v[214:217], v[42:45]
	v_mfma_f32_16x16x32_bf16 v[30:33], v[134:137], v[222:225], v[30:33]
	v_mfma_f32_16x16x32_bf16 v[26:29], v[180:183], v[222:225], v[26:29]
	v_mfma_f32_16x16x32_bf16 v[14:17], v[134:137], v[230:233], v[14:17]
	v_mfma_f32_16x16x32_bf16 v[10:13], v[180:183], v[230:233], v[10:13]
	v_mfma_f32_16x16x32_bf16 v[54:57], v[184:187], v[202:205], v[54:57]
	v_mfma_f32_16x16x32_bf16 v[50:53], v[192:195], v[202:205], v[50:53]
	v_mfma_f32_16x16x32_bf16 v[38:41], v[184:187], v[210:213], v[38:41]
	v_mfma_f32_16x16x32_bf16 v[34:37], v[192:195], v[210:213], v[34:37]
	v_mfma_f32_16x16x32_bf16 v[22:25], v[184:187], v[218:221], v[22:25]
	v_mfma_f32_16x16x32_bf16 v[18:21], v[192:195], v[218:221], v[18:21]
	v_mfma_f32_16x16x32_bf16 v[6:9], v[184:187], v[226:229], v[6:9]
	v_mfma_f32_16x16x32_bf16 v[2:5], v[192:195], v[226:229], v[2:5]
	v_mfma_f32_16x16x32_bf16 v[54:57], v[188:191], v[206:209], v[54:57]
	v_mfma_f32_16x16x32_bf16 v[50:53], v[198:201], v[206:209], v[50:53]
	v_mfma_f32_16x16x32_bf16 v[38:41], v[188:191], v[214:217], v[38:41]
	v_mfma_f32_16x16x32_bf16 v[34:37], v[198:201], v[214:217], v[34:37]
	v_mfma_f32_16x16x32_bf16 v[22:25], v[188:191], v[222:225], v[22:25]
	v_mfma_f32_16x16x32_bf16 v[18:21], v[198:201], v[222:225], v[18:21]
	v_mfma_f32_16x16x32_bf16 v[6:9], v[188:191], v[230:233], v[6:9]
	v_mfma_f32_16x16x32_bf16 v[2:5], v[198:201], v[230:233], v[2:5]
	s_barrier
	s_add_i32 s29, s29, 2
	s_add_u32 s8, s8, 0x100
	s_addc_u32 s9, s9, 0
	s_add_u32 s21, s21, 0x100
	s_addc_u32 s28, s28, 0
	s_cmp_gt_u32 s29, 61
	.p2align	8
.LBB0_126:
	ds_read_b128 v[130:133], v176
	ds_read_b128 v[134:137], v176 offset:1024
	ds_read_b128 v[170:173], v176 offset:2048
	ds_read_b128 v[180:183], v176 offset:3072
	ds_read_b128 v[184:187], v177
	ds_read_b128 v[188:191], v177 offset:1024
	ds_read_b128 v[192:195], v177 offset:2048
	ds_read_b128 v[198:201], v177 offset:3072
	s_add_u32 s14, s8, 0xfff00080
	s_addc_u32 s15, s9, -1
	s_cmp_eq_u32 s29, 60
	s_cselect_b32 s19, s11, s15
	s_cselect_b32 s18, s13, s14
	s_cselect_b32 s15, s17, s28
	s_cselect_b32 s14, s20, s21
	s_add_i32 m0, s73, 0xc000
	ds_read_b128 v[202:205], v178
	ds_read_b128 v[206:209], v178 offset:1024
	ds_read_b128 v[210:213], v178 offset:2048
	ds_read_b128 v[214:217], v178 offset:3072
	ds_read_b128 v[218:221], v178 offset:4096
	ds_read_b128 v[222:225], v178 offset:5120
	ds_read_b128 v[226:229], v178 offset:6144
	ds_read_b128 v[230:233], v178 offset:7168
	global_load_lds_dwordx4 v160, s[8:9]
	s_add_i32 m0, s73, 0xe000
	s_nop 0
	global_load_lds_dwordx4 v162, s[8:9]
	s_waitcnt vmcnt(8)
	s_waitcnt lgkmcnt(0)
	s_barrier
	v_mfma_f32_16x16x32_bf16 v[126:129], v[130:133], v[202:205], v[126:129]
	v_mfma_f32_16x16x32_bf16 v[122:125], v[170:173], v[202:205], v[122:125]
	v_mfma_f32_16x16x32_bf16 v[110:113], v[130:133], v[210:213], v[110:113]
	v_mfma_f32_16x16x32_bf16 v[106:109], v[170:173], v[210:213], v[106:109]
	v_mfma_f32_16x16x32_bf16 v[94:97], v[130:133], v[218:221], v[94:97]
	v_mfma_f32_16x16x32_bf16 v[90:93], v[170:173], v[218:221], v[90:93]
	v_mfma_f32_16x16x32_bf16 v[78:81], v[130:133], v[226:229], v[78:81]
	v_mfma_f32_16x16x32_bf16 v[74:77], v[170:173], v[226:229], v[74:77]
	v_mfma_f32_16x16x32_bf16 v[126:129], v[134:137], v[206:209], v[126:129]
	v_mfma_f32_16x16x32_bf16 v[122:125], v[180:183], v[206:209], v[122:125]
	v_mfma_f32_16x16x32_bf16 v[110:113], v[134:137], v[214:217], v[110:113]
	v_mfma_f32_16x16x32_bf16 v[106:109], v[180:183], v[214:217], v[106:109]
	v_mfma_f32_16x16x32_bf16 v[94:97], v[134:137], v[222:225], v[94:97]
	v_mfma_f32_16x16x32_bf16 v[90:93], v[180:183], v[222:225], v[90:93]
	v_mfma_f32_16x16x32_bf16 v[78:81], v[134:137], v[230:233], v[78:81]
	v_mfma_f32_16x16x32_bf16 v[74:77], v[180:183], v[230:233], v[74:77]
	v_mfma_f32_16x16x32_bf16 v[118:121], v[184:187], v[202:205], v[118:121]
	v_mfma_f32_16x16x32_bf16 v[114:117], v[192:195], v[202:205], v[114:117]
	v_mfma_f32_16x16x32_bf16 v[102:105], v[184:187], v[210:213], v[102:105]
	v_mfma_f32_16x16x32_bf16 v[98:101], v[192:195], v[210:213], v[98:101]
	v_mfma_f32_16x16x32_bf16 v[86:89], v[184:187], v[218:221], v[86:89]
	v_mfma_f32_16x16x32_bf16 v[82:85], v[192:195], v[218:221], v[82:85]
	v_mfma_f32_16x16x32_bf16 v[70:73], v[184:187], v[226:229], v[70:73]
	v_mfma_f32_16x16x32_bf16 v[66:69], v[192:195], v[226:229], v[66:69]
	v_mfma_f32_16x16x32_bf16 v[118:121], v[188:191], v[206:209], v[118:121]
	v_mfma_f32_16x16x32_bf16 v[114:117], v[198:201], v[206:209], v[114:117]
	v_mfma_f32_16x16x32_bf16 v[102:105], v[188:191], v[214:217], v[102:105]
	v_mfma_f32_16x16x32_bf16 v[98:101], v[198:201], v[214:217], v[98:101]
	v_mfma_f32_16x16x32_bf16 v[86:89], v[188:191], v[222:225], v[86:89]
	v_mfma_f32_16x16x32_bf16 v[82:85], v[198:201], v[222:225], v[82:85]
	v_mfma_f32_16x16x32_bf16 v[70:73], v[188:191], v[230:233], v[70:73]
	v_mfma_f32_16x16x32_bf16 v[66:69], v[198:201], v[230:233], v[66:69]
	s_barrier
	s_add_i32 s30, s69, s35
	s_mov_b32 m0, s30
	ds_read_b128 v[202:205], v178 offset:16384
	ds_read_b128 v[206:209], v178 offset:17408
	ds_read_b128 v[210:213], v178 offset:18432
	ds_read_b128 v[214:217], v178 offset:19456
	ds_read_b128 v[218:221], v178 offset:20480
	ds_read_b128 v[222:225], v178 offset:21504
	ds_read_b128 v[226:229], v178 offset:22528
	ds_read_b128 v[230:233], v178 offset:23552
	global_load_lds_dwordx4 v140, s[14:15]
	s_add_i32 m0, s30, 0x2000
	s_add_u32 s30, s14, 0x100000
	s_addc_u32 s31, s15, 0
	s_add_i32 s38, s70, s35
	global_load_lds_dwordx4 v144, s[14:15]
	s_mov_b32 m0, s38
	global_load_lds_dwordx4 v140, s[30:31]
	s_add_i32 m0, s38, 0x2000
	s_nop 0
	global_load_lds_dwordx4 v144, s[30:31]
	s_mov_b32 m0, s73
	s_nop 0
	global_load_lds_dwordx4 v138, s[18:19]
	s_mov_b32 m0, s66
	s_nop 0
	global_load_lds_dwordx4 v142, s[18:19]
	s_waitcnt vmcnt(8)
	s_waitcnt lgkmcnt(0)
	s_barrier
	v_mfma_f32_16x16x32_bf16 v[62:65], v[130:133], v[202:205], v[62:65]
	v_mfma_f32_16x16x32_bf16 v[58:61], v[170:173], v[202:205], v[58:61]
	v_mfma_f32_16x16x32_bf16 v[46:49], v[130:133], v[210:213], v[46:49]
	v_mfma_f32_16x16x32_bf16 v[42:45], v[170:173], v[210:213], v[42:45]
	v_mfma_f32_16x16x32_bf16 v[30:33], v[130:133], v[218:221], v[30:33]
	v_mfma_f32_16x16x32_bf16 v[26:29], v[170:173], v[218:221], v[26:29]
	v_mfma_f32_16x16x32_bf16 v[14:17], v[130:133], v[226:229], v[14:17]
	v_mfma_f32_16x16x32_bf16 v[10:13], v[170:173], v[226:229], v[10:13]
	v_mfma_f32_16x16x32_bf16 v[62:65], v[134:137], v[206:209], v[62:65]
	v_mfma_f32_16x16x32_bf16 v[58:61], v[180:183], v[206:209], v[58:61]
	v_mfma_f32_16x16x32_bf16 v[46:49], v[134:137], v[214:217], v[46:49]
	v_mfma_f32_16x16x32_bf16 v[42:45], v[180:183], v[214:217], v[42:45]
	v_mfma_f32_16x16x32_bf16 v[30:33], v[134:137], v[222:225], v[30:33]
	v_mfma_f32_16x16x32_bf16 v[26:29], v[180:183], v[222:225], v[26:29]
	v_mfma_f32_16x16x32_bf16 v[14:17], v[134:137], v[230:233], v[14:17]
	v_mfma_f32_16x16x32_bf16 v[10:13], v[180:183], v[230:233], v[10:13]
	v_mfma_f32_16x16x32_bf16 v[54:57], v[184:187], v[202:205], v[54:57]
	v_mfma_f32_16x16x32_bf16 v[50:53], v[192:195], v[202:205], v[50:53]
	v_mfma_f32_16x16x32_bf16 v[38:41], v[184:187], v[210:213], v[38:41]
	v_mfma_f32_16x16x32_bf16 v[34:37], v[192:195], v[210:213], v[34:37]
	v_mfma_f32_16x16x32_bf16 v[22:25], v[184:187], v[218:221], v[22:25]
	v_mfma_f32_16x16x32_bf16 v[18:21], v[192:195], v[218:221], v[18:21]
	v_mfma_f32_16x16x32_bf16 v[6:9], v[184:187], v[226:229], v[6:9]
	v_mfma_f32_16x16x32_bf16 v[2:5], v[192:195], v[226:229], v[2:5]
	v_mfma_f32_16x16x32_bf16 v[54:57], v[188:191], v[206:209], v[54:57]
	v_mfma_f32_16x16x32_bf16 v[50:53], v[198:201], v[206:209], v[50:53]
	v_mfma_f32_16x16x32_bf16 v[38:41], v[188:191], v[214:217], v[38:41]
	v_mfma_f32_16x16x32_bf16 v[34:37], v[198:201], v[214:217], v[34:37]
	v_mfma_f32_16x16x32_bf16 v[22:25], v[188:191], v[222:225], v[22:25]
	v_mfma_f32_16x16x32_bf16 v[18:21], v[198:201], v[222:225], v[18:21]
	v_mfma_f32_16x16x32_bf16 v[6:9], v[188:191], v[230:233], v[6:9]
	v_mfma_f32_16x16x32_bf16 v[2:5], v[198:201], v[230:233], v[2:5]
	s_barrier
	s_add_i32 s30, 0, 0x18000
	v_add_u32_e32 v146, s30, v155
	s_add_i32 s31, 0, 0x1c000
	ds_read_b128 v[130:133], v146
	ds_read_b128 v[134:137], v146 offset:1024
	ds_read_b128 v[170:173], v146 offset:2048
	ds_read_b128 v[180:183], v146 offset:3072
	v_add_u32_e32 v146, s31, v155
	ds_read_b128 v[184:187], v146
	ds_read_b128 v[188:191], v146 offset:1024
	ds_read_b128 v[192:195], v146 offset:2048
	ds_read_b128 v[198:201], v146 offset:3072
	s_add_u32 s18, s18, 0x100000
	s_addc_u32 s19, s19, 0
	s_mov_b32 m0, s67
	ds_read_b128 v[202:205], v178 offset:32768
	ds_read_b128 v[206:209], v178 offset:33792
	ds_read_b128 v[210:213], v178 offset:34816
	ds_read_b128 v[214:217], v178 offset:35840
	ds_read_b128 v[218:221], v178 offset:36864
	ds_read_b128 v[222:225], v178 offset:37888
	ds_read_b128 v[226:229], v178 offset:38912
	ds_read_b128 v[230:233], v178 offset:39936
	global_load_lds_dwordx4 v138, s[18:19]
	s_mov_b32 m0, s88
	s_nop 0
	global_load_lds_dwordx4 v142, s[18:19]
	s_waitcnt vmcnt(8)
	s_waitcnt lgkmcnt(0)
	s_barrier
	v_mfma_f32_16x16x32_bf16 v[126:129], v[130:133], v[202:205], v[126:129]
	v_mfma_f32_16x16x32_bf16 v[122:125], v[170:173], v[202:205], v[122:125]
	v_mfma_f32_16x16x32_bf16 v[110:113], v[130:133], v[210:213], v[110:113]
	v_mfma_f32_16x16x32_bf16 v[106:109], v[170:173], v[210:213], v[106:109]
	v_mfma_f32_16x16x32_bf16 v[94:97], v[130:133], v[218:221], v[94:97]
	v_mfma_f32_16x16x32_bf16 v[90:93], v[170:173], v[218:221], v[90:93]
	v_mfma_f32_16x16x32_bf16 v[78:81], v[130:133], v[226:229], v[78:81]
	v_mfma_f32_16x16x32_bf16 v[74:77], v[170:173], v[226:229], v[74:77]
	v_mfma_f32_16x16x32_bf16 v[126:129], v[134:137], v[206:209], v[126:129]
	v_mfma_f32_16x16x32_bf16 v[122:125], v[180:183], v[206:209], v[122:125]
	v_mfma_f32_16x16x32_bf16 v[110:113], v[134:137], v[214:217], v[110:113]
	v_mfma_f32_16x16x32_bf16 v[106:109], v[180:183], v[214:217], v[106:109]
	v_mfma_f32_16x16x32_bf16 v[94:97], v[134:137], v[222:225], v[94:97]
	v_mfma_f32_16x16x32_bf16 v[90:93], v[180:183], v[222:225], v[90:93]
	v_mfma_f32_16x16x32_bf16 v[78:81], v[134:137], v[230:233], v[78:81]
	v_mfma_f32_16x16x32_bf16 v[74:77], v[180:183], v[230:233], v[74:77]
	v_mfma_f32_16x16x32_bf16 v[118:121], v[184:187], v[202:205], v[118:121]
	v_mfma_f32_16x16x32_bf16 v[114:117], v[192:195], v[202:205], v[114:117]
	v_mfma_f32_16x16x32_bf16 v[102:105], v[184:187], v[210:213], v[102:105]
	v_mfma_f32_16x16x32_bf16 v[98:101], v[192:195], v[210:213], v[98:101]
	v_mfma_f32_16x16x32_bf16 v[86:89], v[184:187], v[218:221], v[86:89]
	v_mfma_f32_16x16x32_bf16 v[82:85], v[192:195], v[218:221], v[82:85]
	v_mfma_f32_16x16x32_bf16 v[70:73], v[184:187], v[226:229], v[70:73]
	v_mfma_f32_16x16x32_bf16 v[66:69], v[192:195], v[226:229], v[66:69]
	v_mfma_f32_16x16x32_bf16 v[118:121], v[188:191], v[206:209], v[118:121]
	v_mfma_f32_16x16x32_bf16 v[114:117], v[198:201], v[206:209], v[114:117]
	v_mfma_f32_16x16x32_bf16 v[102:105], v[188:191], v[214:217], v[102:105]
	v_mfma_f32_16x16x32_bf16 v[98:101], v[198:201], v[214:217], v[98:101]
	v_mfma_f32_16x16x32_bf16 v[86:89], v[188:191], v[222:225], v[86:89]
	v_mfma_f32_16x16x32_bf16 v[82:85], v[198:201], v[222:225], v[82:85]
	v_mfma_f32_16x16x32_bf16 v[70:73], v[188:191], v[230:233], v[70:73]
	v_mfma_f32_16x16x32_bf16 v[66:69], v[198:201], v[230:233], v[66:69]
	s_barrier
	s_add_u32 s14, s14, 0x80
	s_addc_u32 s15, s15, 0
	s_add_i32 m0, s35, 0x18000
	ds_read_b128 v[202:205], v178 offset:49152
	ds_read_b128 v[206:209], v178 offset:50176
	ds_read_b128 v[210:213], v178 offset:51200
	ds_read_b128 v[214:217], v178 offset:52224
	ds_read_b128 v[218:221], v178 offset:53248
	ds_read_b128 v[222:225], v178 offset:54272
	ds_read_b128 v[226:229], v178 offset:55296
	ds_read_b128 v[230:233], v178 offset:56320
	global_load_lds_dwordx4 v140, s[14:15]
	s_add_i32 m0, s35, 0x1a000
	s_add_u32 s18, s18, 0xfff00080
	global_load_lds_dwordx4 v144, s[14:15]
	s_addc_u32 s19, s19, -1
	s_add_u32 s14, s14, 0x100000
	s_addc_u32 s15, s15, 0
	s_add_i32 m0, s35, 0x1c000
	s_nop 0
	global_load_lds_dwordx4 v140, s[14:15]
	s_add_i32 m0, s35, 0x1e000
	s_nop 0
	global_load_lds_dwordx4 v144, s[14:15]
	s_mov_b32 m0, s89
	s_nop 0
	global_load_lds_dwordx4 v138, s[18:19]
	s_mov_b32 m0, s68
	s_nop 0
	global_load_lds_dwordx4 v142, s[18:19]
	s_waitcnt vmcnt(8)
	s_waitcnt lgkmcnt(0)
	s_barrier
	v_mfma_f32_16x16x32_bf16 v[62:65], v[130:133], v[202:205], v[62:65]
	v_mfma_f32_16x16x32_bf16 v[58:61], v[170:173], v[202:205], v[58:61]
	v_mfma_f32_16x16x32_bf16 v[46:49], v[130:133], v[210:213], v[46:49]
	v_mfma_f32_16x16x32_bf16 v[42:45], v[170:173], v[210:213], v[42:45]
	v_mfma_f32_16x16x32_bf16 v[30:33], v[130:133], v[218:221], v[30:33]
	v_mfma_f32_16x16x32_bf16 v[26:29], v[170:173], v[218:221], v[26:29]
	v_mfma_f32_16x16x32_bf16 v[14:17], v[130:133], v[226:229], v[14:17]
	v_mfma_f32_16x16x32_bf16 v[10:13], v[170:173], v[226:229], v[10:13]
	v_mfma_f32_16x16x32_bf16 v[62:65], v[134:137], v[206:209], v[62:65]
	v_mfma_f32_16x16x32_bf16 v[58:61], v[180:183], v[206:209], v[58:61]
	v_mfma_f32_16x16x32_bf16 v[46:49], v[134:137], v[214:217], v[46:49]
	v_mfma_f32_16x16x32_bf16 v[42:45], v[180:183], v[214:217], v[42:45]
	v_mfma_f32_16x16x32_bf16 v[30:33], v[134:137], v[222:225], v[30:33]
	v_mfma_f32_16x16x32_bf16 v[26:29], v[180:183], v[222:225], v[26:29]
	v_mfma_f32_16x16x32_bf16 v[14:17], v[134:137], v[230:233], v[14:17]
	v_mfma_f32_16x16x32_bf16 v[10:13], v[180:183], v[230:233], v[10:13]
	v_mfma_f32_16x16x32_bf16 v[54:57], v[184:187], v[202:205], v[54:57]
	v_mfma_f32_16x16x32_bf16 v[50:53], v[192:195], v[202:205], v[50:53]
	v_mfma_f32_16x16x32_bf16 v[38:41], v[184:187], v[210:213], v[38:41]
	v_mfma_f32_16x16x32_bf16 v[34:37], v[192:195], v[210:213], v[34:37]
	v_mfma_f32_16x16x32_bf16 v[22:25], v[184:187], v[218:221], v[22:25]
	v_mfma_f32_16x16x32_bf16 v[18:21], v[192:195], v[218:221], v[18:21]
	v_mfma_f32_16x16x32_bf16 v[6:9], v[184:187], v[226:229], v[6:9]
	v_mfma_f32_16x16x32_bf16 v[2:5], v[192:195], v[226:229], v[2:5]
	v_mfma_f32_16x16x32_bf16 v[54:57], v[188:191], v[206:209], v[54:57]
	v_mfma_f32_16x16x32_bf16 v[50:53], v[198:201], v[206:209], v[50:53]
	v_mfma_f32_16x16x32_bf16 v[38:41], v[188:191], v[214:217], v[38:41]
	v_mfma_f32_16x16x32_bf16 v[34:37], v[198:201], v[214:217], v[34:37]
	v_mfma_f32_16x16x32_bf16 v[22:25], v[188:191], v[222:225], v[22:25]
	v_mfma_f32_16x16x32_bf16 v[18:21], v[198:201], v[222:225], v[18:21]
	v_mfma_f32_16x16x32_bf16 v[6:9], v[188:191], v[230:233], v[6:9]
	v_mfma_f32_16x16x32_bf16 v[2:5], v[198:201], v[230:233], v[2:5]
	s_barrier
	s_add_i32 s29, s29, 2
	s_add_u32 s8, s8, 0x100
	s_addc_u32 s9, s9, 0
	s_add_u32 s21, s21, 0x100
	s_addc_u32 s28, s28, 0
	s_cmp_gt_u32 s29, 61
	s_cbranch_scc0 .LBB0_126
	v_readlane_b32 s8, v249, 56
	v_readlane_b32 s9, v249, 57
	s_and_b64 vcc, exec, s[8:9]
	s_cbranch_vccz .LBB0_129
	s_barrier

.LBB0_329:
	s_setprio 0
	v_readfirstlane_b32 s16, v0
	s_lshr_b32 s16, s16, 2
	s_and_b32 s16, s16, 0x3ffffff0
	v_or_b32_e32 v46, s16, v114
	s_lshl_b32 s16, s36, 7
	s_and_b32 s16, s16, 0x780
	v_add_u32_e32 v62, s16, v46
	v_readlane_b32 s68, v249, 4
	v_lshlrev_b64 v[2:3], 2, v[62:63]
	v_readlane_b32 s69, v249, 5
	v_readlane_b32 s70, v249, 6
	v_readlane_b32 s71, v249, 7
	s_waitcnt lgkmcnt(0)
	v_lshl_add_u64 v[4:5], s[68:69], 0, v[2:3]
	v_add_co_u32_e32 v6, vcc, s42, v4
	v_readlane_b32 s80, v249, 16
	s_nop 0
	v_addc_co_u32_e32 v7, vcc, 0, v5, vcc
	v_add_co_u32_e32 v8, vcc, s43, v4
	v_readlane_b32 s81, v249, 17
	s_nop 0
	v_addc_co_u32_e32 v9, vcc, 0, v5, vcc
	v_add_co_u32_e32 v10, vcc, s50, v4
	v_readlane_b32 s74, v249, 10
	s_nop 0
	v_addc_co_u32_e32 v11, vcc, 0, v5, vcc
	global_load_dword v45, v[4:5], off
	global_load_dword v43, v[6:7], off
	global_load_dword v42, v[8:9], off
	global_load_dword v44, v[10:11], off
	v_lshl_add_u64 v[4:5], s[70:71], 0, v[2:3]
	v_readlane_b32 s75, v249, 11
	v_readlane_b32 s78, v249, 14
	v_readlane_b32 s79, v249, 15
	global_load_dword v74, v[4:5], off
	v_lshl_add_u64 v[4:5], s[80:81], 0, v[2:3]
	global_load_dword v41, v[4:5], off
	v_lshl_add_u64 v[4:5], s[74:75], 0, v[2:3]
	v_lshl_add_u64 v[2:3], s[78:79], 0, v[2:3]
	v_add_u32_e32 v6, s16, v62
	v_mov_b32_e32 v7, v63
	global_load_dword v75, v[2:3], off
	v_lshlrev_b64 v[2:3], 8, v[6:7]
	v_add_u32_e32 v6, 0x80, v6
	v_lshlrev_b64 v[6:7], 8, v[6:7]
	v_lshl_add_u64 v[2:3], v[60:61], 0, v[2:3]
	v_lshl_add_u64 v[6:7], v[60:61], 0, v[6:7]
	global_load_dword v40, v[4:5], off
	global_load_dwordx4 v[26:29], v[2:3], off
	global_load_dwordx4 v[18:21], v[2:3], off offset:64
	global_load_dwordx4 v[10:13], v[2:3], off offset:128
	s_nop 0
	global_load_dwordx4 v[2:5], v[2:3], off offset:192
	s_nop 0
	global_load_dwordx4 v[30:33], v[6:7], off
	global_load_dwordx4 v[22:25], v[6:7], off offset:64
	global_load_dwordx4 v[14:17], v[6:7], off offset:128
	s_nop 0
	global_load_dwordx4 v[6:9], v[6:7], off offset:192
	s_ashr_i32 s16, s36, 4
	s_ashr_i32 s17, s16, 31
	s_lshl_b64 s[20:21], s[16:17], 11
	s_and_b64 vcc, exec, s[14:15]
	v_mov_b32_e32 v73, v63
	v_readlane_b32 s72, v249, 8
	v_readlane_b32 s73, v249, 9
	v_readlane_b32 s76, v249, 12
	v_readlane_b32 s77, v249, 13
	v_readlane_b32 s82, v249, 18
	v_readlane_b32 s83, v249, 19
	s_cbranch_vccnz .LBB0_331
	s_lshl_b64 s[28:29], s[20:21], 2
	s_add_u32 s28, s62, s28
	s_addc_u32 s29, s63, s29
	v_lshl_add_u64 v[34:35], v[62:63], 2, s[28:29]
	global_load_dword v73, v[34:35], off

.LBB0_418:
	s_andn2_b64 vcc, exec, s[14:15]
	s_cbranch_vccnz .LBB0_500
	s_setprio 0
	v_readfirstlane_b32 s15, v0
	s_lshr_b32 s15, s15, 2
	s_lshl_b32 s14, s2, 7
	s_and_b32 s15, s15, 0x3ffffff0
	s_and_b32 s14, s14, 0x780
	v_or_b32_e32 v42, s15, v114
	v_mov_b32_e32 v71, 0
	v_add_u32_e32 v66, s14, v42
	v_mov_b32_e32 v67, v71
	v_readlane_b32 s56, v249, 4
	v_lshlrev_b64 v[2:3], 2, v[66:67]
	v_readlane_b32 s57, v249, 5
	s_movk_i32 s15, 0x2000
	v_readlane_b32 s58, v249, 6
	s_waitcnt lgkmcnt(0)
	v_lshl_add_u64 v[4:5], s[56:57], 0, v[2:3]
	v_add_co_u32_e32 v6, vcc, s15, v4
	s_movk_i32 s15, 0x4000
	s_nop 0
	v_addc_co_u32_e32 v7, vcc, 0, v5, vcc
	v_add_co_u32_e32 v8, vcc, s15, v4
	s_movk_i32 s15, 0x6000
	s_nop 0
	v_addc_co_u32_e32 v9, vcc, 0, v5, vcc
	v_readlane_b32 s59, v249, 7
	v_add_co_u32_e32 v10, vcc, s15, v4
	v_readlane_b32 s68, v249, 16
	v_readlane_b32 s69, v249, 17
	v_addc_co_u32_e32 v11, vcc, 0, v5, vcc
	global_load_dword v133, v[4:5], off
	global_load_dword v134, v[6:7], off
	global_load_dword v135, v[8:9], off
	global_load_dword v136, v[10:11], off
	v_lshl_add_u64 v[4:5], s[58:59], 0, v[2:3]
	v_readlane_b32 s62, v249, 10
	v_readlane_b32 s63, v249, 11
	v_readlane_b32 s66, v249, 14
	v_readlane_b32 s67, v249, 15
	global_load_dword v137, v[4:5], off
	v_lshl_add_u64 v[4:5], s[68:69], 0, v[2:3]
	global_load_dword v36, v[4:5], off
	v_lshl_add_u64 v[4:5], s[62:63], 0, v[2:3]
	v_lshl_add_u64 v[2:3], s[66:67], 0, v[2:3]
	v_add_u32_e32 v70, s14, v66
	global_load_dword v43, v[2:3], off
	v_lshlrev_b64 v[2:3], 8, v[70:71]
	v_add_u32_e32 v70, 0x80, v70
	v_lshlrev_b64 v[18:19], 8, v[70:71]
	v_lshl_add_u64 v[14:15], v[60:61], 0, v[2:3]
	v_lshl_add_u64 v[30:31], v[60:61], 0, v[18:19]
	global_load_dword v1, v[4:5], off
	s_nop 0
	global_load_dwordx4 v[2:5], v[14:15], off
	global_load_dwordx4 v[6:9], v[14:15], off offset:64
	global_load_dwordx4 v[10:13], v[14:15], off offset:128
	s_nop 0
	global_load_dwordx4 v[14:17], v[14:15], off offset:192
	s_nop 0
	global_load_dwordx4 v[18:21], v[30:31], off
	global_load_dwordx4 v[22:25], v[30:31], off offset:64
	global_load_dwordx4 v[26:29], v[30:31], off offset:128
	s_nop 0
	global_load_dwordx4 v[30:33], v[30:31], off offset:192
	s_ashr_i32 s14, s2, 4
	s_lshl_b32 s35, s14, 12
	v_or_b32_e32 v40, s35, v58
	v_ashrrev_i32_e32 v41, 31, v40
	v_lshlrev_b64 v[34:35], 12, v[40:41]
	v_lshl_add_u64 v[34:35], s[0:1], 0, v[34:35]
	v_lshlrev_b32_e32 v70, 1, v66
	s_movk_i32 s16, 0xd000
	v_lshl_add_u64 v[34:35], v[34:35], 0, v[70:71]
	s_mov_b32 s17, -1
	v_lshl_add_u64 v[38:39], v[34:35], 0, s[16:17]
	v_mov_b32_e32 v70, 0
	v_readlane_b32 s60, v249, 8
	v_readlane_b32 s61, v249, 9
	v_readlane_b32 s64, v249, 12
	v_readlane_b32 s65, v249, 13
	v_readlane_b32 s70, v249, 18
	v_readlane_b32 s71, v249, 19
	s_and_saveexec_b64 s[16:17], s[12:13]
	s_cbranch_execz .LBB0_421
	global_load_ushort v34, v[38:39], off
	s_waitcnt vmcnt(0)
	v_lshlrev_b32_e32 v70, 16, v34

.LBB0_666:
	s_add_u32 s10, s22, 0xe400000
	s_addc_u32 s11, s23, 0
	s_add_u32 s8, s22, 0x16400000
	s_addc_u32 s9, s23, 0
	s_add_u32 s12, s22, 0x10000
	s_addc_u32 s13, s23, 0
	s_cmp_lt_i32 s68, 4
	s_cselect_b64 s[0:1], -1, 0
	s_cmp_gt_i32 s69, 3
	s_cselect_b64 s[4:5], -1, 0
	s_and_b64 s[0:1], s[0:1], s[4:5]
	s_andn2_b64 vcc, exec, s[0:1]
	s_mov_b64 s[72:73], s[68:69]
	s_cbranch_vccnz .LBB0_797
	s_cmpk_lt_i32 s2, 0x480
	s_cselect_b64 s[0:1], -1, 0
	s_cmpk_gt_i32 s2, 0x47f
	s_setprio 0
	v_readfirstlane_b32 s4, v0
	s_cbranch_scc1 .LBB0_669
	s_ashr_i32 s5, s2, 31
	s_lshr_b32 s5, s5, 29
	s_add_i32 s5, s2, s5
	s_ashr_i32 s6, s5, 3
	s_and_b32 s5, s5, -8
	s_sub_i32 s5, s2, s5
	s_cmp_lt_i32 s5, 0
	s_movk_i32 s7, 0x91
	s_cselect_b32 s7, s7, 0x90
	s_mul_i32 s5, s5, s7
	s_add_i32 s5, s5, s6
	s_mul_hi_i32 s6, s5, 0x38e38e39
	s_lshr_b32 s7, s6, 31
	s_ashr_i32 s6, s6, 5
	s_add_i32 s6, s6, s7
	s_mul_i32 s7, s6, 9
	s_mulk_i32 s6, 0x90
	s_sub_i32 s5, s5, s6
	s_sext_i32_i16 s6, s5
	s_mulk_i32 s6, 0x1c72
	s_lshr_b32 s14, s6, 31
	s_lshr_b32 s6, s6, 16
	s_add_i32 s6, s6, s14
	s_mul_i32 s14, s6, 9
	s_sub_i32 s5, s5, s14
	s_sext_i32_i16 s5, s5
	s_add_i32 s56, s7, s5
	s_sext_i32_i16 s6, s6

.LBB0_672:
	s_lshl_b32 s1, s1, 5
	s_mov_b64 s[16:17], 0x80
	s_and_b32 s7, s1, 0x60
	s_add_i32 m0, s64, 0x18000
	v_lshl_add_u64 v[8:9], v[8:9], 0, s[16:17]
	s_lshl_b32 s5, s0, 13
	s_lshl_b32 s1, s7, 7
	s_waitcnt vmcnt(2)
	s_barrier
	global_load_lds_dwordx4 v[8:9], off
	v_lshl_add_u64 v[6:7], v[6:7], 0, s[16:17]
	s_add_i32 m0, s64, 0x1a000
	s_add_i32 s69, s64, 0x8000
	s_add_i32 s70, s64, 0xa000
	global_load_lds_dwordx4 v[6:7], off
	v_lshl_add_u64 v[2:3], v[2:3], 0, s[16:17]
	s_mov_b32 m0, s69
	s_add_u32 s18, s60, 0x100080
	global_load_lds_dwordx4 v[2:3], off
	v_lshl_add_u64 v[2:3], v[4:5], 0, s[16:17]
	s_mov_b32 m0, s70
	s_addc_u32 s19, s61, 0
	global_load_lds_dwordx4 v[2:3], off
	s_add_i32 m0, s64, 0x1c000
	v_lshl_add_u64 v[2:3], s[18:19], 0, v[132:133]
	global_load_lds_dwordx4 v[2:3], off
	v_lshl_add_u64 v[2:3], s[18:19], 0, v[136:137]
	s_add_i32 m0, s64, 0x1e000
	v_lshlrev_b32_e32 v6, 6, v0
	global_load_lds_dwordx4 v[2:3], off
	v_and_b32_e32 v2, 15, v0
	v_bfe_u32 v3, v0, 4, 2
	v_lshl_or_b32 v156, s0, 6, v2
	v_lshlrev_b32_e32 v4, 4, v3
	s_movk_i32 s0, 0x3c0
	v_lshl_or_b32 v2, v2, 6, v4
	v_and_b32_e32 v5, 32, v1
	v_and_or_b32 v4, v6, s0, v4
	v_bitop3_b32 v157, s1, v4, v5 bitop3:0xf6
	v_cmp_eq_u32_e64 s[0:1], 0, v3
	v_lshl_or_b32 v158, v3, 3, s7
	v_lshlrev_b32_e32 v3, 10, v0
	v_and_b32_e32 v3, 0x60000, v3
	v_lshlrev_b32_e32 v4, 13, v12
	v_or3_b32 v3, v10, v3, v4
	v_add_u32_e32 v140, v3, v11
	v_lshlrev_b32_e32 v3, 6, v13
	v_bitop3_b32 v2, v2, s5, v5 bitop3:0xde
	s_waitcnt vmcnt(6)
	s_cmpk_lt_u32 s4, 0x100
	s_cbranch_scc1 .Lstatprio_2
	s_setprio 1
.Lstatprio_2:
	v_and_b32_e32 v3, 0xe0000, v3
	s_cselect_b64 s[18:19], -1, 0
	v_or3_b32 v3, v10, v3, v4
	s_add_i32 s74, 0, 0x10000
	s_add_i32 s75, 0, 0x14000
	v_add_u32_e32 v161, 0, v2
	s_brev_b32 s20, 15
	v_mbcnt_lo_u32_b32 v2, -1, 0
	s_mov_b32 s28, 0xf0040000
	s_mov_b32 s30, 0xf0080000
	s_mov_b32 s34, 0xf00c0000
	s_mov_b32 s36, 0xf0200000
	s_mov_b32 s38, 0xf0240000
	s_mov_b32 s40, 0xf0280000
	s_mov_b32 s42, 0xf02c0000
	s_ashr_i32 s71, s3, 31
	s_ashr_i32 s72, s2, 31
	v_mov_b32_e32 v141, v139
	v_add_u32_e32 v142, v3, v11
	v_mov_b32_e32 v143, v139
	v_mov_b64_e32 v[144:145], 0x480
	v_mov_b64_e32 v[146:147], 0x47f
	s_movk_i32 s73, 0x91
	v_add_u32_e32 v159, s74, v157
	v_add_u32_e32 v160, s75, v157
	s_mov_b32 s21, -1
	s_waitcnt vmcnt(0)
	v_mbcnt_hi_u32_b32 v162, -1, v2
	s_mov_b32 s29, -1
	s_mov_b32 s31, -1
	s_mov_b32 s35, -1
	s_mov_b32 s37, -1
	s_mov_b32 s39, -1
	s_mov_b32 s41, -1
	s_mov_b32 s43, -1
	s_barrier
	s_branch .LBB0_675

.LBB0_677:
	s_ashr_i32 s47, s46, 31
	s_lshl_b64 s[48:49], s[46:47], 21
	s_add_u32 s48, s86, s48
	s_addc_u32 s49, s87, s49
	s_and_b64 s[50:51], s[4:5], exec
	s_cselect_b32 s7, s49, s59
	s_cselect_b32 s47, s48, s58
	s_ashr_i32 s45, s44, 31
	s_lshl_b64 s[50:51], s[44:45], 21
	s_add_u32 s50, s82, s50
	s_addc_u32 s51, s83, s51
	s_and_b64 s[62:63], s[4:5], exec
	s_cselect_b32 s45, s51, s61
	s_cselect_b32 s57, s50, s60
	s_add_u32 s58, s58, 0x100080
	s_addc_u32 s59, s59, 0
	s_add_u32 s76, s60, 0x100
	s_addc_u32 s77, s61, 0
	s_mov_b32 s78, -2
	s_waitcnt lgkmcnt(0)
	ds_read_b128 v[148:151], v159
	ds_read_b128 v[152:155], v159 offset:1024
	ds_read_b128 v[164:167], v159 offset:2048
	ds_read_b128 v[168:171], v159 offset:3072
	ds_read_b128 v[172:175], v160
	ds_read_b128 v[176:179], v160 offset:1024
	ds_read_b128 v[180:183], v160 offset:2048
	ds_read_b128 v[184:187], v160 offset:3072
	s_add_u32 s60, s58, 0xfff00080
	s_addc_u32 s61, s59, -1
	s_cmp_eq_u32 s78, 60
	s_cselect_b32 s63, s7, s61
	s_cselect_b32 s62, s47, s60
	s_cselect_b32 s61, s45, s77
	s_cselect_b32 s60, s57, s76
	s_add_i32 m0, s64, 0xc000
	ds_read_b128 v[188:191], v161
	ds_read_b128 v[192:195], v161 offset:1024
	ds_read_b128 v[198:201], v161 offset:2048
	ds_read_b128 v[202:205], v161 offset:3072
	ds_read_b128 v[206:209], v161 offset:4096
	ds_read_b128 v[210:213], v161 offset:5120
	ds_read_b128 v[214:217], v161 offset:6144
	ds_read_b128 v[218:221], v161 offset:7168
	global_load_lds_dwordx4 v140, s[58:59]
	s_add_i32 m0, s64, 0xe000
	s_nop 0
	global_load_lds_dwordx4 v142, s[58:59]
	s_waitcnt vmcnt(32)
	s_waitcnt lgkmcnt(0)
	s_barrier
	v_mfma_f32_16x16x32_bf16 v[126:129], v[148:151], v[188:191], 0
	v_mfma_f32_16x16x32_bf16 v[122:125], v[164:167], v[188:191], 0
	v_mfma_f32_16x16x32_bf16 v[110:113], v[148:151], v[198:201], 0
	v_mfma_f32_16x16x32_bf16 v[106:109], v[164:167], v[198:201], 0
	v_mfma_f32_16x16x32_bf16 v[94:97], v[148:151], v[206:209], 0
	v_mfma_f32_16x16x32_bf16 v[90:93], v[164:167], v[206:209], 0
	v_mfma_f32_16x16x32_bf16 v[78:81], v[148:151], v[214:217], 0
	v_mfma_f32_16x16x32_bf16 v[74:77], v[164:167], v[214:217], 0
	v_mfma_f32_16x16x32_bf16 v[126:129], v[152:155], v[192:195], v[126:129]
	v_mfma_f32_16x16x32_bf16 v[122:125], v[168:171], v[192:195], v[122:125]
	v_mfma_f32_16x16x32_bf16 v[110:113], v[152:155], v[202:205], v[110:113]
	v_mfma_f32_16x16x32_bf16 v[106:109], v[168:171], v[202:205], v[106:109]
	v_mfma_f32_16x16x32_bf16 v[94:97], v[152:155], v[210:213], v[94:97]
	v_mfma_f32_16x16x32_bf16 v[90:93], v[168:171], v[210:213], v[90:93]
	v_mfma_f32_16x16x32_bf16 v[78:81], v[152:155], v[218:221], v[78:81]
	v_mfma_f32_16x16x32_bf16 v[74:77], v[168:171], v[218:221], v[74:77]
	v_mfma_f32_16x16x32_bf16 v[118:121], v[172:175], v[188:191], 0
	v_mfma_f32_16x16x32_bf16 v[114:117], v[180:183], v[188:191], 0
	v_mfma_f32_16x16x32_bf16 v[102:105], v[172:175], v[198:201], 0
	v_mfma_f32_16x16x32_bf16 v[98:101], v[180:183], v[198:201], 0
	v_mfma_f32_16x16x32_bf16 v[86:89], v[172:175], v[206:209], 0
	v_mfma_f32_16x16x32_bf16 v[82:85], v[180:183], v[206:209], 0
	v_mfma_f32_16x16x32_bf16 v[70:73], v[172:175], v[214:217], 0
	v_mfma_f32_16x16x32_bf16 v[66:69], v[180:183], v[214:217], 0
	v_mfma_f32_16x16x32_bf16 v[118:121], v[176:179], v[192:195], v[118:121]
	v_mfma_f32_16x16x32_bf16 v[114:117], v[184:187], v[192:195], v[114:117]
	v_mfma_f32_16x16x32_bf16 v[102:105], v[176:179], v[202:205], v[102:105]
	v_mfma_f32_16x16x32_bf16 v[98:101], v[184:187], v[202:205], v[98:101]
	v_mfma_f32_16x16x32_bf16 v[86:89], v[176:179], v[210:213], v[86:89]
	v_mfma_f32_16x16x32_bf16 v[82:85], v[184:187], v[210:213], v[82:85]
	v_mfma_f32_16x16x32_bf16 v[70:73], v[176:179], v[218:221], v[70:73]
	v_mfma_f32_16x16x32_bf16 v[66:69], v[184:187], v[218:221], v[66:69]
	s_barrier
	s_add_i32 s79, s74, s33
	s_mov_b32 m0, s79
	ds_read_b128 v[188:191], v161 offset:16384
	ds_read_b128 v[192:195], v161 offset:17408
	ds_read_b128 v[198:201], v161 offset:18432
	ds_read_b128 v[202:205], v161 offset:19456
	ds_read_b128 v[206:209], v161 offset:20480
	ds_read_b128 v[210:213], v161 offset:21504
	ds_read_b128 v[214:217], v161 offset:22528
	ds_read_b128 v[218:221], v161 offset:23552
	global_load_lds_dwordx4 v132, s[60:61]
	s_add_i32 m0, s79, 0x2000
	s_add_u32 s80, s60, 0x100000
	s_addc_u32 s81, s61, 0
	s_add_i32 s79, s75, s33
	global_load_lds_dwordx4 v136, s[60:61]
	s_mov_b32 m0, s79
	global_load_lds_dwordx4 v132, s[80:81]
	s_add_i32 m0, s79, 0x2000
	s_nop 0
	global_load_lds_dwordx4 v136, s[80:81]
	s_mov_b32 m0, s64
	s_nop 0
	global_load_lds_dwordx4 v130, s[62:63]
	s_mov_b32 m0, s65
	s_nop 0
	global_load_lds_dwordx4 v134, s[62:63]
	s_waitcnt vmcnt(32)
	s_waitcnt lgkmcnt(0)
	s_barrier
	v_mfma_f32_16x16x32_bf16 v[62:65], v[148:151], v[188:191], 0
	v_mfma_f32_16x16x32_bf16 v[58:61], v[164:167], v[188:191], 0
	v_mfma_f32_16x16x32_bf16 v[46:49], v[148:151], v[198:201], 0
	v_mfma_f32_16x16x32_bf16 v[42:45], v[164:167], v[198:201], 0
	v_mfma_f32_16x16x32_bf16 v[30:33], v[148:151], v[206:209], 0
	v_mfma_f32_16x16x32_bf16 v[26:29], v[164:167], v[206:209], 0
	v_mfma_f32_16x16x32_bf16 v[14:17], v[148:151], v[214:217], 0
	v_mfma_f32_16x16x32_bf16 v[10:13], v[164:167], v[214:217], 0
	v_mfma_f32_16x16x32_bf16 v[62:65], v[152:155], v[192:195], v[62:65]
	v_mfma_f32_16x16x32_bf16 v[58:61], v[168:171], v[192:195], v[58:61]
	v_mfma_f32_16x16x32_bf16 v[46:49], v[152:155], v[202:205], v[46:49]
	v_mfma_f32_16x16x32_bf16 v[42:45], v[168:171], v[202:205], v[42:45]
	v_mfma_f32_16x16x32_bf16 v[30:33], v[152:155], v[210:213], v[30:33]
	v_mfma_f32_16x16x32_bf16 v[26:29], v[168:171], v[210:213], v[26:29]
	v_mfma_f32_16x16x32_bf16 v[14:17], v[152:155], v[218:221], v[14:17]
	v_mfma_f32_16x16x32_bf16 v[10:13], v[168:171], v[218:221], v[10:13]
	v_mfma_f32_16x16x32_bf16 v[54:57], v[172:175], v[188:191], 0
	v_mfma_f32_16x16x32_bf16 v[50:53], v[180:183], v[188:191], 0
	v_mfma_f32_16x16x32_bf16 v[38:41], v[172:175], v[198:201], 0
	v_mfma_f32_16x16x32_bf16 v[34:37], v[180:183], v[198:201], 0
	v_mfma_f32_16x16x32_bf16 v[22:25], v[172:175], v[206:209], 0
	v_mfma_f32_16x16x32_bf16 v[18:21], v[180:183], v[206:209], 0
	v_mfma_f32_16x16x32_bf16 v[6:9], v[172:175], v[214:217], 0
	v_mfma_f32_16x16x32_bf16 v[2:5], v[180:183], v[214:217], 0
	v_mfma_f32_16x16x32_bf16 v[54:57], v[176:179], v[192:195], v[54:57]
	v_mfma_f32_16x16x32_bf16 v[50:53], v[184:187], v[192:195], v[50:53]
	v_mfma_f32_16x16x32_bf16 v[38:41], v[176:179], v[202:205], v[38:41]
	v_mfma_f32_16x16x32_bf16 v[34:37], v[184:187], v[202:205], v[34:37]
	v_mfma_f32_16x16x32_bf16 v[22:25], v[176:179], v[210:213], v[22:25]
	v_mfma_f32_16x16x32_bf16 v[18:21], v[184:187], v[210:213], v[18:21]
	v_mfma_f32_16x16x32_bf16 v[6:9], v[176:179], v[218:221], v[6:9]
	v_mfma_f32_16x16x32_bf16 v[2:5], v[184:187], v[218:221], v[2:5]
	s_barrier
	s_add_i32 s79, 0, 0x18000
	v_add_u32_e32 v138, s79, v157
	s_add_i32 s80, 0, 0x1c000
	ds_read_b128 v[148:151], v138
	ds_read_b128 v[152:155], v138 offset:1024
	ds_read_b128 v[164:167], v138 offset:2048
	ds_read_b128 v[168:171], v138 offset:3072
	v_add_u32_e32 v138, s80, v157
	ds_read_b128 v[172:175], v138
	ds_read_b128 v[176:179], v138 offset:1024
	ds_read_b128 v[180:183], v138 offset:2048
	ds_read_b128 v[184:187], v138 offset:3072
	s_add_u32 s62, s62, 0x100000
	s_addc_u32 s63, s63, 0
	s_mov_b32 m0, s66
	ds_read_b128 v[188:191], v161 offset:32768
	ds_read_b128 v[192:195], v161 offset:33792
	ds_read_b128 v[198:201], v161 offset:34816
	ds_read_b128 v[202:205], v161 offset:35840
	ds_read_b128 v[206:209], v161 offset:36864
	ds_read_b128 v[210:213], v161 offset:37888
	ds_read_b128 v[214:217], v161 offset:38912
	ds_read_b128 v[218:221], v161 offset:39936
	global_load_lds_dwordx4 v130, s[62:63]
	s_mov_b32 m0, s67
	s_nop 0
	global_load_lds_dwordx4 v134, s[62:63]
	s_waitcnt vmcnt(8)
	s_waitcnt lgkmcnt(0)
	s_barrier
	v_mfma_f32_16x16x32_bf16 v[126:129], v[148:151], v[188:191], v[126:129]
	v_mfma_f32_16x16x32_bf16 v[122:125], v[164:167], v[188:191], v[122:125]
	v_mfma_f32_16x16x32_bf16 v[110:113], v[148:151], v[198:201], v[110:113]
	v_mfma_f32_16x16x32_bf16 v[106:109], v[164:167], v[198:201], v[106:109]
	v_mfma_f32_16x16x32_bf16 v[94:97], v[148:151], v[206:209], v[94:97]
	v_mfma_f32_16x16x32_bf16 v[90:93], v[164:167], v[206:209], v[90:93]
	v_mfma_f32_16x16x32_bf16 v[78:81], v[148:151], v[214:217], v[78:81]
	v_mfma_f32_16x16x32_bf16 v[74:77], v[164:167], v[214:217], v[74:77]
	v_mfma_f32_16x16x32_bf16 v[126:129], v[152:155], v[192:195], v[126:129]
	v_mfma_f32_16x16x32_bf16 v[122:125], v[168:171], v[192:195], v[122:125]
	v_mfma_f32_16x16x32_bf16 v[110:113], v[152:155], v[202:205], v[110:113]
	v_mfma_f32_16x16x32_bf16 v[106:109], v[168:171], v[202:205], v[106:109]
	v_mfma_f32_16x16x32_bf16 v[94:97], v[152:155], v[210:213], v[94:97]
	v_mfma_f32_16x16x32_bf16 v[90:93], v[168:171], v[210:213], v[90:93]
	v_mfma_f32_16x16x32_bf16 v[78:81], v[152:155], v[218:221], v[78:81]
	v_mfma_f32_16x16x32_bf16 v[74:77], v[168:171], v[218:221], v[74:77]
	v_mfma_f32_16x16x32_bf16 v[118:121], v[172:175], v[188:191], v[118:121]
	v_mfma_f32_16x16x32_bf16 v[114:117], v[180:183], v[188:191], v[114:117]
	v_mfma_f32_16x16x32_bf16 v[102:105], v[172:175], v[198:201], v[102:105]
	v_mfma_f32_16x16x32_bf16 v[98:101], v[180:183], v[198:201], v[98:101]
	v_mfma_f32_16x16x32_bf16 v[86:89], v[172:175], v[206:209], v[86:89]
	v_mfma_f32_16x16x32_bf16 v[82:85], v[180:183], v[206:209], v[82:85]
	v_mfma_f32_16x16x32_bf16 v[70:73], v[172:175], v[214:217], v[70:73]
	v_mfma_f32_16x16x32_bf16 v[66:69], v[180:183], v[214:217], v[66:69]
	v_mfma_f32_16x16x32_bf16 v[118:121], v[176:179], v[192:195], v[118:121]
	v_mfma_f32_16x16x32_bf16 v[114:117], v[184:187], v[192:195], v[114:117]
	v_mfma_f32_16x16x32_bf16 v[102:105], v[176:179], v[202:205], v[102:105]
	v_mfma_f32_16x16x32_bf16 v[98:101], v[184:187], v[202:205], v[98:101]
	v_mfma_f32_16x16x32_bf16 v[86:89], v[176:179], v[210:213], v[86:89]
	v_mfma_f32_16x16x32_bf16 v[82:85], v[184:187], v[210:213], v[82:85]
	v_mfma_f32_16x16x32_bf16 v[70:73], v[176:179], v[218:221], v[70:73]
	v_mfma_f32_16x16x32_bf16 v[66:69], v[184:187], v[218:221], v[66:69]
	s_barrier
	s_add_u32 s60, s60, 0x80
	s_addc_u32 s61, s61, 0
	s_add_i32 m0, s33, 0x18000
	ds_read_b128 v[188:191], v161 offset:49152
	ds_read_b128 v[192:195], v161 offset:50176
	ds_read_b128 v[198:201], v161 offset:51200
	ds_read_b128 v[202:205], v161 offset:52224
	ds_read_b128 v[206:209], v161 offset:53248
	ds_read_b128 v[210:213], v161 offset:54272
	ds_read_b128 v[214:217], v161 offset:55296
	ds_read_b128 v[218:221], v161 offset:56320
	global_load_lds_dwordx4 v132, s[60:61]
	s_add_i32 m0, s33, 0x1a000
	s_add_u32 s62, s62, 0xfff00080
	global_load_lds_dwordx4 v136, s[60:61]
	s_addc_u32 s63, s63, -1
	s_add_u32 s60, s60, 0x100000
	s_addc_u32 s61, s61, 0
	s_add_i32 m0, s33, 0x1c000
	s_nop 0
	global_load_lds_dwordx4 v132, s[60:61]
	s_add_i32 m0, s33, 0x1e000
	s_nop 0
	global_load_lds_dwordx4 v136, s[60:61]
	s_mov_b32 m0, s69
	s_nop 0
	global_load_lds_dwordx4 v130, s[62:63]
	s_mov_b32 m0, s70
	s_nop 0
	global_load_lds_dwordx4 v134, s[62:63]
	s_waitcnt vmcnt(8)
	s_waitcnt lgkmcnt(0)
	s_barrier
	v_mfma_f32_16x16x32_bf16 v[62:65], v[148:151], v[188:191], v[62:65]
	v_mfma_f32_16x16x32_bf16 v[58:61], v[164:167], v[188:191], v[58:61]
	v_mfma_f32_16x16x32_bf16 v[46:49], v[148:151], v[198:201], v[46:49]
	v_mfma_f32_16x16x32_bf16 v[42:45], v[164:167], v[198:201], v[42:45]
	v_mfma_f32_16x16x32_bf16 v[30:33], v[148:151], v[206:209], v[30:33]
	v_mfma_f32_16x16x32_bf16 v[26:29], v[164:167], v[206:209], v[26:29]
	v_mfma_f32_16x16x32_bf16 v[14:17], v[148:151], v[214:217], v[14:17]
	v_mfma_f32_16x16x32_bf16 v[10:13], v[164:167], v[214:217], v[10:13]
	v_mfma_f32_16x16x32_bf16 v[62:65], v[152:155], v[192:195], v[62:65]
	v_mfma_f32_16x16x32_bf16 v[58:61], v[168:171], v[192:195], v[58:61]
	v_mfma_f32_16x16x32_bf16 v[46:49], v[152:155], v[202:205], v[46:49]
	v_mfma_f32_16x16x32_bf16 v[42:45], v[168:171], v[202:205], v[42:45]
	v_mfma_f32_16x16x32_bf16 v[30:33], v[152:155], v[210:213], v[30:33]
	v_mfma_f32_16x16x32_bf16 v[26:29], v[168:171], v[210:213], v[26:29]
	v_mfma_f32_16x16x32_bf16 v[14:17], v[152:155], v[218:221], v[14:17]
	v_mfma_f32_16x16x32_bf16 v[10:13], v[168:171], v[218:221], v[10:13]
	v_mfma_f32_16x16x32_bf16 v[54:57], v[172:175], v[188:191], v[54:57]
	v_mfma_f32_16x16x32_bf16 v[50:53], v[180:183], v[188:191], v[50:53]
	v_mfma_f32_16x16x32_bf16 v[38:41], v[172:175], v[198:201], v[38:41]
	v_mfma_f32_16x16x32_bf16 v[34:37], v[180:183], v[198:201], v[34:37]
	v_mfma_f32_16x16x32_bf16 v[22:25], v[172:175], v[206:209], v[22:25]
	v_mfma_f32_16x16x32_bf16 v[18:21], v[180:183], v[206:209], v[18:21]
	v_mfma_f32_16x16x32_bf16 v[6:9], v[172:175], v[214:217], v[6:9]
	v_mfma_f32_16x16x32_bf16 v[2:5], v[180:183], v[214:217], v[2:5]
	v_mfma_f32_16x16x32_bf16 v[54:57], v[176:179], v[192:195], v[54:57]
	v_mfma_f32_16x16x32_bf16 v[50:53], v[184:187], v[192:195], v[50:53]
	v_mfma_f32_16x16x32_bf16 v[38:41], v[176:179], v[202:205], v[38:41]
	v_mfma_f32_16x16x32_bf16 v[34:37], v[184:187], v[202:205], v[34:37]
	v_mfma_f32_16x16x32_bf16 v[22:25], v[176:179], v[210:213], v[22:25]
	v_mfma_f32_16x16x32_bf16 v[18:21], v[184:187], v[210:213], v[18:21]
	v_mfma_f32_16x16x32_bf16 v[6:9], v[176:179], v[218:221], v[6:9]
	v_mfma_f32_16x16x32_bf16 v[2:5], v[184:187], v[218:221], v[2:5]
	s_barrier
	s_add_i32 s78, s78, 2
	s_add_u32 s58, s58, 0x100
	s_addc_u32 s59, s59, 0
	s_add_u32 s76, s76, 0x100
	s_addc_u32 s77, s77, 0
	s_cmp_gt_u32 s78, 61
	.p2align	8
.LBB0_678:
	ds_read_b128 v[148:151], v159
	ds_read_b128 v[152:155], v159 offset:1024
	ds_read_b128 v[164:167], v159 offset:2048
	ds_read_b128 v[168:171], v159 offset:3072
	ds_read_b128 v[172:175], v160
	ds_read_b128 v[176:179], v160 offset:1024
	ds_read_b128 v[180:183], v160 offset:2048
	ds_read_b128 v[184:187], v160 offset:3072
	s_add_u32 s60, s58, 0xfff00080
	s_addc_u32 s61, s59, -1
	s_cmp_eq_u32 s78, 60
	s_cselect_b32 s63, s7, s61
	s_cselect_b32 s62, s47, s60
	s_cselect_b32 s61, s45, s77
	s_cselect_b32 s60, s57, s76
	s_add_i32 m0, s64, 0xc000
	ds_read_b128 v[188:191], v161
	ds_read_b128 v[192:195], v161 offset:1024
	ds_read_b128 v[198:201], v161 offset:2048
	ds_read_b128 v[202:205], v161 offset:3072
	ds_read_b128 v[206:209], v161 offset:4096
	ds_read_b128 v[210:213], v161 offset:5120
	ds_read_b128 v[214:217], v161 offset:6144
	ds_read_b128 v[218:221], v161 offset:7168
	global_load_lds_dwordx4 v140, s[58:59]
	s_add_i32 m0, s64, 0xe000
	s_nop 0
	global_load_lds_dwordx4 v142, s[58:59]
	s_waitcnt vmcnt(8)
	s_waitcnt lgkmcnt(0)
	s_barrier
	v_mfma_f32_16x16x32_bf16 v[126:129], v[148:151], v[188:191], v[126:129]
	v_mfma_f32_16x16x32_bf16 v[122:125], v[164:167], v[188:191], v[122:125]
	v_mfma_f32_16x16x32_bf16 v[110:113], v[148:151], v[198:201], v[110:113]
	v_mfma_f32_16x16x32_bf16 v[106:109], v[164:167], v[198:201], v[106:109]
	v_mfma_f32_16x16x32_bf16 v[94:97], v[148:151], v[206:209], v[94:97]
	v_mfma_f32_16x16x32_bf16 v[90:93], v[164:167], v[206:209], v[90:93]
	v_mfma_f32_16x16x32_bf16 v[78:81], v[148:151], v[214:217], v[78:81]
	v_mfma_f32_16x16x32_bf16 v[74:77], v[164:167], v[214:217], v[74:77]
	v_mfma_f32_16x16x32_bf16 v[126:129], v[152:155], v[192:195], v[126:129]
	v_mfma_f32_16x16x32_bf16 v[122:125], v[168:171], v[192:195], v[122:125]
	v_mfma_f32_16x16x32_bf16 v[110:113], v[152:155], v[202:205], v[110:113]
	v_mfma_f32_16x16x32_bf16 v[106:109], v[168:171], v[202:205], v[106:109]
	v_mfma_f32_16x16x32_bf16 v[94:97], v[152:155], v[210:213], v[94:97]
	v_mfma_f32_16x16x32_bf16 v[90:93], v[168:171], v[210:213], v[90:93]
	v_mfma_f32_16x16x32_bf16 v[78:81], v[152:155], v[218:221], v[78:81]
	v_mfma_f32_16x16x32_bf16 v[74:77], v[168:171], v[218:221], v[74:77]
	v_mfma_f32_16x16x32_bf16 v[118:121], v[172:175], v[188:191], v[118:121]
	v_mfma_f32_16x16x32_bf16 v[114:117], v[180:183], v[188:191], v[114:117]
	v_mfma_f32_16x16x32_bf16 v[102:105], v[172:175], v[198:201], v[102:105]
	v_mfma_f32_16x16x32_bf16 v[98:101], v[180:183], v[198:201], v[98:101]
	v_mfma_f32_16x16x32_bf16 v[86:89], v[172:175], v[206:209], v[86:89]
	v_mfma_f32_16x16x32_bf16 v[82:85], v[180:183], v[206:209], v[82:85]
	v_mfma_f32_16x16x32_bf16 v[70:73], v[172:175], v[214:217], v[70:73]
	v_mfma_f32_16x16x32_bf16 v[66:69], v[180:183], v[214:217], v[66:69]
	v_mfma_f32_16x16x32_bf16 v[118:121], v[176:179], v[192:195], v[118:121]
	v_mfma_f32_16x16x32_bf16 v[114:117], v[184:187], v[192:195], v[114:117]
	v_mfma_f32_16x16x32_bf16 v[102:105], v[176:179], v[202:205], v[102:105]
	v_mfma_f32_16x16x32_bf16 v[98:101], v[184:187], v[202:205], v[98:101]
	v_mfma_f32_16x16x32_bf16 v[86:89], v[176:179], v[210:213], v[86:89]
	v_mfma_f32_16x16x32_bf16 v[82:85], v[184:187], v[210:213], v[82:85]
	v_mfma_f32_16x16x32_bf16 v[70:73], v[176:179], v[218:221], v[70:73]
	v_mfma_f32_16x16x32_bf16 v[66:69], v[184:187], v[218:221], v[66:69]
	s_barrier
	s_add_i32 s79, s74, s33
	s_mov_b32 m0, s79
	ds_read_b128 v[188:191], v161 offset:16384
	ds_read_b128 v[192:195], v161 offset:17408
	ds_read_b128 v[198:201], v161 offset:18432
	ds_read_b128 v[202:205], v161 offset:19456
	ds_read_b128 v[206:209], v161 offset:20480
	ds_read_b128 v[210:213], v161 offset:21504
	ds_read_b128 v[214:217], v161 offset:22528
	ds_read_b128 v[218:221], v161 offset:23552
	global_load_lds_dwordx4 v132, s[60:61]
	s_add_i32 m0, s79, 0x2000
	s_add_u32 s80, s60, 0x100000
	s_addc_u32 s81, s61, 0
	s_add_i32 s79, s75, s33
	global_load_lds_dwordx4 v136, s[60:61]
	s_mov_b32 m0, s79
	global_load_lds_dwordx4 v132, s[80:81]
	s_add_i32 m0, s79, 0x2000
	s_nop 0
	global_load_lds_dwordx4 v136, s[80:81]
	s_mov_b32 m0, s64
	s_nop 0
	global_load_lds_dwordx4 v130, s[62:63]
	s_mov_b32 m0, s65
	s_nop 0
	global_load_lds_dwordx4 v134, s[62:63]
	s_waitcnt vmcnt(8)
	s_waitcnt lgkmcnt(0)
	s_barrier
	v_mfma_f32_16x16x32_bf16 v[62:65], v[148:151], v[188:191], v[62:65]
	v_mfma_f32_16x16x32_bf16 v[58:61], v[164:167], v[188:191], v[58:61]
	v_mfma_f32_16x16x32_bf16 v[46:49], v[148:151], v[198:201], v[46:49]
	v_mfma_f32_16x16x32_bf16 v[42:45], v[164:167], v[198:201], v[42:45]
	v_mfma_f32_16x16x32_bf16 v[30:33], v[148:151], v[206:209], v[30:33]
	v_mfma_f32_16x16x32_bf16 v[26:29], v[164:167], v[206:209], v[26:29]
	v_mfma_f32_16x16x32_bf16 v[14:17], v[148:151], v[214:217], v[14:17]
	v_mfma_f32_16x16x32_bf16 v[10:13], v[164:167], v[214:217], v[10:13]
	v_mfma_f32_16x16x32_bf16 v[62:65], v[152:155], v[192:195], v[62:65]
	v_mfma_f32_16x16x32_bf16 v[58:61], v[168:171], v[192:195], v[58:61]
	v_mfma_f32_16x16x32_bf16 v[46:49], v[152:155], v[202:205], v[46:49]
	v_mfma_f32_16x16x32_bf16 v[42:45], v[168:171], v[202:205], v[42:45]
	v_mfma_f32_16x16x32_bf16 v[30:33], v[152:155], v[210:213], v[30:33]
	v_mfma_f32_16x16x32_bf16 v[26:29], v[168:171], v[210:213], v[26:29]
	v_mfma_f32_16x16x32_bf16 v[14:17], v[152:155], v[218:221], v[14:17]
	v_mfma_f32_16x16x32_bf16 v[10:13], v[168:171], v[218:221], v[10:13]
	v_mfma_f32_16x16x32_bf16 v[54:57], v[172:175], v[188:191], v[54:57]
	v_mfma_f32_16x16x32_bf16 v[50:53], v[180:183], v[188:191], v[50:53]
	v_mfma_f32_16x16x32_bf16 v[38:41], v[172:175], v[198:201], v[38:41]
	v_mfma_f32_16x16x32_bf16 v[34:37], v[180:183], v[198:201], v[34:37]
	v_mfma_f32_16x16x32_bf16 v[22:25], v[172:175], v[206:209], v[22:25]
	v_mfma_f32_16x16x32_bf16 v[18:21], v[180:183], v[206:209], v[18:21]
	v_mfma_f32_16x16x32_bf16 v[6:9], v[172:175], v[214:217], v[6:9]
	v_mfma_f32_16x16x32_bf16 v[2:5], v[180:183], v[214:217], v[2:5]
	v_mfma_f32_16x16x32_bf16 v[54:57], v[176:179], v[192:195], v[54:57]
	v_mfma_f32_16x16x32_bf16 v[50:53], v[184:187], v[192:195], v[50:53]
	v_mfma_f32_16x16x32_bf16 v[38:41], v[176:179], v[202:205], v[38:41]
	v_mfma_f32_16x16x32_bf16 v[34:37], v[184:187], v[202:205], v[34:37]
	v_mfma_f32_16x16x32_bf16 v[22:25], v[176:179], v[210:213], v[22:25]
	v_mfma_f32_16x16x32_bf16 v[18:21], v[184:187], v[210:213], v[18:21]
	v_mfma_f32_16x16x32_bf16 v[6:9], v[176:179], v[218:221], v[6:9]
	v_mfma_f32_16x16x32_bf16 v[2:5], v[184:187], v[218:221], v[2:5]
	s_barrier
	s_add_i32 s79, 0, 0x18000
	v_add_u32_e32 v138, s79, v157
	s_add_i32 s80, 0, 0x1c000
	ds_read_b128 v[148:151], v138
	ds_read_b128 v[152:155], v138 offset:1024
	ds_read_b128 v[164:167], v138 offset:2048
	ds_read_b128 v[168:171], v138 offset:3072
	v_add_u32_e32 v138, s80, v157
	ds_read_b128 v[172:175], v138
	ds_read_b128 v[176:179], v138 offset:1024
	ds_read_b128 v[180:183], v138 offset:2048
	ds_read_b128 v[184:187], v138 offset:3072
	s_add_u32 s62, s62, 0x100000
	s_addc_u32 s63, s63, 0
	s_mov_b32 m0, s66
	ds_read_b128 v[188:191], v161 offset:32768
	ds_read_b128 v[192:195], v161 offset:33792
	ds_read_b128 v[198:201], v161 offset:34816
	ds_read_b128 v[202:205], v161 offset:35840
	ds_read_b128 v[206:209], v161 offset:36864
	ds_read_b128 v[210:213], v161 offset:37888
	ds_read_b128 v[214:217], v161 offset:38912
	ds_read_b128 v[218:221], v161 offset:39936
	global_load_lds_dwordx4 v130, s[62:63]
	s_mov_b32 m0, s67
	s_nop 0
	global_load_lds_dwordx4 v134, s[62:63]
	s_waitcnt vmcnt(8)
	s_waitcnt lgkmcnt(0)
	s_barrier
	v_mfma_f32_16x16x32_bf16 v[126:129], v[148:151], v[188:191], v[126:129]
	v_mfma_f32_16x16x32_bf16 v[122:125], v[164:167], v[188:191], v[122:125]
	v_mfma_f32_16x16x32_bf16 v[110:113], v[148:151], v[198:201], v[110:113]
	v_mfma_f32_16x16x32_bf16 v[106:109], v[164:167], v[198:201], v[106:109]
	v_mfma_f32_16x16x32_bf16 v[94:97], v[148:151], v[206:209], v[94:97]
	v_mfma_f32_16x16x32_bf16 v[90:93], v[164:167], v[206:209], v[90:93]
	v_mfma_f32_16x16x32_bf16 v[78:81], v[148:151], v[214:217], v[78:81]
	v_mfma_f32_16x16x32_bf16 v[74:77], v[164:167], v[214:217], v[74:77]
	v_mfma_f32_16x16x32_bf16 v[126:129], v[152:155], v[192:195], v[126:129]
	v_mfma_f32_16x16x32_bf16 v[122:125], v[168:171], v[192:195], v[122:125]
	v_mfma_f32_16x16x32_bf16 v[110:113], v[152:155], v[202:205], v[110:113]
	v_mfma_f32_16x16x32_bf16 v[106:109], v[168:171], v[202:205], v[106:109]
	v_mfma_f32_16x16x32_bf16 v[94:97], v[152:155], v[210:213], v[94:97]
	v_mfma_f32_16x16x32_bf16 v[90:93], v[168:171], v[210:213], v[90:93]
	v_mfma_f32_16x16x32_bf16 v[78:81], v[152:155], v[218:221], v[78:81]
	v_mfma_f32_16x16x32_bf16 v[74:77], v[168:171], v[218:221], v[74:77]
	v_mfma_f32_16x16x32_bf16 v[118:121], v[172:175], v[188:191], v[118:121]
	v_mfma_f32_16x16x32_bf16 v[114:117], v[180:183], v[188:191], v[114:117]
	v_mfma_f32_16x16x32_bf16 v[102:105], v[172:175], v[198:201], v[102:105]
	v_mfma_f32_16x16x32_bf16 v[98:101], v[180:183], v[198:201], v[98:101]
	v_mfma_f32_16x16x32_bf16 v[86:89], v[172:175], v[206:209], v[86:89]
	v_mfma_f32_16x16x32_bf16 v[82:85], v[180:183], v[206:209], v[82:85]
	v_mfma_f32_16x16x32_bf16 v[70:73], v[172:175], v[214:217], v[70:73]
	v_mfma_f32_16x16x32_bf16 v[66:69], v[180:183], v[214:217], v[66:69]
	v_mfma_f32_16x16x32_bf16 v[118:121], v[176:179], v[192:195], v[118:121]
	v_mfma_f32_16x16x32_bf16 v[114:117], v[184:187], v[192:195], v[114:117]
	v_mfma_f32_16x16x32_bf16 v[102:105], v[176:179], v[202:205], v[102:105]
	v_mfma_f32_16x16x32_bf16 v[98:101], v[184:187], v[202:205], v[98:101]
	v_mfma_f32_16x16x32_bf16 v[86:89], v[176:179], v[210:213], v[86:89]
	v_mfma_f32_16x16x32_bf16 v[82:85], v[184:187], v[210:213], v[82:85]
	v_mfma_f32_16x16x32_bf16 v[70:73], v[176:179], v[218:221], v[70:73]
	v_mfma_f32_16x16x32_bf16 v[66:69], v[184:187], v[218:221], v[66:69]
	s_barrier
	s_add_u32 s60, s60, 0x80
	s_addc_u32 s61, s61, 0
	s_add_i32 m0, s33, 0x18000
	ds_read_b128 v[188:191], v161 offset:49152
	ds_read_b128 v[192:195], v161 offset:50176
	ds_read_b128 v[198:201], v161 offset:51200
	ds_read_b128 v[202:205], v161 offset:52224
	ds_read_b128 v[206:209], v161 offset:53248
	ds_read_b128 v[210:213], v161 offset:54272
	ds_read_b128 v[214:217], v161 offset:55296
	ds_read_b128 v[218:221], v161 offset:56320
	global_load_lds_dwordx4 v132, s[60:61]
	s_add_i32 m0, s33, 0x1a000
	s_add_u32 s62, s62, 0xfff00080
	global_load_lds_dwordx4 v136, s[60:61]
	s_addc_u32 s63, s63, -1
	s_add_u32 s60, s60, 0x100000
	s_addc_u32 s61, s61, 0
	s_add_i32 m0, s33, 0x1c000
	s_nop 0
	global_load_lds_dwordx4 v132, s[60:61]
	s_add_i32 m0, s33, 0x1e000
	s_nop 0
	global_load_lds_dwordx4 v136, s[60:61]
	s_mov_b32 m0, s69
	s_nop 0
	global_load_lds_dwordx4 v130, s[62:63]
	s_mov_b32 m0, s70
	s_nop 0
	global_load_lds_dwordx4 v134, s[62:63]
	s_waitcnt vmcnt(8)
	s_waitcnt lgkmcnt(0)
	s_barrier
	v_mfma_f32_16x16x32_bf16 v[62:65], v[148:151], v[188:191], v[62:65]
	v_mfma_f32_16x16x32_bf16 v[58:61], v[164:167], v[188:191], v[58:61]
	v_mfma_f32_16x16x32_bf16 v[46:49], v[148:151], v[198:201], v[46:49]
	v_mfma_f32_16x16x32_bf16 v[42:45], v[164:167], v[198:201], v[42:45]
	v_mfma_f32_16x16x32_bf16 v[30:33], v[148:151], v[206:209], v[30:33]
	v_mfma_f32_16x16x32_bf16 v[26:29], v[164:167], v[206:209], v[26:29]
	v_mfma_f32_16x16x32_bf16 v[14:17], v[148:151], v[214:217], v[14:17]
	v_mfma_f32_16x16x32_bf16 v[10:13], v[164:167], v[214:217], v[10:13]
	v_mfma_f32_16x16x32_bf16 v[62:65], v[152:155], v[192:195], v[62:65]
	v_mfma_f32_16x16x32_bf16 v[58:61], v[168:171], v[192:195], v[58:61]
	v_mfma_f32_16x16x32_bf16 v[46:49], v[152:155], v[202:205], v[46:49]
	v_mfma_f32_16x16x32_bf16 v[42:45], v[168:171], v[202:205], v[42:45]
	v_mfma_f32_16x16x32_bf16 v[30:33], v[152:155], v[210:213], v[30:33]
	v_mfma_f32_16x16x32_bf16 v[26:29], v[168:171], v[210:213], v[26:29]
	v_mfma_f32_16x16x32_bf16 v[14:17], v[152:155], v[218:221], v[14:17]
	v_mfma_f32_16x16x32_bf16 v[10:13], v[168:171], v[218:221], v[10:13]
	v_mfma_f32_16x16x32_bf16 v[54:57], v[172:175], v[188:191], v[54:57]
	v_mfma_f32_16x16x32_bf16 v[50:53], v[180:183], v[188:191], v[50:53]
	v_mfma_f32_16x16x32_bf16 v[38:41], v[172:175], v[198:201], v[38:41]
	v_mfma_f32_16x16x32_bf16 v[34:37], v[180:183], v[198:201], v[34:37]
	v_mfma_f32_16x16x32_bf16 v[22:25], v[172:175], v[206:209], v[22:25]
	v_mfma_f32_16x16x32_bf16 v[18:21], v[180:183], v[206:209], v[18:21]
	v_mfma_f32_16x16x32_bf16 v[6:9], v[172:175], v[214:217], v[6:9]
	v_mfma_f32_16x16x32_bf16 v[2:5], v[180:183], v[214:217], v[2:5]
	v_mfma_f32_16x16x32_bf16 v[54:57], v[176:179], v[192:195], v[54:57]
	v_mfma_f32_16x16x32_bf16 v[50:53], v[184:187], v[192:195], v[50:53]
	v_mfma_f32_16x16x32_bf16 v[38:41], v[176:179], v[202:205], v[38:41]
	v_mfma_f32_16x16x32_bf16 v[34:37], v[184:187], v[202:205], v[34:37]
	v_mfma_f32_16x16x32_bf16 v[22:25], v[176:179], v[210:213], v[22:25]
	v_mfma_f32_16x16x32_bf16 v[18:21], v[184:187], v[210:213], v[18:21]
	v_mfma_f32_16x16x32_bf16 v[6:9], v[176:179], v[218:221], v[6:9]
	v_mfma_f32_16x16x32_bf16 v[2:5], v[184:187], v[218:221], v[2:5]
	s_barrier
	s_add_i32 s78, s78, 2
	s_add_u32 s58, s58, 0x100
	s_addc_u32 s59, s59, 0
	s_add_u32 s76, s76, 0x100
	s_addc_u32 s77, s77, 0
	s_cmp_gt_u32 s78, 61
	s_cbranch_scc0 .LBB0_678
	s_and_b64 vcc, exec, s[18:19]
	s_cbranch_vccz .LBB0_681
	s_barrier

.LBB0_797:
	s_cmp_lt_i32 s72, 5
	s_cselect_b64 s[0:1], -1, 0
	s_cmp_gt_i32 s73, 4
	s_cselect_b64 s[4:5], -1, 0
	s_and_b64 s[0:1], s[0:1], s[4:5]
	s_andn2_b64 vcc, exec, s[0:1]
	s_cbranch_vccnz .LBB0_868
	s_cmpk_gt_i32 s2, 0x11ff
	s_setprio 0
	v_readfirstlane_b32 s1, v0
	s_cbranch_scc1 .LBB0_814
	s_waitcnt lgkmcnt(0)
	v_lshrrev_b32_e32 v3, 1, v0
	v_and_b32_e32 v13, 24, v3
	v_lshrrev_b32_e32 v3, 5, v0
	v_lshlrev_b32_e32 v1, 4, v0
	v_and_b32_e32 v2, 32, v0
	v_and_b32_e32 v3, 4, v3
	v_bfe_u32 v4, v0, 2, 2
	v_bfe_u32 v12, v0, 2, 4
	v_bitop3_b32 v10, v1, v2, 48 bitop3:0x6c
	v_and_b32_e32 v11, 64, v0
	v_or3_b32 v3, v3, v4, v13
	v_lshrrev_b32_e32 v4, 3, v0
	v_or_b32_e32 v14, 0x2000, v1
	v_or_b32_e32 v2, v10, v11
	v_and_or_b32 v5, v4, 48, v12
	v_and_or_b32 v4, v4, 32, v3
	v_lshrrev_b32_e32 v1, 7, v14
	s_movk_i32 s0, 0x70
	v_lshl_or_b32 v132, v4, 13, v2
	v_and_or_b32 v4, v1, s0, v12
	s_movk_i32 s0, 0x60
	s_ashr_i32 s48, s2, 31
	v_and_or_b32 v1, v1, s0, v3
	s_lshr_b32 s0, s48, 29
	s_add_i32 s0, s2, s0
	s_lshr_b32 s6, s1, 6
	s_ashr_i32 s4, s0, 3
	s_and_b32 s0, s0, -8
	s_lshr_b32 s14, s1, 8
	s_lshl_b32 s33, s6, 10
	s_sub_i32 s0, s2, s0
	s_cmp_lt_i32 s0, 0
	s_movk_i32 s49, 0x241
	s_cselect_b32 s5, s49, 0x240
	s_mul_i32 s0, s0, s5
	s_add_i32 s0, s0, s4
	s_mul_hi_i32 s4, s0, 0x38e38e39
	s_lshr_b32 s5, s4, 31
	s_ashr_i32 s4, s4, 7
	s_add_i32 s4, s4, s5
	s_mul_i32 s5, s4, 9
	s_mulk_i32 s4, 0x240
	s_sub_i32 s4, s0, s4
	s_sext_i32_i16 s0, s4
	s_mulk_i32 s0, 0x1c72
	s_lshr_b32 s7, s0, 31
	s_lshr_b32 s0, s0, 16
	s_add_i32 s0, s0, s7
	s_mul_i32 s7, s0, 9
	s_sub_i32 s4, s4, s7
	s_sext_i32_i16 s4, s4
	s_add_i32 s40, s5, s4
	s_ashr_i32 s41, s40, 31
	s_bfe_i64 s[16:17], s[0:1], 0x100000
	s_lshl_b64 s[4:5], s[40:41], 21
	s_lshl_b64 s[16:17], s[16:17], 21
	v_readlane_b32 s76, v249, 36
	v_readlane_b32 s77, v249, 37
	s_add_u32 s44, s76, s16
	s_addc_u32 s45, s77, s17
	s_add_i32 s41, s33, 0
	s_add_i32 m0, s41, 0x10000
	v_lshl_or_b32 v136, v1, 13, v2
	global_load_lds_dwordx4 v132, s[44:45]
	s_add_i32 m0, s41, 0x12000
	s_add_u32 s16, s44, 0x100000
	global_load_lds_dwordx4 v136, s[44:45]
	s_addc_u32 s17, s45, 0
	s_add_i32 m0, s41, 0x14000
	v_lshl_or_b32 v130, v5, 13, v2
	global_load_lds_dwordx4 v132, s[16:17]
	s_add_i32 m0, s41, 0x16000
	s_add_u32 s42, s8, s4
	s_addc_u32 s43, s9, s5
	s_add_i32 s50, s41, 0x2000
	global_load_lds_dwordx4 v136, s[16:17]
	s_mov_b32 m0, s41
	s_add_u32 s4, s42, 0x100000
	v_lshl_or_b32 v134, v4, 13, v2
	global_load_lds_dwordx4 v130, s[42:43]
	s_mov_b32 m0, s50
	s_addc_u32 s5, s43, 0
	s_add_i32 s51, s41, 0x4000
	global_load_lds_dwordx4 v134, s[42:43]
	s_mov_b32 m0, s51
	s_add_i32 s52, s41, 0x6000
	global_load_lds_dwordx4 v130, s[4:5]
	s_mov_b32 m0, s52
	v_mov_b32_e32 v133, 0
	global_load_lds_dwordx4 v134, s[4:5]
	v_mov_b32_e32 v137, v133
	v_mov_b32_e32 v131, v133
	v_mov_b32_e32 v135, v133
	s_cmp_eq_u32 s14, 1
	s_mov_b32 s53, 0
	v_lshl_add_u64 v[8:9], s[44:45], 0, v[132:133]
	v_lshl_add_u64 v[6:7], s[44:45], 0, v[136:137]
	v_lshl_add_u64 v[2:3], s[42:43], 0, v[130:131]
	s_cselect_b64 s[4:5], -1, 0
	s_cmp_lg_u32 s14, 1
	v_lshl_add_u64 v[4:5], s[42:43], 0, v[134:135]
	s_cbranch_scc1 .LBB0_801
	s_barrier
.LBB0_801:
	s_lshl_b32 s6, s6, 5
	s_and_b32 s18, s6, 0x60
	s_mov_b64 s[6:7], 0x80
	s_add_i32 m0, s41, 0x18000
	v_lshl_add_u64 v[8:9], v[8:9], 0, s[6:7]
	s_ashr_i32 s54, s3, 31
	s_lshl_b32 s15, s14, 13
	s_lshl_b32 s19, s18, 7
	s_waitcnt vmcnt(2)
	s_barrier
	global_load_lds_dwordx4 v[8:9], off
	v_lshl_add_u64 v[6:7], v[6:7], 0, s[6:7]
	s_add_i32 m0, s41, 0x1a000
	s_add_i32 s55, s41, 0x8000
	s_add_i32 s56, s41, 0xa000
	global_load_lds_dwordx4 v[6:7], off
	v_lshl_add_u64 v[2:3], v[2:3], 0, s[6:7]
	s_mov_b32 m0, s55
	s_add_u32 s16, s44, 0x100080
	global_load_lds_dwordx4 v[2:3], off
	v_lshl_add_u64 v[2:3], v[4:5], 0, s[6:7]
	s_mov_b32 m0, s56
	s_addc_u32 s17, s45, 0
	global_load_lds_dwordx4 v[2:3], off
	s_add_i32 m0, s41, 0x1c000
	v_lshl_add_u64 v[2:3], s[16:17], 0, v[132:133]
	global_load_lds_dwordx4 v[2:3], off
	v_lshl_add_u64 v[2:3], s[16:17], 0, v[136:137]
	s_add_i32 m0, s41, 0x1e000
	s_sext_i32_i16 s63, s0
	global_load_lds_dwordx4 v[2:3], off
	v_lshlrev_b32_e32 v3, 1, v13
	v_lshlrev_b32_e32 v1, 6, v0
	s_movk_i32 s0, 0x3c0
	v_and_b32_e32 v2, 15, v0
	v_and_or_b32 v4, v1, s0, v3
	v_lshlrev_b32_e32 v1, 2, v0
	v_and_b32_e32 v5, 32, v1
	v_lshl_or_b32 v1, s14, 6, v2
	v_lshl_or_b32 v2, v2, 6, v3
	v_lshlrev_b32_e32 v3, 10, v0
	v_bitop3_b32 v148, s19, v4, v5 bitop3:0xf6
	v_and_b32_e32 v3, 0x60000, v3
	v_lshlrev_b32_e32 v4, 13, v12
	v_or3_b32 v3, v10, v3, v4
	v_add_u32_e32 v138, v3, v11
	v_lshlrev_b32_e32 v3, 6, v14
	s_waitcnt vmcnt(6)
	s_cmpk_lt_u32 s1, 0x100
	s_cbranch_scc1 .Lstatprio_3
	s_setprio 1
.Lstatprio_3:
	v_and_b32_e32 v3, 0xe0000, v3
	v_bitop3_b32 v2, v2, s15, v5 bitop3:0xde
	s_cselect_b64 s[14:15], -1, 0
	v_or3_b32 v3, v10, v3, v4
	s_add_i32 s57, 0, 0x10000
	s_add_i32 s58, 0, 0x14000
	v_or_b32_e32 v149, s18, v13
	v_mov_b32_e32 v139, v133
	v_add_u32_e32 v140, v3, v11
	v_mov_b32_e32 v141, v133
	v_mov_b64_e32 v[142:143], 0x1200
	v_mov_b64_e32 v[144:145], 0x11ff
	v_add_u32_e32 v150, s57, v148
	v_add_u32_e32 v151, s58, v148
	v_add_u32_e32 v152, 0, v2
	s_mov_b64 s[16:17], 0x400000
	s_mov_b32 s59, 0x400000
	s_mov_b64 s[18:19], 0x480000
	s_mov_b32 s60, 0x480000
	s_mov_b64 s[20:21], 0x500000
	s_mov_b32 s61, 0x500000
	s_mov_b64 s[28:29], 0x580000
	s_mov_b32 s62, 0x580000
	s_barrier
	s_waitcnt vmcnt(0)
	s_branch .LBB0_804

.LBB0_806:
	s_ashr_i32 s35, s34, 31
	s_lshl_b64 s[36:37], s[34:35], 21
	s_add_u32 s36, s8, s36
	s_addc_u32 s37, s9, s37
	s_and_b64 s[38:39], s[0:1], exec
	s_cselect_b32 s35, s37, s43
	s_cselect_b32 s64, s36, s42
	s_ashr_i32 s31, s30, 31
	s_lshl_b64 s[38:39], s[30:31], 21
	s_add_u32 s38, s76, s38
	s_addc_u32 s39, s77, s39
	s_and_b64 s[46:47], s[0:1], exec
	s_cselect_b32 s31, s39, s45
	s_cselect_b32 s65, s38, s44
	s_add_u32 s42, s42, 0x100080
	s_addc_u32 s43, s43, 0
	s_add_u32 s66, s44, 0x100
	s_addc_u32 s67, s45, 0
	s_mov_b32 s68, -2
	ds_read_b128 v[154:157], v150
	ds_read_b128 v[158:161], v150 offset:1024
	ds_read_b128 v[162:165], v150 offset:2048
	ds_read_b128 v[166:169], v150 offset:3072
	ds_read_b128 v[170:173], v151
	ds_read_b128 v[174:177], v151 offset:1024
	ds_read_b128 v[178:181], v151 offset:2048
	ds_read_b128 v[182:185], v151 offset:3072
	s_add_u32 s44, s42, 0xfff00080
	s_addc_u32 s45, s43, -1
	s_cmp_eq_u32 s68, 60
	s_cselect_b32 s47, s35, s45
	s_cselect_b32 s46, s64, s44
	s_cselect_b32 s45, s31, s67
	s_cselect_b32 s44, s65, s66
	s_add_i32 m0, s41, 0xc000
	ds_read_b128 v[186:189], v152
	ds_read_b128 v[190:193], v152 offset:1024
	ds_read_b128 v[198:201], v152 offset:2048
	ds_read_b128 v[202:205], v152 offset:3072
	ds_read_b128 v[206:209], v152 offset:4096
	ds_read_b128 v[210:213], v152 offset:5120
	ds_read_b128 v[214:217], v152 offset:6144
	ds_read_b128 v[218:221], v152 offset:7168
	global_load_lds_dwordx4 v138, s[42:43]
	s_add_i32 m0, s41, 0xe000
	s_nop 0
	global_load_lds_dwordx4 v140, s[42:43]
	s_waitcnt vmcnt(24)
	s_waitcnt lgkmcnt(0)
	s_barrier
	v_mfma_f32_16x16x32_bf16 v[126:129], v[154:157], v[186:189], 0
	v_mfma_f32_16x16x32_bf16 v[122:125], v[162:165], v[186:189], 0
	v_mfma_f32_16x16x32_bf16 v[110:113], v[154:157], v[198:201], 0
	v_mfma_f32_16x16x32_bf16 v[106:109], v[162:165], v[198:201], 0
	v_mfma_f32_16x16x32_bf16 v[94:97], v[154:157], v[206:209], 0
	v_mfma_f32_16x16x32_bf16 v[90:93], v[162:165], v[206:209], 0
	v_mfma_f32_16x16x32_bf16 v[78:81], v[154:157], v[214:217], 0
	v_mfma_f32_16x16x32_bf16 v[74:77], v[162:165], v[214:217], 0
	v_mfma_f32_16x16x32_bf16 v[126:129], v[158:161], v[190:193], v[126:129]
	v_mfma_f32_16x16x32_bf16 v[122:125], v[166:169], v[190:193], v[122:125]
	v_mfma_f32_16x16x32_bf16 v[110:113], v[158:161], v[202:205], v[110:113]
	v_mfma_f32_16x16x32_bf16 v[106:109], v[166:169], v[202:205], v[106:109]
	v_mfma_f32_16x16x32_bf16 v[94:97], v[158:161], v[210:213], v[94:97]
	v_mfma_f32_16x16x32_bf16 v[90:93], v[166:169], v[210:213], v[90:93]
	v_mfma_f32_16x16x32_bf16 v[78:81], v[158:161], v[218:221], v[78:81]
	v_mfma_f32_16x16x32_bf16 v[74:77], v[166:169], v[218:221], v[74:77]
	v_mfma_f32_16x16x32_bf16 v[118:121], v[170:173], v[186:189], 0
	v_mfma_f32_16x16x32_bf16 v[114:117], v[178:181], v[186:189], 0
	v_mfma_f32_16x16x32_bf16 v[102:105], v[170:173], v[198:201], 0
	v_mfma_f32_16x16x32_bf16 v[98:101], v[178:181], v[198:201], 0
	v_mfma_f32_16x16x32_bf16 v[86:89], v[170:173], v[206:209], 0
	v_mfma_f32_16x16x32_bf16 v[82:85], v[178:181], v[206:209], 0
	v_mfma_f32_16x16x32_bf16 v[70:73], v[170:173], v[214:217], 0
	v_mfma_f32_16x16x32_bf16 v[66:69], v[178:181], v[214:217], 0
	v_mfma_f32_16x16x32_bf16 v[118:121], v[174:177], v[190:193], v[118:121]
	v_mfma_f32_16x16x32_bf16 v[114:117], v[182:185], v[190:193], v[114:117]
	v_mfma_f32_16x16x32_bf16 v[102:105], v[174:177], v[202:205], v[102:105]
	v_mfma_f32_16x16x32_bf16 v[98:101], v[182:185], v[202:205], v[98:101]
	v_mfma_f32_16x16x32_bf16 v[86:89], v[174:177], v[210:213], v[86:89]
	v_mfma_f32_16x16x32_bf16 v[82:85], v[182:185], v[210:213], v[82:85]
	v_mfma_f32_16x16x32_bf16 v[70:73], v[174:177], v[218:221], v[70:73]
	v_mfma_f32_16x16x32_bf16 v[66:69], v[182:185], v[218:221], v[66:69]
	s_barrier
	s_add_i32 s69, s57, s33
	s_mov_b32 m0, s69
	ds_read_b128 v[186:189], v152 offset:16384
	ds_read_b128 v[190:193], v152 offset:17408
	ds_read_b128 v[198:201], v152 offset:18432
	ds_read_b128 v[202:205], v152 offset:19456
	ds_read_b128 v[206:209], v152 offset:20480
	ds_read_b128 v[210:213], v152 offset:21504
	ds_read_b128 v[214:217], v152 offset:22528
	ds_read_b128 v[218:221], v152 offset:23552
	global_load_lds_dwordx4 v132, s[44:45]
	s_add_i32 m0, s69, 0x2000
	s_add_u32 s70, s44, 0x100000
	s_addc_u32 s71, s45, 0
	s_add_i32 s69, s58, s33
	global_load_lds_dwordx4 v136, s[44:45]
	s_mov_b32 m0, s69
	global_load_lds_dwordx4 v132, s[70:71]
	s_add_i32 m0, s69, 0x2000
	s_nop 0
	global_load_lds_dwordx4 v136, s[70:71]
	s_mov_b32 m0, s41
	s_nop 0
	global_load_lds_dwordx4 v130, s[46:47]
	s_mov_b32 m0, s50
	s_nop 0
	global_load_lds_dwordx4 v134, s[46:47]
	s_waitcnt vmcnt(24)
	s_waitcnt lgkmcnt(0)
	s_barrier
	v_mfma_f32_16x16x32_bf16 v[62:65], v[154:157], v[186:189], 0
	v_mfma_f32_16x16x32_bf16 v[58:61], v[162:165], v[186:189], 0
	v_mfma_f32_16x16x32_bf16 v[46:49], v[154:157], v[198:201], 0
	v_mfma_f32_16x16x32_bf16 v[42:45], v[162:165], v[198:201], 0
	v_mfma_f32_16x16x32_bf16 v[30:33], v[154:157], v[206:209], 0
	v_mfma_f32_16x16x32_bf16 v[26:29], v[162:165], v[206:209], 0
	v_mfma_f32_16x16x32_bf16 v[14:17], v[154:157], v[214:217], 0
	v_mfma_f32_16x16x32_bf16 v[10:13], v[162:165], v[214:217], 0
	v_mfma_f32_16x16x32_bf16 v[62:65], v[158:161], v[190:193], v[62:65]
	v_mfma_f32_16x16x32_bf16 v[58:61], v[166:169], v[190:193], v[58:61]
	v_mfma_f32_16x16x32_bf16 v[46:49], v[158:161], v[202:205], v[46:49]
	v_mfma_f32_16x16x32_bf16 v[42:45], v[166:169], v[202:205], v[42:45]
	v_mfma_f32_16x16x32_bf16 v[30:33], v[158:161], v[210:213], v[30:33]
	v_mfma_f32_16x16x32_bf16 v[26:29], v[166:169], v[210:213], v[26:29]
	v_mfma_f32_16x16x32_bf16 v[14:17], v[158:161], v[218:221], v[14:17]
	v_mfma_f32_16x16x32_bf16 v[10:13], v[166:169], v[218:221], v[10:13]
	v_mfma_f32_16x16x32_bf16 v[54:57], v[170:173], v[186:189], 0
	v_mfma_f32_16x16x32_bf16 v[50:53], v[178:181], v[186:189], 0
	v_mfma_f32_16x16x32_bf16 v[38:41], v[170:173], v[198:201], 0
	v_mfma_f32_16x16x32_bf16 v[34:37], v[178:181], v[198:201], 0
	v_mfma_f32_16x16x32_bf16 v[22:25], v[170:173], v[206:209], 0
	v_mfma_f32_16x16x32_bf16 v[18:21], v[178:181], v[206:209], 0
	v_mfma_f32_16x16x32_bf16 v[6:9], v[170:173], v[214:217], 0
	v_mfma_f32_16x16x32_bf16 v[2:5], v[178:181], v[214:217], 0
	v_mfma_f32_16x16x32_bf16 v[54:57], v[174:177], v[190:193], v[54:57]
	v_mfma_f32_16x16x32_bf16 v[50:53], v[182:185], v[190:193], v[50:53]
	v_mfma_f32_16x16x32_bf16 v[38:41], v[174:177], v[202:205], v[38:41]
	v_mfma_f32_16x16x32_bf16 v[34:37], v[182:185], v[202:205], v[34:37]
	v_mfma_f32_16x16x32_bf16 v[22:25], v[174:177], v[210:213], v[22:25]
	v_mfma_f32_16x16x32_bf16 v[18:21], v[182:185], v[210:213], v[18:21]
	v_mfma_f32_16x16x32_bf16 v[6:9], v[174:177], v[218:221], v[6:9]
	v_mfma_f32_16x16x32_bf16 v[2:5], v[182:185], v[218:221], v[2:5]
	s_barrier
	s_add_i32 s69, 0, 0x18000
	v_add_u32_e32 v153, s69, v148
	s_add_i32 s70, 0, 0x1c000
	ds_read_b128 v[154:157], v153
	ds_read_b128 v[158:161], v153 offset:1024
	ds_read_b128 v[162:165], v153 offset:2048
	ds_read_b128 v[166:169], v153 offset:3072
	v_add_u32_e32 v153, s70, v148
	ds_read_b128 v[170:173], v153
	ds_read_b128 v[174:177], v153 offset:1024
	ds_read_b128 v[178:181], v153 offset:2048
	ds_read_b128 v[182:185], v153 offset:3072
	s_add_u32 s46, s46, 0x100000
	s_addc_u32 s47, s47, 0
	s_mov_b32 m0, s51
	ds_read_b128 v[186:189], v152 offset:32768
	ds_read_b128 v[190:193], v152 offset:33792
	ds_read_b128 v[198:201], v152 offset:34816
	ds_read_b128 v[202:205], v152 offset:35840
	ds_read_b128 v[206:209], v152 offset:36864
	ds_read_b128 v[210:213], v152 offset:37888
	ds_read_b128 v[214:217], v152 offset:38912
	ds_read_b128 v[218:221], v152 offset:39936
	global_load_lds_dwordx4 v130, s[46:47]
	s_mov_b32 m0, s52
	s_nop 0
	global_load_lds_dwordx4 v134, s[46:47]
	s_waitcnt vmcnt(8)
	s_waitcnt lgkmcnt(0)
	s_barrier
	v_mfma_f32_16x16x32_bf16 v[126:129], v[154:157], v[186:189], v[126:129]
	v_mfma_f32_16x16x32_bf16 v[122:125], v[162:165], v[186:189], v[122:125]
	v_mfma_f32_16x16x32_bf16 v[110:113], v[154:157], v[198:201], v[110:113]
	v_mfma_f32_16x16x32_bf16 v[106:109], v[162:165], v[198:201], v[106:109]
	v_mfma_f32_16x16x32_bf16 v[94:97], v[154:157], v[206:209], v[94:97]
	v_mfma_f32_16x16x32_bf16 v[90:93], v[162:165], v[206:209], v[90:93]
	v_mfma_f32_16x16x32_bf16 v[78:81], v[154:157], v[214:217], v[78:81]
	v_mfma_f32_16x16x32_bf16 v[74:77], v[162:165], v[214:217], v[74:77]
	v_mfma_f32_16x16x32_bf16 v[126:129], v[158:161], v[190:193], v[126:129]
	v_mfma_f32_16x16x32_bf16 v[122:125], v[166:169], v[190:193], v[122:125]
	v_mfma_f32_16x16x32_bf16 v[110:113], v[158:161], v[202:205], v[110:113]
	v_mfma_f32_16x16x32_bf16 v[106:109], v[166:169], v[202:205], v[106:109]
	v_mfma_f32_16x16x32_bf16 v[94:97], v[158:161], v[210:213], v[94:97]
	v_mfma_f32_16x16x32_bf16 v[90:93], v[166:169], v[210:213], v[90:93]
	v_mfma_f32_16x16x32_bf16 v[78:81], v[158:161], v[218:221], v[78:81]
	v_mfma_f32_16x16x32_bf16 v[74:77], v[166:169], v[218:221], v[74:77]
	v_mfma_f32_16x16x32_bf16 v[118:121], v[170:173], v[186:189], v[118:121]
	v_mfma_f32_16x16x32_bf16 v[114:117], v[178:181], v[186:189], v[114:117]
	v_mfma_f32_16x16x32_bf16 v[102:105], v[170:173], v[198:201], v[102:105]
	v_mfma_f32_16x16x32_bf16 v[98:101], v[178:181], v[198:201], v[98:101]
	v_mfma_f32_16x16x32_bf16 v[86:89], v[170:173], v[206:209], v[86:89]
	v_mfma_f32_16x16x32_bf16 v[82:85], v[178:181], v[206:209], v[82:85]
	v_mfma_f32_16x16x32_bf16 v[70:73], v[170:173], v[214:217], v[70:73]
	v_mfma_f32_16x16x32_bf16 v[66:69], v[178:181], v[214:217], v[66:69]
	v_mfma_f32_16x16x32_bf16 v[118:121], v[174:177], v[190:193], v[118:121]
	v_mfma_f32_16x16x32_bf16 v[114:117], v[182:185], v[190:193], v[114:117]
	v_mfma_f32_16x16x32_bf16 v[102:105], v[174:177], v[202:205], v[102:105]
	v_mfma_f32_16x16x32_bf16 v[98:101], v[182:185], v[202:205], v[98:101]
	v_mfma_f32_16x16x32_bf16 v[86:89], v[174:177], v[210:213], v[86:89]
	v_mfma_f32_16x16x32_bf16 v[82:85], v[182:185], v[210:213], v[82:85]
	v_mfma_f32_16x16x32_bf16 v[70:73], v[174:177], v[218:221], v[70:73]
	v_mfma_f32_16x16x32_bf16 v[66:69], v[182:185], v[218:221], v[66:69]
	s_barrier
	s_add_u32 s44, s44, 0x80
	s_addc_u32 s45, s45, 0
	s_add_i32 m0, s33, 0x18000
	ds_read_b128 v[186:189], v152 offset:49152
	ds_read_b128 v[190:193], v152 offset:50176
	ds_read_b128 v[198:201], v152 offset:51200
	ds_read_b128 v[202:205], v152 offset:52224
	ds_read_b128 v[206:209], v152 offset:53248
	ds_read_b128 v[210:213], v152 offset:54272
	ds_read_b128 v[214:217], v152 offset:55296
	ds_read_b128 v[218:221], v152 offset:56320
	global_load_lds_dwordx4 v132, s[44:45]
	s_add_i32 m0, s33, 0x1a000
	s_add_u32 s46, s46, 0xfff00080
	global_load_lds_dwordx4 v136, s[44:45]
	s_addc_u32 s47, s47, -1
	s_add_u32 s44, s44, 0x100000
	s_addc_u32 s45, s45, 0
	s_add_i32 m0, s33, 0x1c000
	s_nop 0
	global_load_lds_dwordx4 v132, s[44:45]
	s_add_i32 m0, s33, 0x1e000
	s_nop 0
	global_load_lds_dwordx4 v136, s[44:45]
	s_mov_b32 m0, s55
	s_nop 0
	global_load_lds_dwordx4 v130, s[46:47]
	s_mov_b32 m0, s56
	s_nop 0
	global_load_lds_dwordx4 v134, s[46:47]
	s_waitcnt vmcnt(8)
	s_waitcnt lgkmcnt(0)
	s_barrier
	v_mfma_f32_16x16x32_bf16 v[62:65], v[154:157], v[186:189], v[62:65]
	v_mfma_f32_16x16x32_bf16 v[58:61], v[162:165], v[186:189], v[58:61]
	v_mfma_f32_16x16x32_bf16 v[46:49], v[154:157], v[198:201], v[46:49]
	v_mfma_f32_16x16x32_bf16 v[42:45], v[162:165], v[198:201], v[42:45]
	v_mfma_f32_16x16x32_bf16 v[30:33], v[154:157], v[206:209], v[30:33]
	v_mfma_f32_16x16x32_bf16 v[26:29], v[162:165], v[206:209], v[26:29]
	v_mfma_f32_16x16x32_bf16 v[14:17], v[154:157], v[214:217], v[14:17]
	v_mfma_f32_16x16x32_bf16 v[10:13], v[162:165], v[214:217], v[10:13]
	v_mfma_f32_16x16x32_bf16 v[62:65], v[158:161], v[190:193], v[62:65]
	v_mfma_f32_16x16x32_bf16 v[58:61], v[166:169], v[190:193], v[58:61]
	v_mfma_f32_16x16x32_bf16 v[46:49], v[158:161], v[202:205], v[46:49]
	v_mfma_f32_16x16x32_bf16 v[42:45], v[166:169], v[202:205], v[42:45]
	v_mfma_f32_16x16x32_bf16 v[30:33], v[158:161], v[210:213], v[30:33]
	v_mfma_f32_16x16x32_bf16 v[26:29], v[166:169], v[210:213], v[26:29]
	v_mfma_f32_16x16x32_bf16 v[14:17], v[158:161], v[218:221], v[14:17]
	v_mfma_f32_16x16x32_bf16 v[10:13], v[166:169], v[218:221], v[10:13]
	v_mfma_f32_16x16x32_bf16 v[54:57], v[170:173], v[186:189], v[54:57]
	v_mfma_f32_16x16x32_bf16 v[50:53], v[178:181], v[186:189], v[50:53]
	v_mfma_f32_16x16x32_bf16 v[38:41], v[170:173], v[198:201], v[38:41]
	v_mfma_f32_16x16x32_bf16 v[34:37], v[178:181], v[198:201], v[34:37]
	v_mfma_f32_16x16x32_bf16 v[22:25], v[170:173], v[206:209], v[22:25]
	v_mfma_f32_16x16x32_bf16 v[18:21], v[178:181], v[206:209], v[18:21]
	v_mfma_f32_16x16x32_bf16 v[6:9], v[170:173], v[214:217], v[6:9]
	v_mfma_f32_16x16x32_bf16 v[2:5], v[178:181], v[214:217], v[2:5]
	v_mfma_f32_16x16x32_bf16 v[54:57], v[174:177], v[190:193], v[54:57]
	v_mfma_f32_16x16x32_bf16 v[50:53], v[182:185], v[190:193], v[50:53]
	v_mfma_f32_16x16x32_bf16 v[38:41], v[174:177], v[202:205], v[38:41]
	v_mfma_f32_16x16x32_bf16 v[34:37], v[182:185], v[202:205], v[34:37]
	v_mfma_f32_16x16x32_bf16 v[22:25], v[174:177], v[210:213], v[22:25]
	v_mfma_f32_16x16x32_bf16 v[18:21], v[182:185], v[210:213], v[18:21]
	v_mfma_f32_16x16x32_bf16 v[6:9], v[174:177], v[218:221], v[6:9]
	v_mfma_f32_16x16x32_bf16 v[2:5], v[182:185], v[218:221], v[2:5]
	s_barrier
	s_add_i32 s68, s68, 2
	s_add_u32 s42, s42, 0x100
	s_addc_u32 s43, s43, 0
	s_add_u32 s66, s66, 0x100
	s_addc_u32 s67, s67, 0
	s_cmp_gt_u32 s68, 61
	.p2align	8
.LBB0_807:
	ds_read_b128 v[154:157], v150
	ds_read_b128 v[158:161], v150 offset:1024
	ds_read_b128 v[162:165], v150 offset:2048
	ds_read_b128 v[166:169], v150 offset:3072
	ds_read_b128 v[170:173], v151
	ds_read_b128 v[174:177], v151 offset:1024
	ds_read_b128 v[178:181], v151 offset:2048
	ds_read_b128 v[182:185], v151 offset:3072
	s_add_u32 s44, s42, 0xfff00080
	s_addc_u32 s45, s43, -1
	s_cmp_eq_u32 s68, 60
	s_cselect_b32 s47, s35, s45
	s_cselect_b32 s46, s64, s44
	s_cselect_b32 s45, s31, s67
	s_cselect_b32 s44, s65, s66
	s_add_i32 m0, s41, 0xc000
	ds_read_b128 v[186:189], v152
	ds_read_b128 v[190:193], v152 offset:1024
	ds_read_b128 v[198:201], v152 offset:2048
	ds_read_b128 v[202:205], v152 offset:3072
	ds_read_b128 v[206:209], v152 offset:4096
	ds_read_b128 v[210:213], v152 offset:5120
	ds_read_b128 v[214:217], v152 offset:6144
	ds_read_b128 v[218:221], v152 offset:7168
	global_load_lds_dwordx4 v138, s[42:43]
	s_add_i32 m0, s41, 0xe000
	s_nop 0
	global_load_lds_dwordx4 v140, s[42:43]
	s_waitcnt vmcnt(8)
	s_waitcnt lgkmcnt(0)
	s_barrier
	v_mfma_f32_16x16x32_bf16 v[126:129], v[154:157], v[186:189], v[126:129]
	v_mfma_f32_16x16x32_bf16 v[122:125], v[162:165], v[186:189], v[122:125]
	v_mfma_f32_16x16x32_bf16 v[110:113], v[154:157], v[198:201], v[110:113]
	v_mfma_f32_16x16x32_bf16 v[106:109], v[162:165], v[198:201], v[106:109]
	v_mfma_f32_16x16x32_bf16 v[94:97], v[154:157], v[206:209], v[94:97]
	v_mfma_f32_16x16x32_bf16 v[90:93], v[162:165], v[206:209], v[90:93]
	v_mfma_f32_16x16x32_bf16 v[78:81], v[154:157], v[214:217], v[78:81]
	v_mfma_f32_16x16x32_bf16 v[74:77], v[162:165], v[214:217], v[74:77]
	v_mfma_f32_16x16x32_bf16 v[126:129], v[158:161], v[190:193], v[126:129]
	v_mfma_f32_16x16x32_bf16 v[122:125], v[166:169], v[190:193], v[122:125]
	v_mfma_f32_16x16x32_bf16 v[110:113], v[158:161], v[202:205], v[110:113]
	v_mfma_f32_16x16x32_bf16 v[106:109], v[166:169], v[202:205], v[106:109]
	v_mfma_f32_16x16x32_bf16 v[94:97], v[158:161], v[210:213], v[94:97]
	v_mfma_f32_16x16x32_bf16 v[90:93], v[166:169], v[210:213], v[90:93]
	v_mfma_f32_16x16x32_bf16 v[78:81], v[158:161], v[218:221], v[78:81]
	v_mfma_f32_16x16x32_bf16 v[74:77], v[166:169], v[218:221], v[74:77]
	v_mfma_f32_16x16x32_bf16 v[118:121], v[170:173], v[186:189], v[118:121]
	v_mfma_f32_16x16x32_bf16 v[114:117], v[178:181], v[186:189], v[114:117]
	v_mfma_f32_16x16x32_bf16 v[102:105], v[170:173], v[198:201], v[102:105]
	v_mfma_f32_16x16x32_bf16 v[98:101], v[178:181], v[198:201], v[98:101]
	v_mfma_f32_16x16x32_bf16 v[86:89], v[170:173], v[206:209], v[86:89]
	v_mfma_f32_16x16x32_bf16 v[82:85], v[178:181], v[206:209], v[82:85]
	v_mfma_f32_16x16x32_bf16 v[70:73], v[170:173], v[214:217], v[70:73]
	v_mfma_f32_16x16x32_bf16 v[66:69], v[178:181], v[214:217], v[66:69]
	v_mfma_f32_16x16x32_bf16 v[118:121], v[174:177], v[190:193], v[118:121]
	v_mfma_f32_16x16x32_bf16 v[114:117], v[182:185], v[190:193], v[114:117]
	v_mfma_f32_16x16x32_bf16 v[102:105], v[174:177], v[202:205], v[102:105]
	v_mfma_f32_16x16x32_bf16 v[98:101], v[182:185], v[202:205], v[98:101]
	v_mfma_f32_16x16x32_bf16 v[86:89], v[174:177], v[210:213], v[86:89]
	v_mfma_f32_16x16x32_bf16 v[82:85], v[182:185], v[210:213], v[82:85]
	v_mfma_f32_16x16x32_bf16 v[70:73], v[174:177], v[218:221], v[70:73]
	v_mfma_f32_16x16x32_bf16 v[66:69], v[182:185], v[218:221], v[66:69]
	s_barrier
	s_add_i32 s69, s57, s33
	s_mov_b32 m0, s69
	ds_read_b128 v[186:189], v152 offset:16384
	ds_read_b128 v[190:193], v152 offset:17408
	ds_read_b128 v[198:201], v152 offset:18432
	ds_read_b128 v[202:205], v152 offset:19456
	ds_read_b128 v[206:209], v152 offset:20480
	ds_read_b128 v[210:213], v152 offset:21504
	ds_read_b128 v[214:217], v152 offset:22528
	ds_read_b128 v[218:221], v152 offset:23552
	global_load_lds_dwordx4 v132, s[44:45]
	s_add_i32 m0, s69, 0x2000
	s_add_u32 s70, s44, 0x100000
	s_addc_u32 s71, s45, 0
	s_add_i32 s69, s58, s33
	global_load_lds_dwordx4 v136, s[44:45]
	s_mov_b32 m0, s69
	global_load_lds_dwordx4 v132, s[70:71]
	s_add_i32 m0, s69, 0x2000
	s_nop 0
	global_load_lds_dwordx4 v136, s[70:71]
	s_mov_b32 m0, s41
	s_nop 0
	global_load_lds_dwordx4 v130, s[46:47]
	s_mov_b32 m0, s50
	s_nop 0
	global_load_lds_dwordx4 v134, s[46:47]
	s_waitcnt vmcnt(8)
	s_waitcnt lgkmcnt(0)
	s_barrier
	v_mfma_f32_16x16x32_bf16 v[62:65], v[154:157], v[186:189], v[62:65]
	v_mfma_f32_16x16x32_bf16 v[58:61], v[162:165], v[186:189], v[58:61]
	v_mfma_f32_16x16x32_bf16 v[46:49], v[154:157], v[198:201], v[46:49]
	v_mfma_f32_16x16x32_bf16 v[42:45], v[162:165], v[198:201], v[42:45]
	v_mfma_f32_16x16x32_bf16 v[30:33], v[154:157], v[206:209], v[30:33]
	v_mfma_f32_16x16x32_bf16 v[26:29], v[162:165], v[206:209], v[26:29]
	v_mfma_f32_16x16x32_bf16 v[14:17], v[154:157], v[214:217], v[14:17]
	v_mfma_f32_16x16x32_bf16 v[10:13], v[162:165], v[214:217], v[10:13]
	v_mfma_f32_16x16x32_bf16 v[62:65], v[158:161], v[190:193], v[62:65]
	v_mfma_f32_16x16x32_bf16 v[58:61], v[166:169], v[190:193], v[58:61]
	v_mfma_f32_16x16x32_bf16 v[46:49], v[158:161], v[202:205], v[46:49]
	v_mfma_f32_16x16x32_bf16 v[42:45], v[166:169], v[202:205], v[42:45]
	v_mfma_f32_16x16x32_bf16 v[30:33], v[158:161], v[210:213], v[30:33]
	v_mfma_f32_16x16x32_bf16 v[26:29], v[166:169], v[210:213], v[26:29]
	v_mfma_f32_16x16x32_bf16 v[14:17], v[158:161], v[218:221], v[14:17]
	v_mfma_f32_16x16x32_bf16 v[10:13], v[166:169], v[218:221], v[10:13]
	v_mfma_f32_16x16x32_bf16 v[54:57], v[170:173], v[186:189], v[54:57]
	v_mfma_f32_16x16x32_bf16 v[50:53], v[178:181], v[186:189], v[50:53]
	v_mfma_f32_16x16x32_bf16 v[38:41], v[170:173], v[198:201], v[38:41]
	v_mfma_f32_16x16x32_bf16 v[34:37], v[178:181], v[198:201], v[34:37]
	v_mfma_f32_16x16x32_bf16 v[22:25], v[170:173], v[206:209], v[22:25]
	v_mfma_f32_16x16x32_bf16 v[18:21], v[178:181], v[206:209], v[18:21]
	v_mfma_f32_16x16x32_bf16 v[6:9], v[170:173], v[214:217], v[6:9]
	v_mfma_f32_16x16x32_bf16 v[2:5], v[178:181], v[214:217], v[2:5]
	v_mfma_f32_16x16x32_bf16 v[54:57], v[174:177], v[190:193], v[54:57]
	v_mfma_f32_16x16x32_bf16 v[50:53], v[182:185], v[190:193], v[50:53]
	v_mfma_f32_16x16x32_bf16 v[38:41], v[174:177], v[202:205], v[38:41]
	v_mfma_f32_16x16x32_bf16 v[34:37], v[182:185], v[202:205], v[34:37]
	v_mfma_f32_16x16x32_bf16 v[22:25], v[174:177], v[210:213], v[22:25]
	v_mfma_f32_16x16x32_bf16 v[18:21], v[182:185], v[210:213], v[18:21]
	v_mfma_f32_16x16x32_bf16 v[6:9], v[174:177], v[218:221], v[6:9]
	v_mfma_f32_16x16x32_bf16 v[2:5], v[182:185], v[218:221], v[2:5]
	s_barrier
	s_add_i32 s69, 0, 0x18000
	v_add_u32_e32 v153, s69, v148
	s_add_i32 s70, 0, 0x1c000
	ds_read_b128 v[154:157], v153
	ds_read_b128 v[158:161], v153 offset:1024
	ds_read_b128 v[162:165], v153 offset:2048
	ds_read_b128 v[166:169], v153 offset:3072
	v_add_u32_e32 v153, s70, v148
	ds_read_b128 v[170:173], v153
	ds_read_b128 v[174:177], v153 offset:1024
	ds_read_b128 v[178:181], v153 offset:2048
	ds_read_b128 v[182:185], v153 offset:3072
	s_add_u32 s46, s46, 0x100000
	s_addc_u32 s47, s47, 0
	s_mov_b32 m0, s51
	ds_read_b128 v[186:189], v152 offset:32768
	ds_read_b128 v[190:193], v152 offset:33792
	ds_read_b128 v[198:201], v152 offset:34816
	ds_read_b128 v[202:205], v152 offset:35840
	ds_read_b128 v[206:209], v152 offset:36864
	ds_read_b128 v[210:213], v152 offset:37888
	ds_read_b128 v[214:217], v152 offset:38912
	ds_read_b128 v[218:221], v152 offset:39936
	global_load_lds_dwordx4 v130, s[46:47]
	s_mov_b32 m0, s52
	s_nop 0
	global_load_lds_dwordx4 v134, s[46:47]
	s_waitcnt vmcnt(8)
	s_waitcnt lgkmcnt(0)
	s_barrier
	v_mfma_f32_16x16x32_bf16 v[126:129], v[154:157], v[186:189], v[126:129]
	v_mfma_f32_16x16x32_bf16 v[122:125], v[162:165], v[186:189], v[122:125]
	v_mfma_f32_16x16x32_bf16 v[110:113], v[154:157], v[198:201], v[110:113]
	v_mfma_f32_16x16x32_bf16 v[106:109], v[162:165], v[198:201], v[106:109]
	v_mfma_f32_16x16x32_bf16 v[94:97], v[154:157], v[206:209], v[94:97]
	v_mfma_f32_16x16x32_bf16 v[90:93], v[162:165], v[206:209], v[90:93]
	v_mfma_f32_16x16x32_bf16 v[78:81], v[154:157], v[214:217], v[78:81]
	v_mfma_f32_16x16x32_bf16 v[74:77], v[162:165], v[214:217], v[74:77]
	v_mfma_f32_16x16x32_bf16 v[126:129], v[158:161], v[190:193], v[126:129]
	v_mfma_f32_16x16x32_bf16 v[122:125], v[166:169], v[190:193], v[122:125]
	v_mfma_f32_16x16x32_bf16 v[110:113], v[158:161], v[202:205], v[110:113]
	v_mfma_f32_16x16x32_bf16 v[106:109], v[166:169], v[202:205], v[106:109]
	v_mfma_f32_16x16x32_bf16 v[94:97], v[158:161], v[210:213], v[94:97]
	v_mfma_f32_16x16x32_bf16 v[90:93], v[166:169], v[210:213], v[90:93]
	v_mfma_f32_16x16x32_bf16 v[78:81], v[158:161], v[218:221], v[78:81]
	v_mfma_f32_16x16x32_bf16 v[74:77], v[166:169], v[218:221], v[74:77]
	v_mfma_f32_16x16x32_bf16 v[118:121], v[170:173], v[186:189], v[118:121]
	v_mfma_f32_16x16x32_bf16 v[114:117], v[178:181], v[186:189], v[114:117]
	v_mfma_f32_16x16x32_bf16 v[102:105], v[170:173], v[198:201], v[102:105]
	v_mfma_f32_16x16x32_bf16 v[98:101], v[178:181], v[198:201], v[98:101]
	v_mfma_f32_16x16x32_bf16 v[86:89], v[170:173], v[206:209], v[86:89]
	v_mfma_f32_16x16x32_bf16 v[82:85], v[178:181], v[206:209], v[82:85]
	v_mfma_f32_16x16x32_bf16 v[70:73], v[170:173], v[214:217], v[70:73]
	v_mfma_f32_16x16x32_bf16 v[66:69], v[178:181], v[214:217], v[66:69]
	v_mfma_f32_16x16x32_bf16 v[118:121], v[174:177], v[190:193], v[118:121]
	v_mfma_f32_16x16x32_bf16 v[114:117], v[182:185], v[190:193], v[114:117]
	v_mfma_f32_16x16x32_bf16 v[102:105], v[174:177], v[202:205], v[102:105]
	v_mfma_f32_16x16x32_bf16 v[98:101], v[182:185], v[202:205], v[98:101]
	v_mfma_f32_16x16x32_bf16 v[86:89], v[174:177], v[210:213], v[86:89]
	v_mfma_f32_16x16x32_bf16 v[82:85], v[182:185], v[210:213], v[82:85]
	v_mfma_f32_16x16x32_bf16 v[70:73], v[174:177], v[218:221], v[70:73]
	v_mfma_f32_16x16x32_bf16 v[66:69], v[182:185], v[218:221], v[66:69]
	s_barrier
	s_add_u32 s44, s44, 0x80
	s_addc_u32 s45, s45, 0
	s_add_i32 m0, s33, 0x18000
	ds_read_b128 v[186:189], v152 offset:49152
	ds_read_b128 v[190:193], v152 offset:50176
	ds_read_b128 v[198:201], v152 offset:51200
	ds_read_b128 v[202:205], v152 offset:52224
	ds_read_b128 v[206:209], v152 offset:53248
	ds_read_b128 v[210:213], v152 offset:54272
	ds_read_b128 v[214:217], v152 offset:55296
	ds_read_b128 v[218:221], v152 offset:56320
	global_load_lds_dwordx4 v132, s[44:45]
	s_add_i32 m0, s33, 0x1a000
	s_add_u32 s46, s46, 0xfff00080
	global_load_lds_dwordx4 v136, s[44:45]
	s_addc_u32 s47, s47, -1
	s_add_u32 s44, s44, 0x100000
	s_addc_u32 s45, s45, 0
	s_add_i32 m0, s33, 0x1c000
	s_nop 0
	global_load_lds_dwordx4 v132, s[44:45]
	s_add_i32 m0, s33, 0x1e000
	s_nop 0
	global_load_lds_dwordx4 v136, s[44:45]
	s_mov_b32 m0, s55
	s_nop 0
	global_load_lds_dwordx4 v130, s[46:47]
	s_mov_b32 m0, s56
	s_nop 0
	global_load_lds_dwordx4 v134, s[46:47]
	s_waitcnt vmcnt(8)
	s_waitcnt lgkmcnt(0)
	s_barrier
	v_mfma_f32_16x16x32_bf16 v[62:65], v[154:157], v[186:189], v[62:65]
	v_mfma_f32_16x16x32_bf16 v[58:61], v[162:165], v[186:189], v[58:61]
	v_mfma_f32_16x16x32_bf16 v[46:49], v[154:157], v[198:201], v[46:49]
	v_mfma_f32_16x16x32_bf16 v[42:45], v[162:165], v[198:201], v[42:45]
	v_mfma_f32_16x16x32_bf16 v[30:33], v[154:157], v[206:209], v[30:33]
	v_mfma_f32_16x16x32_bf16 v[26:29], v[162:165], v[206:209], v[26:29]
	v_mfma_f32_16x16x32_bf16 v[14:17], v[154:157], v[214:217], v[14:17]
	v_mfma_f32_16x16x32_bf16 v[10:13], v[162:165], v[214:217], v[10:13]
	v_mfma_f32_16x16x32_bf16 v[62:65], v[158:161], v[190:193], v[62:65]
	v_mfma_f32_16x16x32_bf16 v[58:61], v[166:169], v[190:193], v[58:61]
	v_mfma_f32_16x16x32_bf16 v[46:49], v[158:161], v[202:205], v[46:49]
	v_mfma_f32_16x16x32_bf16 v[42:45], v[166:169], v[202:205], v[42:45]
	v_mfma_f32_16x16x32_bf16 v[30:33], v[158:161], v[210:213], v[30:33]
	v_mfma_f32_16x16x32_bf16 v[26:29], v[166:169], v[210:213], v[26:29]
	v_mfma_f32_16x16x32_bf16 v[14:17], v[158:161], v[218:221], v[14:17]
	v_mfma_f32_16x16x32_bf16 v[10:13], v[166:169], v[218:221], v[10:13]
	v_mfma_f32_16x16x32_bf16 v[54:57], v[170:173], v[186:189], v[54:57]
	v_mfma_f32_16x16x32_bf16 v[50:53], v[178:181], v[186:189], v[50:53]
	v_mfma_f32_16x16x32_bf16 v[38:41], v[170:173], v[198:201], v[38:41]
	v_mfma_f32_16x16x32_bf16 v[34:37], v[178:181], v[198:201], v[34:37]
	v_mfma_f32_16x16x32_bf16 v[22:25], v[170:173], v[206:209], v[22:25]
	v_mfma_f32_16x16x32_bf16 v[18:21], v[178:181], v[206:209], v[18:21]
	v_mfma_f32_16x16x32_bf16 v[6:9], v[170:173], v[214:217], v[6:9]
	v_mfma_f32_16x16x32_bf16 v[2:5], v[178:181], v[214:217], v[2:5]
	v_mfma_f32_16x16x32_bf16 v[54:57], v[174:177], v[190:193], v[54:57]
	v_mfma_f32_16x16x32_bf16 v[50:53], v[182:185], v[190:193], v[50:53]
	v_mfma_f32_16x16x32_bf16 v[38:41], v[174:177], v[202:205], v[38:41]
	v_mfma_f32_16x16x32_bf16 v[34:37], v[182:185], v[202:205], v[34:37]
	v_mfma_f32_16x16x32_bf16 v[22:25], v[174:177], v[210:213], v[22:25]
	v_mfma_f32_16x16x32_bf16 v[18:21], v[182:185], v[210:213], v[18:21]
	v_mfma_f32_16x16x32_bf16 v[6:9], v[174:177], v[218:221], v[6:9]
	v_mfma_f32_16x16x32_bf16 v[2:5], v[182:185], v[218:221], v[2:5]
	s_barrier
	s_add_i32 s68, s68, 2
	s_add_u32 s42, s42, 0x100
	s_addc_u32 s43, s43, 0
	s_add_u32 s66, s66, 0x100
	s_addc_u32 s67, s67, 0
	s_cmp_gt_u32 s68, 61
	s_cbranch_scc0 .LBB0_807
	s_and_b64 vcc, exec, s[14:15]
	s_cbranch_vccz .LBB0_810
	s_barrier

.LBB0_868:
	s_cmp_lt_i32 s72, 6
	s_cselect_b64 s[0:1], -1, 0
	s_cmp_gt_i32 s73, 5
	s_cselect_b64 s[4:5], -1, 0
	s_and_b64 s[0:1], s[0:1], s[4:5]
	s_andn2_b64 vcc, exec, s[0:1]
	s_cbranch_vccnz .LBB0_961
	v_lshrrev_b32_e32 v1, 1, v0
	v_and_b32_e32 v142, 24, v1
	v_lshlrev_b32_e32 v1, 6, v0
	v_lshlrev_b32_e32 v2, 2, v0
	v_lshlrev_b32_e32 v146, 1, v142
	v_and_b32_e32 v1, 0x3c0, v1
	v_and_b32_e32 v2, 32, v2
	s_cmpk_lg_i32 s3, 0x100
	s_setprio 0
	v_readfirstlane_b32 s30, v0
	v_and_b32_e32 v145, 15, v0
	v_bitop3_b32 v147, v146, v2, v1 bitop3:0x36
	v_bfe_u32 v148, v0, 2, 2
	v_bfe_u32 v144, v0, 2, 4
	v_lshrrev_b32_e32 v149, 5, v0
	v_lshlrev_b32_e32 v1, 4, v0
	v_and_b32_e32 v151, 32, v0
	v_and_b32_e32 v143, 64, v0
	v_lshrrev_b32_e32 v150, 3, v0
	s_cbranch_scc1 .LBB0_877
	s_and_b32 s33, s74, 1
	s_lshr_b32 s14, s30, 6
	s_bfe_u32 s31, s74, 0x30001
	s_ashr_i32 s1, s74, 4
	s_lshr_b32 s15, s30, 8
	s_lshl_b32 s20, s14, 10
	s_lshl_b32 s21, s33, 14
	s_add_u32 s4, s10, s21
	s_addc_u32 s5, s11, 0
	s_mov_b32 s0, 0
	s_add_u32 s17, s22, s21
	s_addc_u32 s28, s23, 0
	v_and_b32_e32 v2, 4, v149
	v_or_b32_e32 v10, 0x2000, v1
	s_lshl_b32 s16, s31, 23
	s_ashr_i64 s[18:19], s[0:1], 9
	v_or3_b32 v2, v2, v148, v142
	s_waitcnt lgkmcnt(0)
	v_lshrrev_b32_e32 v3, 7, v10
	s_movk_i32 s6, 0x60
	v_bitop3_b32 v11, v1, v151, 48 bitop3:0x6c
	s_add_u32 s4, s4, s18
	v_and_or_b32 v4, v3, s6, v2
	v_or_b32_e32 v5, v11, v143
	v_and_or_b32 v2, v150, 32, v2
	s_addc_u32 s5, s5, s19
	s_add_i32 s0, s20, 0
	v_lshl_or_b32 v134, v2, 15, v5
	s_add_i32 m0, s0, 0x10000
	s_movk_i32 s6, 0x70
	global_load_lds_dwordx4 v134, s[4:5]
	s_add_i32 m0, s0, 0x12000
	v_lshl_or_b32 v130, v4, 15, v5
	v_and_or_b32 v3, v3, s6, v144
	s_add_u32 s6, s4, 0x400000
	global_load_lds_dwordx4 v130, s[4:5]
	s_addc_u32 s7, s5, 0
	s_add_i32 m0, s0, 0x14000
	v_and_or_b32 v2, v150, 48, v144
	global_load_lds_dwordx4 v134, s[6:7]
	s_add_i32 m0, s0, 0x16000
	s_add_u32 s17, s17, s16
	s_addc_u32 s29, s28, 0
	global_load_lds_dwordx4 v130, s[6:7]
	s_add_u32 s6, s17, 0x3f400000
	s_addc_u32 s7, s29, 0
	s_add_i32 s34, s0, 0x2000
	v_lshl_or_b32 v136, v2, 15, v5
	s_mov_b32 m0, s0
	s_add_u32 s28, s17, 1.0
	v_lshl_or_b32 v132, v3, 15, v5
	global_load_lds_dwordx4 v136, s[6:7]
	s_mov_b32 m0, s34
	s_addc_u32 s29, s29, 0
	s_add_i32 s36, s0, 0x4000
	global_load_lds_dwordx4 v132, s[6:7]
	s_mov_b32 m0, s36
	s_add_i32 s37, s0, 0x6000
	global_load_lds_dwordx4 v136, s[28:29]
	s_mov_b32 m0, s37
	v_mov_b32_e32 v135, 0
	global_load_lds_dwordx4 v132, s[28:29]
	v_mov_b32_e32 v131, v135
	v_mov_b32_e32 v137, v135
	v_mov_b32_e32 v133, v135
	v_lshl_add_u64 v[8:9], s[4:5], 0, v[134:135]
	v_lshl_add_u64 v[6:7], s[4:5], 0, v[130:131]
	v_lshl_add_u64 v[4:5], s[6:7], 0, v[136:137]
	s_cmp_lg_u32 s15, 1
	v_lshl_add_u64 v[2:3], s[6:7], 0, v[132:133]
	s_cbranch_scc1 .LBB0_872
	s_barrier

.LBB0_873:
	ds_read_b128 v[158:161], v153
	ds_read_b128 v[162:165], v153 offset:1024
	ds_read_b128 v[166:169], v153 offset:2048
	ds_read_b128 v[170:173], v153 offset:3072
	ds_read_b128 v[174:177], v154
	ds_read_b128 v[178:181], v154 offset:1024
	ds_read_b128 v[182:185], v154 offset:2048
	ds_read_b128 v[186:189], v154 offset:3072
	s_add_u32 s20, s16, s18
	s_addc_u32 s21, s17, s19
	s_add_u32 s20, s20, 0x3f400100
	s_addc_u32 s21, s21, 0
	s_add_u32 s53, s40, s18
	s_addc_u32 s54, s41, s19
	s_cmpk_eq_i32 s18, 0x3f00
	s_cselect_b32 s29, s7, s21
	s_cselect_b32 s28, s6, s20
	s_cselect_b32 s21, s5, s54
	s_cselect_b32 s20, s4, s53
	s_mov_b32 m0, s43
	v_lshl_add_u64 v[194:195], v[138:139], 0, s[18:19]
	ds_read_b128 v[190:193], v155
	ds_read_b128 v[198:201], v155 offset:1024
	ds_read_b128 v[202:205], v155 offset:2048
	ds_read_b128 v[206:209], v155 offset:3072
	ds_read_b128 v[210:213], v155 offset:4096
	ds_read_b128 v[214:217], v155 offset:5120
	ds_read_b128 v[218:221], v155 offset:6144
	ds_read_b128 v[222:225], v155 offset:7168
	global_load_lds_dwordx4 v[194:195], off
	v_lshl_add_u64 v[194:195], v[140:141], 0, s[18:19]
	s_mov_b32 m0, s44
	s_nop 0
	global_load_lds_dwordx4 v[194:195], off
	s_waitcnt vmcnt(8)
	s_waitcnt lgkmcnt(0)
	s_barrier
	v_mfma_f32_16x16x32_bf16 v[126:129], v[158:161], v[190:193], v[126:129]
	v_mfma_f32_16x16x32_bf16 v[122:125], v[166:169], v[190:193], v[122:125]
	v_mfma_f32_16x16x32_bf16 v[110:113], v[158:161], v[202:205], v[110:113]
	v_mfma_f32_16x16x32_bf16 v[106:109], v[166:169], v[202:205], v[106:109]
	v_mfma_f32_16x16x32_bf16 v[94:97], v[158:161], v[210:213], v[94:97]
	v_mfma_f32_16x16x32_bf16 v[90:93], v[166:169], v[210:213], v[90:93]
	v_mfma_f32_16x16x32_bf16 v[78:81], v[158:161], v[218:221], v[78:81]
	v_mfma_f32_16x16x32_bf16 v[74:77], v[166:169], v[218:221], v[74:77]
	v_mfma_f32_16x16x32_bf16 v[126:129], v[162:165], v[198:201], v[126:129]
	v_mfma_f32_16x16x32_bf16 v[122:125], v[170:173], v[198:201], v[122:125]
	v_mfma_f32_16x16x32_bf16 v[110:113], v[162:165], v[206:209], v[110:113]
	v_mfma_f32_16x16x32_bf16 v[106:109], v[170:173], v[206:209], v[106:109]
	v_mfma_f32_16x16x32_bf16 v[94:97], v[162:165], v[214:217], v[94:97]
	v_mfma_f32_16x16x32_bf16 v[90:93], v[170:173], v[214:217], v[90:93]
	v_mfma_f32_16x16x32_bf16 v[78:81], v[162:165], v[222:225], v[78:81]
	v_mfma_f32_16x16x32_bf16 v[74:77], v[170:173], v[222:225], v[74:77]
	v_mfma_f32_16x16x32_bf16 v[118:121], v[174:177], v[190:193], v[118:121]
	v_mfma_f32_16x16x32_bf16 v[114:117], v[182:185], v[190:193], v[114:117]
	v_mfma_f32_16x16x32_bf16 v[102:105], v[174:177], v[202:205], v[102:105]
	v_mfma_f32_16x16x32_bf16 v[98:101], v[182:185], v[202:205], v[98:101]
	v_mfma_f32_16x16x32_bf16 v[86:89], v[174:177], v[210:213], v[86:89]
	v_mfma_f32_16x16x32_bf16 v[82:85], v[182:185], v[210:213], v[82:85]
	v_mfma_f32_16x16x32_bf16 v[70:73], v[174:177], v[218:221], v[70:73]
	v_mfma_f32_16x16x32_bf16 v[66:69], v[182:185], v[218:221], v[66:69]
	v_mfma_f32_16x16x32_bf16 v[118:121], v[178:181], v[198:201], v[118:121]
	v_mfma_f32_16x16x32_bf16 v[114:117], v[186:189], v[198:201], v[114:117]
	v_mfma_f32_16x16x32_bf16 v[102:105], v[178:181], v[206:209], v[102:105]
	v_mfma_f32_16x16x32_bf16 v[98:101], v[186:189], v[206:209], v[98:101]
	v_mfma_f32_16x16x32_bf16 v[86:89], v[178:181], v[214:217], v[86:89]
	v_mfma_f32_16x16x32_bf16 v[82:85], v[186:189], v[214:217], v[82:85]
	v_mfma_f32_16x16x32_bf16 v[70:73], v[178:181], v[222:225], v[70:73]
	v_mfma_f32_16x16x32_bf16 v[66:69], v[186:189], v[222:225], v[66:69]
	s_barrier
	s_mov_b32 m0, s45
	v_lshl_add_u64 v[194:195], s[20:21], 0, v[134:135]
	s_add_u32 s54, s20, 0x400000
	ds_read_b128 v[190:193], v155 offset:16384
	ds_read_b128 v[198:201], v155 offset:17408
	ds_read_b128 v[202:205], v155 offset:18432
	ds_read_b128 v[206:209], v155 offset:19456
	ds_read_b128 v[210:213], v155 offset:20480
	ds_read_b128 v[214:217], v155 offset:21504
	ds_read_b128 v[218:221], v155 offset:22528
	ds_read_b128 v[222:225], v155 offset:23552
	global_load_lds_dwordx4 v[194:195], off
	v_lshl_add_u64 v[226:227], s[20:21], 0, v[130:131]
	s_mov_b32 m0, s46
	s_addc_u32 s55, s21, 0
	global_load_lds_dwordx4 v[226:227], off
	v_lshl_add_u64 v[228:229], s[54:55], 0, v[134:135]
	s_mov_b32 m0, s47
	v_lshl_add_u64 v[230:231], s[28:29], 0, v[132:133]
	global_load_lds_dwordx4 v[228:229], off
	v_lshl_add_u64 v[228:229], s[54:55], 0, v[130:131]
	s_mov_b32 m0, s48
	s_nop 0
	global_load_lds_dwordx4 v[228:229], off
	v_lshl_add_u64 v[228:229], s[28:29], 0, v[136:137]
	s_mov_b32 m0, s0
	s_nop 0
	global_load_lds_dwordx4 v[228:229], off
	s_mov_b32 m0, s34
	s_nop 0
	global_load_lds_dwordx4 v[230:231], off
	s_waitcnt vmcnt(8)
	s_waitcnt lgkmcnt(0)
	s_barrier
	v_mfma_f32_16x16x32_bf16 v[62:65], v[158:161], v[190:193], v[62:65]
	v_mfma_f32_16x16x32_bf16 v[58:61], v[166:169], v[190:193], v[58:61]
	v_mfma_f32_16x16x32_bf16 v[46:49], v[158:161], v[202:205], v[46:49]
	v_mfma_f32_16x16x32_bf16 v[42:45], v[166:169], v[202:205], v[42:45]
	v_mfma_f32_16x16x32_bf16 v[30:33], v[158:161], v[210:213], v[30:33]
	v_mfma_f32_16x16x32_bf16 v[26:29], v[166:169], v[210:213], v[26:29]
	v_mfma_f32_16x16x32_bf16 v[14:17], v[158:161], v[218:221], v[14:17]
	v_mfma_f32_16x16x32_bf16 v[10:13], v[166:169], v[218:221], v[10:13]
	v_mfma_f32_16x16x32_bf16 v[62:65], v[162:165], v[198:201], v[62:65]
	v_mfma_f32_16x16x32_bf16 v[58:61], v[170:173], v[198:201], v[58:61]
	v_mfma_f32_16x16x32_bf16 v[46:49], v[162:165], v[206:209], v[46:49]
	v_mfma_f32_16x16x32_bf16 v[42:45], v[170:173], v[206:209], v[42:45]
	v_mfma_f32_16x16x32_bf16 v[30:33], v[162:165], v[214:217], v[30:33]
	v_mfma_f32_16x16x32_bf16 v[26:29], v[170:173], v[214:217], v[26:29]
	v_mfma_f32_16x16x32_bf16 v[14:17], v[162:165], v[222:225], v[14:17]
	v_mfma_f32_16x16x32_bf16 v[10:13], v[170:173], v[222:225], v[10:13]
	v_mfma_f32_16x16x32_bf16 v[54:57], v[174:177], v[190:193], v[54:57]
	v_mfma_f32_16x16x32_bf16 v[50:53], v[182:185], v[190:193], v[50:53]
	v_mfma_f32_16x16x32_bf16 v[38:41], v[174:177], v[202:205], v[38:41]
	v_mfma_f32_16x16x32_bf16 v[34:37], v[182:185], v[202:205], v[34:37]
	v_mfma_f32_16x16x32_bf16 v[22:25], v[174:177], v[210:213], v[22:25]
	v_mfma_f32_16x16x32_bf16 v[18:21], v[182:185], v[210:213], v[18:21]
	v_mfma_f32_16x16x32_bf16 v[6:9], v[174:177], v[218:221], v[6:9]
	v_mfma_f32_16x16x32_bf16 v[2:5], v[182:185], v[218:221], v[2:5]
	v_mfma_f32_16x16x32_bf16 v[54:57], v[178:181], v[198:201], v[54:57]
	v_mfma_f32_16x16x32_bf16 v[50:53], v[186:189], v[198:201], v[50:53]
	v_mfma_f32_16x16x32_bf16 v[38:41], v[178:181], v[206:209], v[38:41]
	v_mfma_f32_16x16x32_bf16 v[34:37], v[186:189], v[206:209], v[34:37]
	v_mfma_f32_16x16x32_bf16 v[22:25], v[178:181], v[214:217], v[22:25]
	v_mfma_f32_16x16x32_bf16 v[18:21], v[186:189], v[214:217], v[18:21]
	v_mfma_f32_16x16x32_bf16 v[6:9], v[178:181], v[222:225], v[6:9]
	v_mfma_f32_16x16x32_bf16 v[2:5], v[186:189], v[222:225], v[2:5]
	s_barrier
	ds_read_b128 v[158:161], v156
	ds_read_b128 v[162:165], v156 offset:1024
	ds_read_b128 v[166:169], v156 offset:2048
	ds_read_b128 v[170:173], v156 offset:3072
	ds_read_b128 v[174:177], v157
	ds_read_b128 v[178:181], v157 offset:1024
	ds_read_b128 v[182:185], v157 offset:2048
	ds_read_b128 v[186:189], v157 offset:3072
	s_add_u32 s28, s28, 0x400000
	s_addc_u32 s29, s29, 0
	s_mov_b32 m0, s36
	v_lshl_add_u64 v[232:233], s[28:29], 0, v[136:137]
	ds_read_b128 v[190:193], v155 offset:32768
	ds_read_b128 v[198:201], v155 offset:33792
	ds_read_b128 v[202:205], v155 offset:34816
	ds_read_b128 v[206:209], v155 offset:35840
	ds_read_b128 v[210:213], v155 offset:36864
	ds_read_b128 v[214:217], v155 offset:37888
	ds_read_b128 v[218:221], v155 offset:38912
	ds_read_b128 v[222:225], v155 offset:39936
	global_load_lds_dwordx4 v[232:233], off
	v_lshl_add_u64 v[232:233], s[28:29], 0, v[132:133]
	s_mov_b32 m0, s37
	s_nop 0
	global_load_lds_dwordx4 v[232:233], off
	s_waitcnt vmcnt(8)
	s_waitcnt lgkmcnt(0)
	s_barrier
	v_mfma_f32_16x16x32_bf16 v[126:129], v[158:161], v[190:193], v[126:129]
	v_mfma_f32_16x16x32_bf16 v[122:125], v[166:169], v[190:193], v[122:125]
	v_mfma_f32_16x16x32_bf16 v[110:113], v[158:161], v[202:205], v[110:113]
	v_mfma_f32_16x16x32_bf16 v[106:109], v[166:169], v[202:205], v[106:109]
	v_mfma_f32_16x16x32_bf16 v[94:97], v[158:161], v[210:213], v[94:97]
	v_mfma_f32_16x16x32_bf16 v[90:93], v[166:169], v[210:213], v[90:93]
	v_mfma_f32_16x16x32_bf16 v[78:81], v[158:161], v[218:221], v[78:81]
	v_mfma_f32_16x16x32_bf16 v[74:77], v[166:169], v[218:221], v[74:77]
	v_mfma_f32_16x16x32_bf16 v[126:129], v[162:165], v[198:201], v[126:129]
	v_mfma_f32_16x16x32_bf16 v[122:125], v[170:173], v[198:201], v[122:125]
	v_mfma_f32_16x16x32_bf16 v[110:113], v[162:165], v[206:209], v[110:113]
	v_mfma_f32_16x16x32_bf16 v[106:109], v[170:173], v[206:209], v[106:109]
	v_mfma_f32_16x16x32_bf16 v[94:97], v[162:165], v[214:217], v[94:97]
	v_mfma_f32_16x16x32_bf16 v[90:93], v[170:173], v[214:217], v[90:93]
	v_mfma_f32_16x16x32_bf16 v[78:81], v[162:165], v[222:225], v[78:81]
	v_mfma_f32_16x16x32_bf16 v[74:77], v[170:173], v[222:225], v[74:77]
	v_mfma_f32_16x16x32_bf16 v[118:121], v[174:177], v[190:193], v[118:121]
	v_mfma_f32_16x16x32_bf16 v[114:117], v[182:185], v[190:193], v[114:117]
	v_mfma_f32_16x16x32_bf16 v[102:105], v[174:177], v[202:205], v[102:105]
	v_mfma_f32_16x16x32_bf16 v[98:101], v[182:185], v[202:205], v[98:101]
	v_mfma_f32_16x16x32_bf16 v[86:89], v[174:177], v[210:213], v[86:89]
	v_mfma_f32_16x16x32_bf16 v[82:85], v[182:185], v[210:213], v[82:85]
	v_mfma_f32_16x16x32_bf16 v[70:73], v[174:177], v[218:221], v[70:73]
	v_mfma_f32_16x16x32_bf16 v[66:69], v[182:185], v[218:221], v[66:69]
	v_mfma_f32_16x16x32_bf16 v[118:121], v[178:181], v[198:201], v[118:121]
	v_mfma_f32_16x16x32_bf16 v[114:117], v[186:189], v[198:201], v[114:117]
	v_mfma_f32_16x16x32_bf16 v[102:105], v[178:181], v[206:209], v[102:105]
	v_mfma_f32_16x16x32_bf16 v[98:101], v[186:189], v[206:209], v[98:101]
	v_mfma_f32_16x16x32_bf16 v[86:89], v[178:181], v[214:217], v[86:89]
	v_mfma_f32_16x16x32_bf16 v[82:85], v[186:189], v[214:217], v[82:85]
	v_mfma_f32_16x16x32_bf16 v[70:73], v[178:181], v[222:225], v[70:73]
	v_mfma_f32_16x16x32_bf16 v[66:69], v[186:189], v[222:225], v[66:69]
	s_barrier
	s_mov_b32 m0, s49
	v_lshl_add_u64 v[194:195], v[194:195], 0, s[14:15]
	s_add_u32 s20, s20, 0x400080
	ds_read_b128 v[190:193], v155 offset:49152
	ds_read_b128 v[198:201], v155 offset:50176
	ds_read_b128 v[202:205], v155 offset:51200
	ds_read_b128 v[206:209], v155 offset:52224
	ds_read_b128 v[210:213], v155 offset:53248
	ds_read_b128 v[214:217], v155 offset:54272
	ds_read_b128 v[218:221], v155 offset:55296
	ds_read_b128 v[222:225], v155 offset:56320
	global_load_lds_dwordx4 v[194:195], off
	v_lshl_add_u64 v[194:195], v[226:227], 0, s[14:15]
	s_mov_b32 m0, s50
	s_addc_u32 s21, s21, 0
	global_load_lds_dwordx4 v[194:195], off
	v_lshl_add_u64 v[194:195], s[20:21], 0, v[134:135]
	s_mov_b32 m0, s51
	s_nop 0
	global_load_lds_dwordx4 v[194:195], off
	v_lshl_add_u64 v[194:195], s[20:21], 0, v[130:131]
	s_mov_b32 m0, s52
	s_nop 0
	global_load_lds_dwordx4 v[194:195], off
	v_lshl_add_u64 v[194:195], v[228:229], 0, s[14:15]
	s_mov_b32 m0, s38
	s_nop 0
	global_load_lds_dwordx4 v[194:195], off
	v_lshl_add_u64 v[194:195], v[230:231], 0, s[14:15]
	s_mov_b32 m0, s39
	s_nop 0
	global_load_lds_dwordx4 v[194:195], off
	s_waitcnt vmcnt(8)
	s_waitcnt lgkmcnt(0)
	s_barrier
	v_mfma_f32_16x16x32_bf16 v[62:65], v[158:161], v[190:193], v[62:65]
	v_mfma_f32_16x16x32_bf16 v[58:61], v[166:169], v[190:193], v[58:61]
	v_mfma_f32_16x16x32_bf16 v[46:49], v[158:161], v[202:205], v[46:49]
	v_mfma_f32_16x16x32_bf16 v[42:45], v[166:169], v[202:205], v[42:45]
	v_mfma_f32_16x16x32_bf16 v[30:33], v[158:161], v[210:213], v[30:33]
	v_mfma_f32_16x16x32_bf16 v[26:29], v[166:169], v[210:213], v[26:29]
	v_mfma_f32_16x16x32_bf16 v[14:17], v[158:161], v[218:221], v[14:17]
	v_mfma_f32_16x16x32_bf16 v[10:13], v[166:169], v[218:221], v[10:13]
	v_mfma_f32_16x16x32_bf16 v[62:65], v[162:165], v[198:201], v[62:65]
	v_mfma_f32_16x16x32_bf16 v[58:61], v[170:173], v[198:201], v[58:61]
	v_mfma_f32_16x16x32_bf16 v[46:49], v[162:165], v[206:209], v[46:49]
	v_mfma_f32_16x16x32_bf16 v[42:45], v[170:173], v[206:209], v[42:45]
	v_mfma_f32_16x16x32_bf16 v[30:33], v[162:165], v[214:217], v[30:33]
	v_mfma_f32_16x16x32_bf16 v[26:29], v[170:173], v[214:217], v[26:29]
	v_mfma_f32_16x16x32_bf16 v[14:17], v[162:165], v[222:225], v[14:17]
	v_mfma_f32_16x16x32_bf16 v[10:13], v[170:173], v[222:225], v[10:13]
	v_mfma_f32_16x16x32_bf16 v[54:57], v[174:177], v[190:193], v[54:57]
	v_mfma_f32_16x16x32_bf16 v[50:53], v[182:185], v[190:193], v[50:53]
	v_mfma_f32_16x16x32_bf16 v[38:41], v[174:177], v[202:205], v[38:41]
	v_mfma_f32_16x16x32_bf16 v[34:37], v[182:185], v[202:205], v[34:37]
	v_mfma_f32_16x16x32_bf16 v[22:25], v[174:177], v[210:213], v[22:25]
	v_mfma_f32_16x16x32_bf16 v[18:21], v[182:185], v[210:213], v[18:21]
	v_mfma_f32_16x16x32_bf16 v[6:9], v[174:177], v[218:221], v[6:9]
	v_mfma_f32_16x16x32_bf16 v[2:5], v[182:185], v[218:221], v[2:5]
	v_mfma_f32_16x16x32_bf16 v[54:57], v[178:181], v[198:201], v[54:57]
	v_mfma_f32_16x16x32_bf16 v[50:53], v[186:189], v[198:201], v[50:53]
	v_mfma_f32_16x16x32_bf16 v[38:41], v[178:181], v[206:209], v[38:41]
	v_mfma_f32_16x16x32_bf16 v[34:37], v[186:189], v[206:209], v[34:37]
	v_mfma_f32_16x16x32_bf16 v[22:25], v[178:181], v[214:217], v[22:25]
	v_mfma_f32_16x16x32_bf16 v[18:21], v[186:189], v[214:217], v[18:21]
	v_mfma_f32_16x16x32_bf16 v[6:9], v[178:181], v[222:225], v[6:9]
	v_mfma_f32_16x16x32_bf16 v[2:5], v[186:189], v[222:225], v[2:5]
	s_barrier
	s_add_i32 s42, s42, 2
	s_add_u32 s18, s18, 0x100
	s_addc_u32 s19, s19, 0
	s_cmpk_gt_u32 s42, 0x7d
	s_cbranch_scc0 .LBB0_873
	s_lshl_b32 s0, s33, 25
	s_add_u32 s0, s22, s0
	s_addc_u32 s5, s23, 0
	s_add_u32 s4, s0, 0x43800000
	s_addc_u32 s5, s5, 0
	s_add_u32 s6, s22, 0x20000
	s_addc_u32 s7, s23, 0
	v_lshl_add_u32 v130, s31, 8, v152
	v_mov_b32_e32 v131, 0
	v_lshl_add_u64 v[132:133], v[130:131], 2, s[6:7]
	global_load_dword v137, v[132:133], off
	v_mov_b32_e32 v136, 0x358637bd
	v_lshl_or_b32 v134, s1, 8, v142
	v_or_b32_e32 v134, s35, v134
	v_lshlrev_b64 v[138:139], 14, v[130:131]
	v_ashrrev_i32_e32 v135, 31, v134
	v_lshlrev_b64 v[134:135], 2, v[134:135]
	v_lshl_add_u64 v[138:139], s[4:5], 0, v[138:139]
	v_or_b32_e32 v140, 16, v130
	v_mov_b32_e32 v141, v131
	v_lshl_add_u64 v[138:139], v[138:139], 0, v[134:135]
	v_lshl_add_u64 v[152:153], v[140:141], 2, s[6:7]
	s_cmpk_lt_u32 s30, 0x100
	s_cbranch_scc1 .Lstatprio_4
	s_setprio 1
.Lstatprio_4:
	s_waitcnt vmcnt(0)
	v_fmamk_f32 v137, v137, 0x39800000, v136
	v_div_scale_f32 v154, s[0:1], v137, v137, 1.0
	v_rcp_f32_e32 v155, v154
	v_div_scale_f32 v156, vcc, 1.0, v137, 1.0
	v_fma_f32 v157, -v154, v155, 1.0
	v_fmac_f32_e32 v155, v157, v155
	v_mul_f32_e32 v157, v156, v155
	v_fma_f32 v158, -v154, v157, v156
	v_fmac_f32_e32 v157, v158, v155
	v_fma_f32 v154, -v154, v157, v156
	v_div_fmas_f32 v154, v154, v155, v157
	v_div_fixup_f32 v154, v154, v137, 1.0
	v_pk_mul_f32 v[128:129], v[128:129], v[154:155] op_sel_hi:[1,0]
	v_pk_mul_f32 v[126:127], v[126:127], v[154:155] op_sel_hi:[1,0]
	v_pk_mul_f32 v[124:125], v[124:125], v[154:155] op_sel_hi:[1,0]
	v_pk_mul_f32 v[122:123], v[122:123], v[154:155] op_sel_hi:[1,0]
	v_pk_mul_f32 v[120:121], v[120:121], v[154:155] op_sel_hi:[1,0]
	v_pk_mul_f32 v[118:119], v[118:119], v[154:155] op_sel_hi:[1,0]
	v_pk_mul_f32 v[116:117], v[116:117], v[154:155] op_sel_hi:[1,0]
	v_pk_mul_f32 v[114:115], v[114:115], v[154:155] op_sel_hi:[1,0]
	global_store_dwordx4 v[138:139], v[126:129], off
	global_store_dwordx4 v[138:139], v[122:125], off offset:16
	global_store_dwordx4 v[138:139], v[118:121], off offset:512
	global_store_dwordx4 v[138:139], v[114:117], off offset:528
	global_load_dword v118, v[152:153], off
	s_waitcnt vmcnt(0)
	v_fmamk_f32 v120, v118, 0x39800000, v136
	v_div_scale_f32 v121, s[0:1], v120, v120, 1.0
	v_rcp_f32_e32 v122, v121
	v_div_scale_f32 v123, vcc, 1.0, v120, 1.0
	v_lshlrev_b64 v[116:117], 14, v[140:141]
	v_fma_f32 v124, -v121, v122, 1.0
	v_fmac_f32_e32 v122, v124, v122
	v_mul_f32_e32 v124, v123, v122
	v_fma_f32 v125, -v121, v124, v123
	v_fmac_f32_e32 v124, v125, v122
	v_fma_f32 v121, -v121, v124, v123
	v_div_fmas_f32 v121, v121, v122, v124
	v_lshl_add_u64 v[116:117], s[4:5], 0, v[116:117]
	v_div_fixup_f32 v120, v121, v120, 1.0
	v_or_b32_e32 v114, 32, v130
	v_mov_b32_e32 v115, v131
	v_lshl_add_u64 v[116:117], v[116:117], 0, v[134:135]
	v_pk_mul_f32 v[112:113], v[112:113], v[120:121] op_sel_hi:[1,0]
	v_pk_mul_f32 v[110:111], v[110:111], v[120:121] op_sel_hi:[1,0]
	v_lshl_add_u64 v[118:119], v[114:115], 2, s[6:7]
	v_pk_mul_f32 v[108:109], v[108:109], v[120:121] op_sel_hi:[1,0]
	v_pk_mul_f32 v[106:107], v[106:107], v[120:121] op_sel_hi:[1,0]
	v_pk_mul_f32 v[104:105], v[104:105], v[120:121] op_sel_hi:[1,0]
	v_pk_mul_f32 v[102:103], v[102:103], v[120:121] op_sel_hi:[1,0]
	v_pk_mul_f32 v[100:101], v[100:101], v[120:121] op_sel_hi:[1,0]
	v_pk_mul_f32 v[98:99], v[98:99], v[120:121] op_sel_hi:[1,0]
	global_store_dwordx4 v[116:117], v[110:113], off
	global_store_dwordx4 v[116:117], v[106:109], off offset:16
	global_store_dwordx4 v[116:117], v[102:105], off offset:512
	global_store_dwordx4 v[116:117], v[98:101], off offset:528
	global_load_dword v102, v[118:119], off
	s_waitcnt vmcnt(0)
	v_fmamk_f32 v104, v102, 0x39800000, v136
	v_div_scale_f32 v105, s[0:1], v104, v104, 1.0
	v_rcp_f32_e32 v106, v105
	v_div_scale_f32 v107, vcc, 1.0, v104, 1.0
	v_lshlrev_b64 v[100:101], 14, v[114:115]
	v_fma_f32 v108, -v105, v106, 1.0
	v_fmac_f32_e32 v106, v108, v106
	v_mul_f32_e32 v108, v107, v106
	v_fma_f32 v109, -v105, v108, v107
	v_fmac_f32_e32 v108, v109, v106
	v_fma_f32 v105, -v105, v108, v107
	v_div_fmas_f32 v105, v105, v106, v108
	v_lshl_add_u64 v[100:101], s[4:5], 0, v[100:101]
	v_div_fixup_f32 v104, v105, v104, 1.0
	v_or_b32_e32 v98, 48, v130
	v_mov_b32_e32 v99, v131
	v_lshl_add_u64 v[100:101], v[100:101], 0, v[134:135]
	v_pk_mul_f32 v[96:97], v[96:97], v[104:105] op_sel_hi:[1,0]
	v_pk_mul_f32 v[94:95], v[94:95], v[104:105] op_sel_hi:[1,0]
	v_lshl_add_u64 v[102:103], v[98:99], 2, s[6:7]
	v_pk_mul_f32 v[92:93], v[92:93], v[104:105] op_sel_hi:[1,0]
	v_pk_mul_f32 v[90:91], v[90:91], v[104:105] op_sel_hi:[1,0]
	v_pk_mul_f32 v[88:89], v[88:89], v[104:105] op_sel_hi:[1,0]
	v_pk_mul_f32 v[86:87], v[86:87], v[104:105] op_sel_hi:[1,0]
	v_pk_mul_f32 v[84:85], v[84:85], v[104:105] op_sel_hi:[1,0]
	v_pk_mul_f32 v[82:83], v[82:83], v[104:105] op_sel_hi:[1,0]
	global_store_dwordx4 v[100:101], v[94:97], off
	global_store_dwordx4 v[100:101], v[90:93], off offset:16
	global_store_dwordx4 v[100:101], v[86:89], off offset:512
	global_store_dwordx4 v[100:101], v[82:85], off offset:528
	global_load_dword v84, v[102:103], off
	s_nop 0
	v_lshlrev_b64 v[82:83], 14, v[98:99]
	v_lshl_add_u64 v[82:83], s[4:5], 0, v[82:83]
	v_lshl_add_u64 v[82:83], v[82:83], 0, v[134:135]
	s_waitcnt vmcnt(0)
	v_fmamk_f32 v84, v84, 0x39800000, v136
	v_div_scale_f32 v85, s[0:1], v84, v84, 1.0
	v_rcp_f32_e32 v86, v85
	v_div_scale_f32 v87, vcc, 1.0, v84, 1.0
	v_fma_f32 v88, -v85, v86, 1.0
	v_fmac_f32_e32 v86, v88, v86
	v_mul_f32_e32 v88, v87, v86
	v_fma_f32 v89, -v85, v88, v87
	v_fmac_f32_e32 v88, v89, v86
	v_fma_f32 v85, -v85, v88, v87
	v_div_fmas_f32 v85, v85, v86, v88
	v_div_fixup_f32 v84, v85, v84, 1.0
	v_pk_mul_f32 v[80:81], v[80:81], v[84:85] op_sel_hi:[1,0]
	v_pk_mul_f32 v[78:79], v[78:79], v[84:85] op_sel_hi:[1,0]
	v_pk_mul_f32 v[76:77], v[76:77], v[84:85] op_sel_hi:[1,0]
	v_pk_mul_f32 v[74:75], v[74:75], v[84:85] op_sel_hi:[1,0]
	v_pk_mul_f32 v[72:73], v[72:73], v[84:85] op_sel_hi:[1,0]
	v_pk_mul_f32 v[70:71], v[70:71], v[84:85] op_sel_hi:[1,0]
	v_pk_mul_f32 v[68:69], v[68:69], v[84:85] op_sel_hi:[1,0]
	v_pk_mul_f32 v[66:67], v[66:67], v[84:85] op_sel_hi:[1,0]
	global_store_dwordx4 v[82:83], v[78:81], off
	global_store_dwordx4 v[82:83], v[74:77], off offset:16
	global_store_dwordx4 v[82:83], v[70:73], off offset:512
	global_store_dwordx4 v[82:83], v[66:69], off offset:528
	global_load_dword v68, v[132:133], off offset:512
	s_nop 0
	v_add_u32_e32 v66, 0x80, v130
	v_mov_b32_e32 v67, v131
	v_lshlrev_b64 v[66:67], 14, v[66:67]
	v_lshl_add_u64 v[66:67], s[4:5], 0, v[66:67]
	v_lshl_add_u64 v[66:67], v[66:67], 0, v[134:135]
	s_waitcnt vmcnt(0)
	v_fmamk_f32 v68, v68, 0x39800000, v136
	v_div_scale_f32 v69, s[0:1], v68, v68, 1.0
	v_rcp_f32_e32 v70, v69
	v_div_scale_f32 v71, vcc, 1.0, v68, 1.0
	v_fma_f32 v72, -v69, v70, 1.0
	v_fmac_f32_e32 v70, v72, v70
	v_mul_f32_e32 v72, v71, v70
	v_fma_f32 v73, -v69, v72, v71
	v_fmac_f32_e32 v72, v73, v70
	v_fma_f32 v69, -v69, v72, v71
	v_div_fmas_f32 v69, v69, v70, v72
	v_div_fixup_f32 v68, v69, v68, 1.0
	v_pk_mul_f32 v[64:65], v[64:65], v[68:69] op_sel_hi:[1,0]
	v_pk_mul_f32 v[62:63], v[62:63], v[68:69] op_sel_hi:[1,0]
	v_pk_mul_f32 v[60:61], v[60:61], v[68:69] op_sel_hi:[1,0]
	v_pk_mul_f32 v[58:59], v[58:59], v[68:69] op_sel_hi:[1,0]
	v_pk_mul_f32 v[56:57], v[56:57], v[68:69] op_sel_hi:[1,0]
	v_pk_mul_f32 v[54:55], v[54:55], v[68:69] op_sel_hi:[1,0]
	v_pk_mul_f32 v[52:53], v[52:53], v[68:69] op_sel_hi:[1,0]
	v_pk_mul_f32 v[50:51], v[50:51], v[68:69] op_sel_hi:[1,0]
	global_store_dwordx4 v[66:67], v[62:65], off
	global_store_dwordx4 v[66:67], v[58:61], off offset:16
	global_store_dwordx4 v[66:67], v[54:57], off offset:512
	global_store_dwordx4 v[66:67], v[50:53], off offset:528
	global_load_dword v52, v[132:133], off offset:576
	s_nop 0
	v_add_u32_e32 v50, 0x90, v130
	v_mov_b32_e32 v51, v131
	v_lshlrev_b64 v[50:51], 14, v[50:51]
	v_lshl_add_u64 v[50:51], s[4:5], 0, v[50:51]
	v_lshl_add_u64 v[50:51], v[50:51], 0, v[134:135]
	s_waitcnt vmcnt(0)
	v_fmamk_f32 v52, v52, 0x39800000, v136
	v_div_scale_f32 v53, s[0:1], v52, v52, 1.0
	v_rcp_f32_e32 v54, v53
	v_div_scale_f32 v55, vcc, 1.0, v52, 1.0
	v_fma_f32 v56, -v53, v54, 1.0
	v_fmac_f32_e32 v54, v56, v54
	v_mul_f32_e32 v56, v55, v54
	v_fma_f32 v57, -v53, v56, v55
	v_fmac_f32_e32 v56, v57, v54
	v_fma_f32 v53, -v53, v56, v55
	v_div_fmas_f32 v53, v53, v54, v56
	v_div_fixup_f32 v52, v53, v52, 1.0
	v_pk_mul_f32 v[48:49], v[48:49], v[52:53] op_sel_hi:[1,0]
	v_pk_mul_f32 v[46:47], v[46:47], v[52:53] op_sel_hi:[1,0]
	v_pk_mul_f32 v[44:45], v[44:45], v[52:53] op_sel_hi:[1,0]
	v_pk_mul_f32 v[42:43], v[42:43], v[52:53] op_sel_hi:[1,0]
	v_pk_mul_f32 v[40:41], v[40:41], v[52:53] op_sel_hi:[1,0]
	v_pk_mul_f32 v[38:39], v[38:39], v[52:53] op_sel_hi:[1,0]
	v_pk_mul_f32 v[36:37], v[36:37], v[52:53] op_sel_hi:[1,0]
	v_pk_mul_f32 v[34:35], v[34:35], v[52:53] op_sel_hi:[1,0]
	global_store_dwordx4 v[50:51], v[46:49], off
	global_store_dwordx4 v[50:51], v[42:45], off offset:16
	global_store_dwordx4 v[50:51], v[38:41], off offset:512
	global_store_dwordx4 v[50:51], v[34:37], off offset:528
	global_load_dword v36, v[132:133], off offset:640
	s_nop 0
	v_add_u32_e32 v34, 0xa0, v130
	v_mov_b32_e32 v35, v131
	v_lshlrev_b64 v[34:35], 14, v[34:35]
	v_lshl_add_u64 v[34:35], s[4:5], 0, v[34:35]
	v_lshl_add_u64 v[34:35], v[34:35], 0, v[134:135]
	v_add_u32_e32 v130, 0xb0, v130
	s_waitcnt vmcnt(0)
	v_fmamk_f32 v36, v36, 0x39800000, v136
	v_div_scale_f32 v37, s[0:1], v36, v36, 1.0
	v_rcp_f32_e32 v38, v37
	v_div_scale_f32 v39, vcc, 1.0, v36, 1.0
	v_fma_f32 v40, -v37, v38, 1.0
	v_fmac_f32_e32 v38, v40, v38
	v_mul_f32_e32 v40, v39, v38
	v_fma_f32 v41, -v37, v40, v39
	v_fmac_f32_e32 v40, v41, v38
	v_fma_f32 v37, -v37, v40, v39
	v_div_fmas_f32 v37, v37, v38, v40
	v_div_fixup_f32 v36, v37, v36, 1.0
	v_pk_mul_f32 v[32:33], v[32:33], v[36:37] op_sel_hi:[1,0]
	v_pk_mul_f32 v[30:31], v[30:31], v[36:37] op_sel_hi:[1,0]
	v_pk_mul_f32 v[28:29], v[28:29], v[36:37] op_sel_hi:[1,0]
	v_pk_mul_f32 v[26:27], v[26:27], v[36:37] op_sel_hi:[1,0]
	v_pk_mul_f32 v[24:25], v[24:25], v[36:37] op_sel_hi:[1,0]
	v_pk_mul_f32 v[22:23], v[22:23], v[36:37] op_sel_hi:[1,0]
	v_pk_mul_f32 v[20:21], v[20:21], v[36:37] op_sel_hi:[1,0]
	v_pk_mul_f32 v[18:19], v[18:19], v[36:37] op_sel_hi:[1,0]
	global_store_dwordx4 v[34:35], v[30:33], off
	global_store_dwordx4 v[34:35], v[26:29], off offset:16
	global_store_dwordx4 v[34:35], v[22:25], off offset:512
	global_store_dwordx4 v[34:35], v[18:21], off offset:528
	global_load_dword v20, v[132:133], off offset:704
	s_waitcnt vmcnt(0)
	v_fmac_f32_e32 v136, 0x39800000, v20
	v_div_scale_f32 v20, s[0:1], v136, v136, 1.0
	v_rcp_f32_e32 v21, v20
	v_div_scale_f32 v22, vcc, 1.0, v136, 1.0
	v_lshlrev_b64 v[18:19], 14, v[130:131]
	v_fma_f32 v23, -v20, v21, 1.0
	v_fmac_f32_e32 v21, v23, v21
	v_mul_f32_e32 v23, v22, v21
	v_fma_f32 v24, -v20, v23, v22
	v_fmac_f32_e32 v23, v24, v21
	v_fma_f32 v20, -v20, v23, v22
	v_div_fmas_f32 v20, v20, v21, v23
	v_lshl_add_u64 v[18:19], s[4:5], 0, v[18:19]
	v_div_fixup_f32 v20, v20, v136, 1.0
	v_lshl_add_u64 v[18:19], v[18:19], 0, v[134:135]
	v_pk_mul_f32 v[16:17], v[16:17], v[20:21] op_sel_hi:[1,0]
	v_pk_mul_f32 v[14:15], v[14:15], v[20:21] op_sel_hi:[1,0]
	v_pk_mul_f32 v[12:13], v[12:13], v[20:21] op_sel_hi:[1,0]
	v_pk_mul_f32 v[10:11], v[10:11], v[20:21] op_sel_hi:[1,0]
	v_pk_mul_f32 v[8:9], v[8:9], v[20:21] op_sel_hi:[1,0]
	v_pk_mul_f32 v[6:7], v[6:7], v[20:21] op_sel_hi:[1,0]
	v_pk_mul_f32 v[4:5], v[4:5], v[20:21] op_sel_hi:[1,0]
	v_pk_mul_f32 v[2:3], v[2:3], v[20:21] op_sel_hi:[1,0]
	global_store_dwordx4 v[18:19], v[14:17], off
	global_store_dwordx4 v[18:19], v[10:13], off offset:16
	global_store_dwordx4 v[18:19], v[6:9], off offset:512
	global_store_dwordx4 v[18:19], v[2:5], off offset:528
	s_waitcnt vmcnt(0)
	s_cbranch_scc0 .LBB0_876
	s_barrier

.LBB0_880:
	s_or_b64 exec, exec, s[0:1]
	s_cmpk_gt_i32 s2, 0x3ff
	s_setprio 0
	v_readfirstlane_b32 s14, v0
	s_cbranch_scc1 .LBB0_904
	s_ashr_i32 s33, s2, 31
	s_lshr_b32 s0, s33, 29
	s_add_i32 s6, s2, s0
	s_and_b32 s0, s6, -8
	s_sub_i32 s5, s2, s0
	s_cmp_gt_i32 s5, -1
	s_cbranch_scc0 .LBB0_883
	s_lshl_b32 s4, s5, 7
	s_ashr_i32 s0, s6, 3
	s_cbranch_execz .LBB0_884
	s_branch .LBB0_885

.LBB0_887:
	s_lshl_b32 s6, s6, 5
	s_and_b32 s18, s6, 0x60
	s_mov_b64 s[6:7], 0x80
	s_add_i32 m0, s41, 0x18000
	v_lshl_add_u64 v[8:9], v[8:9], 0, s[6:7]
	s_lshl_b32 s15, s1, 13
	s_waitcnt vmcnt(2)
	s_barrier
	global_load_lds_dwordx4 v[8:9], off
	v_lshl_add_u64 v[6:7], v[6:7], 0, s[6:7]
	s_add_i32 m0, s41, 0x1a000
	s_add_i32 s53, s41, 0x8000
	s_add_i32 s54, s41, 0xa000
	global_load_lds_dwordx4 v[6:7], off
	v_lshl_add_u64 v[2:3], v[2:3], 0, s[6:7]
	s_mov_b32 m0, s53
	s_add_u32 s16, s44, 0x400080
	global_load_lds_dwordx4 v[2:3], off
	v_lshl_add_u64 v[2:3], v[4:5], 0, s[6:7]
	s_mov_b32 m0, s54
	s_addc_u32 s17, s45, 0
	global_load_lds_dwordx4 v[2:3], off
	s_add_i32 m0, s41, 0x1c000
	v_lshl_add_u64 v[2:3], s[16:17], 0, v[132:133]
	global_load_lds_dwordx4 v[2:3], off
	v_lshl_add_u64 v[2:3], s[16:17], 0, v[136:137]
	s_add_i32 m0, s41, 0x1e000
	v_lshlrev_b32_e32 v4, 15, v144
	global_load_lds_dwordx4 v[2:3], off
	v_lshlrev_b32_e32 v3, 2, v145
	v_lshl_or_b32 v2, v145, 6, v146
	v_and_b32_e32 v3, 32, v3
	v_bitop3_b32 v2, v2, s15, v3 bitop3:0xde
	v_lshlrev_b32_e32 v3, 12, v0
	v_and_b32_e32 v3, 0x180000, v3
	v_or3_b32 v3, v10, v3, v4
	v_add_u32_e32 v138, v3, v143
	v_lshlrev_b32_e32 v3, 8, v11
	s_waitcnt vmcnt(6)
	s_cmpk_lt_u32 s14, 0x100
	s_cbranch_scc1 .Lstatprio_5
	s_setprio 1
.Lstatprio_5:
	v_and_b32_e32 v3, 0x380000, v3
	v_lshl_or_b32 v154, s18, 7, v147
	s_cselect_b64 s[14:15], -1, 0
	v_or3_b32 v3, v10, v3, v4
	s_add_i32 s56, 0, 0x10000
	s_add_i32 s57, 0, 0x14000
	s_sext_i32_i8 s62, s0
	v_lshl_or_b32 v1, s1, 6, v145
	s_ashr_i32 s55, s3, 31
	v_or_b32_e32 v155, s18, v142
	v_mov_b32_e32 v139, v133
	v_add_u32_e32 v140, v3, v143
	v_mov_b32_e32 v141, v133
	v_mov_b64_e32 v[142:143], 0x400
	v_mov_b64_e32 v[144:145], 0x3ff
	v_add_u32_e32 v156, s56, v154
	v_add_u32_e32 v157, s57, v154
	v_add_u32_e32 v158, 0, v2
	v_mov_b32_e32 v159, 0x358637bd
	s_mov_b64 s[16:17], 0x100000
	s_mov_b32 s58, 0x100000
	s_mov_b64 s[18:19], 0x120000
	s_mov_b32 s59, 0x120000
	s_mov_b64 s[20:21], 0x140000
	s_mov_b32 s60, 0x140000
	s_mov_b64 s[28:29], 0x160000
	s_mov_b32 s61, 0x160000
	s_barrier
	s_branch .LBB0_890

.LBB0_896:
	s_ashr_i32 s35, s34, 31
	s_lshl_b64 s[36:37], s[34:35], 23
	s_add_u32 s36, s86, s36
	s_addc_u32 s37, s87, s37
	s_and_b64 s[38:39], s[0:1], exec
	s_cselect_b32 s35, s37, s43
	s_cselect_b32 s63, s36, s42
	s_ashr_i32 s31, s30, 31
	s_lshl_b64 s[38:39], s[30:31], 23
	s_add_u32 s38, s10, s38
	s_addc_u32 s39, s11, s39
	s_and_b64 s[46:47], s[0:1], exec
	s_cselect_b32 s31, s39, s45
	s_cselect_b32 s64, s38, s44
	s_add_u32 s42, s42, 0x400080
	s_addc_u32 s43, s43, 0
	s_add_u32 s65, s44, 0x100
	s_addc_u32 s66, s45, 0
	s_mov_b32 s67, -2
	ds_read_b128 v[146:149], v156
	ds_read_b128 v[150:153], v156 offset:1024
	ds_read_b128 v[160:163], v156 offset:2048
	ds_read_b128 v[164:167], v156 offset:3072
	ds_read_b128 v[168:171], v157
	ds_read_b128 v[172:175], v157 offset:1024
	ds_read_b128 v[176:179], v157 offset:2048
	ds_read_b128 v[180:183], v157 offset:3072
	s_add_u32 s44, s42, 0xffc00080
	s_addc_u32 s45, s43, -1
	s_cmpk_eq_i32 s67, 0xfc
	s_cselect_b32 s47, s35, s45
	s_cselect_b32 s46, s63, s44
	s_cselect_b32 s45, s31, s66
	s_cselect_b32 s44, s64, s65
	s_add_i32 m0, s41, 0xc000
	ds_read_b128 v[184:187], v158
	ds_read_b128 v[188:191], v158 offset:1024
	ds_read_b128 v[192:195], v158 offset:2048
	ds_read_b128 v[198:201], v158 offset:3072
	ds_read_b128 v[202:205], v158 offset:4096
	ds_read_b128 v[206:209], v158 offset:5120
	ds_read_b128 v[210:213], v158 offset:6144
	ds_read_b128 v[214:217], v158 offset:7168
	global_load_lds_dwordx4 v138, s[42:43]
	s_add_i32 m0, s41, 0xe000
	s_nop 0
	global_load_lds_dwordx4 v140, s[42:43]
	s_waitcnt vmcnt(24)
	s_waitcnt lgkmcnt(0)
	s_barrier
	v_mfma_f32_16x16x32_bf16 v[126:129], v[146:149], v[184:187], 0
	v_mfma_f32_16x16x32_bf16 v[122:125], v[160:163], v[184:187], 0
	v_mfma_f32_16x16x32_bf16 v[110:113], v[146:149], v[192:195], 0
	v_mfma_f32_16x16x32_bf16 v[106:109], v[160:163], v[192:195], 0
	v_mfma_f32_16x16x32_bf16 v[94:97], v[146:149], v[202:205], 0
	v_mfma_f32_16x16x32_bf16 v[90:93], v[160:163], v[202:205], 0
	v_mfma_f32_16x16x32_bf16 v[78:81], v[146:149], v[210:213], 0
	v_mfma_f32_16x16x32_bf16 v[74:77], v[160:163], v[210:213], 0
	v_mfma_f32_16x16x32_bf16 v[126:129], v[150:153], v[188:191], v[126:129]
	v_mfma_f32_16x16x32_bf16 v[122:125], v[164:167], v[188:191], v[122:125]
	v_mfma_f32_16x16x32_bf16 v[110:113], v[150:153], v[198:201], v[110:113]
	v_mfma_f32_16x16x32_bf16 v[106:109], v[164:167], v[198:201], v[106:109]
	v_mfma_f32_16x16x32_bf16 v[94:97], v[150:153], v[206:209], v[94:97]
	v_mfma_f32_16x16x32_bf16 v[90:93], v[164:167], v[206:209], v[90:93]
	v_mfma_f32_16x16x32_bf16 v[78:81], v[150:153], v[214:217], v[78:81]
	v_mfma_f32_16x16x32_bf16 v[74:77], v[164:167], v[214:217], v[74:77]
	v_mfma_f32_16x16x32_bf16 v[118:121], v[168:171], v[184:187], 0
	v_mfma_f32_16x16x32_bf16 v[114:117], v[176:179], v[184:187], 0
	v_mfma_f32_16x16x32_bf16 v[102:105], v[168:171], v[192:195], 0
	v_mfma_f32_16x16x32_bf16 v[98:101], v[176:179], v[192:195], 0
	v_mfma_f32_16x16x32_bf16 v[86:89], v[168:171], v[202:205], 0
	v_mfma_f32_16x16x32_bf16 v[82:85], v[176:179], v[202:205], 0
	v_mfma_f32_16x16x32_bf16 v[70:73], v[168:171], v[210:213], 0
	v_mfma_f32_16x16x32_bf16 v[66:69], v[176:179], v[210:213], 0
	v_mfma_f32_16x16x32_bf16 v[118:121], v[172:175], v[188:191], v[118:121]
	v_mfma_f32_16x16x32_bf16 v[114:117], v[180:183], v[188:191], v[114:117]
	v_mfma_f32_16x16x32_bf16 v[102:105], v[172:175], v[198:201], v[102:105]
	v_mfma_f32_16x16x32_bf16 v[98:101], v[180:183], v[198:201], v[98:101]
	v_mfma_f32_16x16x32_bf16 v[86:89], v[172:175], v[206:209], v[86:89]
	v_mfma_f32_16x16x32_bf16 v[82:85], v[180:183], v[206:209], v[82:85]
	v_mfma_f32_16x16x32_bf16 v[70:73], v[172:175], v[214:217], v[70:73]
	v_mfma_f32_16x16x32_bf16 v[66:69], v[180:183], v[214:217], v[66:69]
	s_barrier
	s_add_i32 s68, s56, s48
	s_mov_b32 m0, s68
	ds_read_b128 v[184:187], v158 offset:16384
	ds_read_b128 v[188:191], v158 offset:17408
	ds_read_b128 v[192:195], v158 offset:18432
	ds_read_b128 v[198:201], v158 offset:19456
	ds_read_b128 v[202:205], v158 offset:20480
	ds_read_b128 v[206:209], v158 offset:21504
	ds_read_b128 v[210:213], v158 offset:22528
	ds_read_b128 v[214:217], v158 offset:23552
	global_load_lds_dwordx4 v132, s[44:45]
	s_add_i32 m0, s68, 0x2000
	s_add_u32 s68, s44, 0x400000
	s_addc_u32 s69, s45, 0
	s_add_i32 s70, s57, s48
	global_load_lds_dwordx4 v136, s[44:45]
	s_mov_b32 m0, s70
	global_load_lds_dwordx4 v132, s[68:69]
	s_add_i32 m0, s70, 0x2000
	s_nop 0
	global_load_lds_dwordx4 v136, s[68:69]
	s_mov_b32 m0, s41
	s_nop 0
	global_load_lds_dwordx4 v130, s[46:47]
	s_mov_b32 m0, s49
	s_nop 0
	global_load_lds_dwordx4 v134, s[46:47]
	s_waitcnt vmcnt(24)
	s_waitcnt lgkmcnt(0)
	s_barrier
	v_mfma_f32_16x16x32_bf16 v[62:65], v[146:149], v[184:187], 0
	v_mfma_f32_16x16x32_bf16 v[58:61], v[160:163], v[184:187], 0
	v_mfma_f32_16x16x32_bf16 v[46:49], v[146:149], v[192:195], 0
	v_mfma_f32_16x16x32_bf16 v[42:45], v[160:163], v[192:195], 0
	v_mfma_f32_16x16x32_bf16 v[30:33], v[146:149], v[202:205], 0
	v_mfma_f32_16x16x32_bf16 v[26:29], v[160:163], v[202:205], 0
	v_mfma_f32_16x16x32_bf16 v[14:17], v[146:149], v[210:213], 0
	v_mfma_f32_16x16x32_bf16 v[10:13], v[160:163], v[210:213], 0
	v_mfma_f32_16x16x32_bf16 v[62:65], v[150:153], v[188:191], v[62:65]
	v_mfma_f32_16x16x32_bf16 v[58:61], v[164:167], v[188:191], v[58:61]
	v_mfma_f32_16x16x32_bf16 v[46:49], v[150:153], v[198:201], v[46:49]
	v_mfma_f32_16x16x32_bf16 v[42:45], v[164:167], v[198:201], v[42:45]
	v_mfma_f32_16x16x32_bf16 v[30:33], v[150:153], v[206:209], v[30:33]
	v_mfma_f32_16x16x32_bf16 v[26:29], v[164:167], v[206:209], v[26:29]
	v_mfma_f32_16x16x32_bf16 v[14:17], v[150:153], v[214:217], v[14:17]
	v_mfma_f32_16x16x32_bf16 v[10:13], v[164:167], v[214:217], v[10:13]
	v_mfma_f32_16x16x32_bf16 v[54:57], v[168:171], v[184:187], 0
	v_mfma_f32_16x16x32_bf16 v[50:53], v[176:179], v[184:187], 0
	v_mfma_f32_16x16x32_bf16 v[38:41], v[168:171], v[192:195], 0
	v_mfma_f32_16x16x32_bf16 v[34:37], v[176:179], v[192:195], 0
	v_mfma_f32_16x16x32_bf16 v[22:25], v[168:171], v[202:205], 0
	v_mfma_f32_16x16x32_bf16 v[18:21], v[176:179], v[202:205], 0
	v_mfma_f32_16x16x32_bf16 v[6:9], v[168:171], v[210:213], 0
	v_mfma_f32_16x16x32_bf16 v[2:5], v[176:179], v[210:213], 0
	v_mfma_f32_16x16x32_bf16 v[54:57], v[172:175], v[188:191], v[54:57]
	v_mfma_f32_16x16x32_bf16 v[50:53], v[180:183], v[188:191], v[50:53]
	v_mfma_f32_16x16x32_bf16 v[38:41], v[172:175], v[198:201], v[38:41]
	v_mfma_f32_16x16x32_bf16 v[34:37], v[180:183], v[198:201], v[34:37]
	v_mfma_f32_16x16x32_bf16 v[22:25], v[172:175], v[206:209], v[22:25]
	v_mfma_f32_16x16x32_bf16 v[18:21], v[180:183], v[206:209], v[18:21]
	v_mfma_f32_16x16x32_bf16 v[6:9], v[172:175], v[214:217], v[6:9]
	v_mfma_f32_16x16x32_bf16 v[2:5], v[180:183], v[214:217], v[2:5]
	s_barrier
	s_add_i32 s68, 0, 0x18000
	s_add_i32 s69, 0, 0x1c000
	v_add_u32_e32 v164, s68, v154
	v_add_u32_e32 v180, s69, v154
	ds_read_b128 v[146:149], v164
	ds_read_b128 v[150:153], v164 offset:1024
	ds_read_b128 v[160:163], v164 offset:2048
	ds_read_b128 v[164:167], v164 offset:3072
	ds_read_b128 v[168:171], v180
	ds_read_b128 v[172:175], v180 offset:1024
	ds_read_b128 v[176:179], v180 offset:2048
	ds_read_b128 v[180:183], v180 offset:3072
	s_add_u32 s46, s46, 0x400000
	s_addc_u32 s47, s47, 0
	s_mov_b32 m0, s50
	ds_read_b128 v[184:187], v158 offset:32768
	ds_read_b128 v[188:191], v158 offset:33792
	ds_read_b128 v[192:195], v158 offset:34816
	ds_read_b128 v[198:201], v158 offset:35840
	ds_read_b128 v[202:205], v158 offset:36864
	ds_read_b128 v[206:209], v158 offset:37888
	ds_read_b128 v[210:213], v158 offset:38912
	ds_read_b128 v[214:217], v158 offset:39936
	global_load_lds_dwordx4 v130, s[46:47]
	s_mov_b32 m0, s51
	s_nop 0
	global_load_lds_dwordx4 v134, s[46:47]
	s_waitcnt vmcnt(8)
	s_waitcnt lgkmcnt(0)
	s_barrier
	v_mfma_f32_16x16x32_bf16 v[126:129], v[146:149], v[184:187], v[126:129]
	v_mfma_f32_16x16x32_bf16 v[122:125], v[160:163], v[184:187], v[122:125]
	v_mfma_f32_16x16x32_bf16 v[110:113], v[146:149], v[192:195], v[110:113]
	v_mfma_f32_16x16x32_bf16 v[106:109], v[160:163], v[192:195], v[106:109]
	v_mfma_f32_16x16x32_bf16 v[94:97], v[146:149], v[202:205], v[94:97]
	v_mfma_f32_16x16x32_bf16 v[90:93], v[160:163], v[202:205], v[90:93]
	v_mfma_f32_16x16x32_bf16 v[78:81], v[146:149], v[210:213], v[78:81]
	v_mfma_f32_16x16x32_bf16 v[74:77], v[160:163], v[210:213], v[74:77]
	v_mfma_f32_16x16x32_bf16 v[126:129], v[150:153], v[188:191], v[126:129]
	v_mfma_f32_16x16x32_bf16 v[122:125], v[164:167], v[188:191], v[122:125]
	v_mfma_f32_16x16x32_bf16 v[110:113], v[150:153], v[198:201], v[110:113]
	v_mfma_f32_16x16x32_bf16 v[106:109], v[164:167], v[198:201], v[106:109]
	v_mfma_f32_16x16x32_bf16 v[94:97], v[150:153], v[206:209], v[94:97]
	v_mfma_f32_16x16x32_bf16 v[90:93], v[164:167], v[206:209], v[90:93]
	v_mfma_f32_16x16x32_bf16 v[78:81], v[150:153], v[214:217], v[78:81]
	v_mfma_f32_16x16x32_bf16 v[74:77], v[164:167], v[214:217], v[74:77]
	v_mfma_f32_16x16x32_bf16 v[118:121], v[168:171], v[184:187], v[118:121]
	v_mfma_f32_16x16x32_bf16 v[114:117], v[176:179], v[184:187], v[114:117]
	v_mfma_f32_16x16x32_bf16 v[102:105], v[168:171], v[192:195], v[102:105]
	v_mfma_f32_16x16x32_bf16 v[98:101], v[176:179], v[192:195], v[98:101]
	v_mfma_f32_16x16x32_bf16 v[86:89], v[168:171], v[202:205], v[86:89]
	v_mfma_f32_16x16x32_bf16 v[82:85], v[176:179], v[202:205], v[82:85]
	v_mfma_f32_16x16x32_bf16 v[70:73], v[168:171], v[210:213], v[70:73]
	v_mfma_f32_16x16x32_bf16 v[66:69], v[176:179], v[210:213], v[66:69]
	v_mfma_f32_16x16x32_bf16 v[118:121], v[172:175], v[188:191], v[118:121]
	v_mfma_f32_16x16x32_bf16 v[114:117], v[180:183], v[188:191], v[114:117]
	v_mfma_f32_16x16x32_bf16 v[102:105], v[172:175], v[198:201], v[102:105]
	v_mfma_f32_16x16x32_bf16 v[98:101], v[180:183], v[198:201], v[98:101]
	v_mfma_f32_16x16x32_bf16 v[86:89], v[172:175], v[206:209], v[86:89]
	v_mfma_f32_16x16x32_bf16 v[82:85], v[180:183], v[206:209], v[82:85]
	v_mfma_f32_16x16x32_bf16 v[70:73], v[172:175], v[214:217], v[70:73]
	v_mfma_f32_16x16x32_bf16 v[66:69], v[180:183], v[214:217], v[66:69]
	s_barrier
	s_add_u32 s44, s44, 0x80
	s_addc_u32 s45, s45, 0
	s_add_i32 m0, s48, 0x18000
	ds_read_b128 v[184:187], v158 offset:49152
	ds_read_b128 v[188:191], v158 offset:50176
	ds_read_b128 v[192:195], v158 offset:51200
	ds_read_b128 v[198:201], v158 offset:52224
	ds_read_b128 v[202:205], v158 offset:53248
	ds_read_b128 v[206:209], v158 offset:54272
	ds_read_b128 v[210:213], v158 offset:55296
	ds_read_b128 v[214:217], v158 offset:56320
	global_load_lds_dwordx4 v132, s[44:45]
	s_add_i32 m0, s48, 0x1a000
	s_add_u32 s46, s46, 0xffc00080
	global_load_lds_dwordx4 v136, s[44:45]
	s_addc_u32 s47, s47, -1
	s_add_u32 s44, s44, 0x400000
	s_addc_u32 s45, s45, 0
	s_add_i32 m0, s48, 0x1c000
	s_nop 0
	global_load_lds_dwordx4 v132, s[44:45]
	s_add_i32 m0, s48, 0x1e000
	s_nop 0
	global_load_lds_dwordx4 v136, s[44:45]
	s_mov_b32 m0, s53
	s_nop 0
	global_load_lds_dwordx4 v130, s[46:47]
	s_mov_b32 m0, s54
	s_nop 0
	global_load_lds_dwordx4 v134, s[46:47]
	s_waitcnt vmcnt(8)
	s_waitcnt lgkmcnt(0)
	s_barrier
	v_mfma_f32_16x16x32_bf16 v[62:65], v[146:149], v[184:187], v[62:65]
	v_mfma_f32_16x16x32_bf16 v[58:61], v[160:163], v[184:187], v[58:61]
	v_mfma_f32_16x16x32_bf16 v[46:49], v[146:149], v[192:195], v[46:49]
	v_mfma_f32_16x16x32_bf16 v[42:45], v[160:163], v[192:195], v[42:45]
	v_mfma_f32_16x16x32_bf16 v[30:33], v[146:149], v[202:205], v[30:33]
	v_mfma_f32_16x16x32_bf16 v[26:29], v[160:163], v[202:205], v[26:29]
	v_mfma_f32_16x16x32_bf16 v[14:17], v[146:149], v[210:213], v[14:17]
	v_mfma_f32_16x16x32_bf16 v[10:13], v[160:163], v[210:213], v[10:13]
	v_mfma_f32_16x16x32_bf16 v[62:65], v[150:153], v[188:191], v[62:65]
	v_mfma_f32_16x16x32_bf16 v[58:61], v[164:167], v[188:191], v[58:61]
	v_mfma_f32_16x16x32_bf16 v[46:49], v[150:153], v[198:201], v[46:49]
	v_mfma_f32_16x16x32_bf16 v[42:45], v[164:167], v[198:201], v[42:45]
	v_mfma_f32_16x16x32_bf16 v[30:33], v[150:153], v[206:209], v[30:33]
	v_mfma_f32_16x16x32_bf16 v[26:29], v[164:167], v[206:209], v[26:29]
	v_mfma_f32_16x16x32_bf16 v[14:17], v[150:153], v[214:217], v[14:17]
	v_mfma_f32_16x16x32_bf16 v[10:13], v[164:167], v[214:217], v[10:13]
	v_mfma_f32_16x16x32_bf16 v[54:57], v[168:171], v[184:187], v[54:57]
	v_mfma_f32_16x16x32_bf16 v[50:53], v[176:179], v[184:187], v[50:53]
	v_mfma_f32_16x16x32_bf16 v[38:41], v[168:171], v[192:195], v[38:41]
	v_mfma_f32_16x16x32_bf16 v[34:37], v[176:179], v[192:195], v[34:37]
	v_mfma_f32_16x16x32_bf16 v[22:25], v[168:171], v[202:205], v[22:25]
	v_mfma_f32_16x16x32_bf16 v[18:21], v[176:179], v[202:205], v[18:21]
	v_mfma_f32_16x16x32_bf16 v[6:9], v[168:171], v[210:213], v[6:9]
	v_mfma_f32_16x16x32_bf16 v[2:5], v[176:179], v[210:213], v[2:5]
	v_mfma_f32_16x16x32_bf16 v[54:57], v[172:175], v[188:191], v[54:57]
	v_mfma_f32_16x16x32_bf16 v[50:53], v[180:183], v[188:191], v[50:53]
	v_mfma_f32_16x16x32_bf16 v[38:41], v[172:175], v[198:201], v[38:41]
	v_mfma_f32_16x16x32_bf16 v[34:37], v[180:183], v[198:201], v[34:37]
	v_mfma_f32_16x16x32_bf16 v[22:25], v[172:175], v[206:209], v[22:25]
	v_mfma_f32_16x16x32_bf16 v[18:21], v[180:183], v[206:209], v[18:21]
	v_mfma_f32_16x16x32_bf16 v[6:9], v[172:175], v[214:217], v[6:9]
	v_mfma_f32_16x16x32_bf16 v[2:5], v[180:183], v[214:217], v[2:5]
	s_barrier
	s_add_i32 s67, s67, 2
	s_add_u32 s42, s42, 0x100
	s_addc_u32 s43, s43, 0
	s_add_u32 s65, s65, 0x100
	s_addc_u32 s66, s66, 0
	s_cmpk_gt_u32 s67, 0xfd
	.p2align	8
.LBB0_897:
	ds_read_b128 v[146:149], v156
	ds_read_b128 v[150:153], v156 offset:1024
	ds_read_b128 v[160:163], v156 offset:2048
	ds_read_b128 v[164:167], v156 offset:3072
	ds_read_b128 v[168:171], v157
	ds_read_b128 v[172:175], v157 offset:1024
	ds_read_b128 v[176:179], v157 offset:2048
	ds_read_b128 v[180:183], v157 offset:3072
	s_add_u32 s44, s42, 0xffc00080
	s_addc_u32 s45, s43, -1
	s_cmpk_eq_i32 s67, 0xfc
	s_cselect_b32 s47, s35, s45
	s_cselect_b32 s46, s63, s44
	s_cselect_b32 s45, s31, s66
	s_cselect_b32 s44, s64, s65
	s_add_i32 m0, s41, 0xc000
	ds_read_b128 v[184:187], v158
	ds_read_b128 v[188:191], v158 offset:1024
	ds_read_b128 v[192:195], v158 offset:2048
	ds_read_b128 v[198:201], v158 offset:3072
	ds_read_b128 v[202:205], v158 offset:4096
	ds_read_b128 v[206:209], v158 offset:5120
	ds_read_b128 v[210:213], v158 offset:6144
	ds_read_b128 v[214:217], v158 offset:7168
	global_load_lds_dwordx4 v138, s[42:43]
	s_add_i32 m0, s41, 0xe000
	s_nop 0
	global_load_lds_dwordx4 v140, s[42:43]
	s_waitcnt vmcnt(8)
	s_waitcnt lgkmcnt(0)
	s_barrier
	v_mfma_f32_16x16x32_bf16 v[126:129], v[146:149], v[184:187], v[126:129]
	v_mfma_f32_16x16x32_bf16 v[122:125], v[160:163], v[184:187], v[122:125]
	v_mfma_f32_16x16x32_bf16 v[110:113], v[146:149], v[192:195], v[110:113]
	v_mfma_f32_16x16x32_bf16 v[106:109], v[160:163], v[192:195], v[106:109]
	v_mfma_f32_16x16x32_bf16 v[94:97], v[146:149], v[202:205], v[94:97]
	v_mfma_f32_16x16x32_bf16 v[90:93], v[160:163], v[202:205], v[90:93]
	v_mfma_f32_16x16x32_bf16 v[78:81], v[146:149], v[210:213], v[78:81]
	v_mfma_f32_16x16x32_bf16 v[74:77], v[160:163], v[210:213], v[74:77]
	v_mfma_f32_16x16x32_bf16 v[126:129], v[150:153], v[188:191], v[126:129]
	v_mfma_f32_16x16x32_bf16 v[122:125], v[164:167], v[188:191], v[122:125]
	v_mfma_f32_16x16x32_bf16 v[110:113], v[150:153], v[198:201], v[110:113]
	v_mfma_f32_16x16x32_bf16 v[106:109], v[164:167], v[198:201], v[106:109]
	v_mfma_f32_16x16x32_bf16 v[94:97], v[150:153], v[206:209], v[94:97]
	v_mfma_f32_16x16x32_bf16 v[90:93], v[164:167], v[206:209], v[90:93]
	v_mfma_f32_16x16x32_bf16 v[78:81], v[150:153], v[214:217], v[78:81]
	v_mfma_f32_16x16x32_bf16 v[74:77], v[164:167], v[214:217], v[74:77]
	v_mfma_f32_16x16x32_bf16 v[118:121], v[168:171], v[184:187], v[118:121]
	v_mfma_f32_16x16x32_bf16 v[114:117], v[176:179], v[184:187], v[114:117]
	v_mfma_f32_16x16x32_bf16 v[102:105], v[168:171], v[192:195], v[102:105]
	v_mfma_f32_16x16x32_bf16 v[98:101], v[176:179], v[192:195], v[98:101]
	v_mfma_f32_16x16x32_bf16 v[86:89], v[168:171], v[202:205], v[86:89]
	v_mfma_f32_16x16x32_bf16 v[82:85], v[176:179], v[202:205], v[82:85]
	v_mfma_f32_16x16x32_bf16 v[70:73], v[168:171], v[210:213], v[70:73]
	v_mfma_f32_16x16x32_bf16 v[66:69], v[176:179], v[210:213], v[66:69]
	v_mfma_f32_16x16x32_bf16 v[118:121], v[172:175], v[188:191], v[118:121]
	v_mfma_f32_16x16x32_bf16 v[114:117], v[180:183], v[188:191], v[114:117]
	v_mfma_f32_16x16x32_bf16 v[102:105], v[172:175], v[198:201], v[102:105]
	v_mfma_f32_16x16x32_bf16 v[98:101], v[180:183], v[198:201], v[98:101]
	v_mfma_f32_16x16x32_bf16 v[86:89], v[172:175], v[206:209], v[86:89]
	v_mfma_f32_16x16x32_bf16 v[82:85], v[180:183], v[206:209], v[82:85]
	v_mfma_f32_16x16x32_bf16 v[70:73], v[172:175], v[214:217], v[70:73]
	v_mfma_f32_16x16x32_bf16 v[66:69], v[180:183], v[214:217], v[66:69]
	s_barrier
	s_add_i32 s68, s56, s48
	s_mov_b32 m0, s68
	ds_read_b128 v[184:187], v158 offset:16384
	ds_read_b128 v[188:191], v158 offset:17408
	ds_read_b128 v[192:195], v158 offset:18432
	ds_read_b128 v[198:201], v158 offset:19456
	ds_read_b128 v[202:205], v158 offset:20480
	ds_read_b128 v[206:209], v158 offset:21504
	ds_read_b128 v[210:213], v158 offset:22528
	ds_read_b128 v[214:217], v158 offset:23552
	global_load_lds_dwordx4 v132, s[44:45]
	s_add_i32 m0, s68, 0x2000
	s_add_u32 s68, s44, 0x400000
	s_addc_u32 s69, s45, 0
	s_add_i32 s70, s57, s48
	global_load_lds_dwordx4 v136, s[44:45]
	s_mov_b32 m0, s70
	global_load_lds_dwordx4 v132, s[68:69]
	s_add_i32 m0, s70, 0x2000
	s_nop 0
	global_load_lds_dwordx4 v136, s[68:69]
	s_mov_b32 m0, s41
	s_nop 0
	global_load_lds_dwordx4 v130, s[46:47]
	s_mov_b32 m0, s49
	s_nop 0
	global_load_lds_dwordx4 v134, s[46:47]
	s_waitcnt vmcnt(8)
	s_waitcnt lgkmcnt(0)
	s_barrier
	v_mfma_f32_16x16x32_bf16 v[62:65], v[146:149], v[184:187], v[62:65]
	v_mfma_f32_16x16x32_bf16 v[58:61], v[160:163], v[184:187], v[58:61]
	v_mfma_f32_16x16x32_bf16 v[46:49], v[146:149], v[192:195], v[46:49]
	v_mfma_f32_16x16x32_bf16 v[42:45], v[160:163], v[192:195], v[42:45]
	v_mfma_f32_16x16x32_bf16 v[30:33], v[146:149], v[202:205], v[30:33]
	v_mfma_f32_16x16x32_bf16 v[26:29], v[160:163], v[202:205], v[26:29]
	v_mfma_f32_16x16x32_bf16 v[14:17], v[146:149], v[210:213], v[14:17]
	v_mfma_f32_16x16x32_bf16 v[10:13], v[160:163], v[210:213], v[10:13]
	v_mfma_f32_16x16x32_bf16 v[62:65], v[150:153], v[188:191], v[62:65]
	v_mfma_f32_16x16x32_bf16 v[58:61], v[164:167], v[188:191], v[58:61]
	v_mfma_f32_16x16x32_bf16 v[46:49], v[150:153], v[198:201], v[46:49]
	v_mfma_f32_16x16x32_bf16 v[42:45], v[164:167], v[198:201], v[42:45]
	v_mfma_f32_16x16x32_bf16 v[30:33], v[150:153], v[206:209], v[30:33]
	v_mfma_f32_16x16x32_bf16 v[26:29], v[164:167], v[206:209], v[26:29]
	v_mfma_f32_16x16x32_bf16 v[14:17], v[150:153], v[214:217], v[14:17]
	v_mfma_f32_16x16x32_bf16 v[10:13], v[164:167], v[214:217], v[10:13]
	v_mfma_f32_16x16x32_bf16 v[54:57], v[168:171], v[184:187], v[54:57]
	v_mfma_f32_16x16x32_bf16 v[50:53], v[176:179], v[184:187], v[50:53]
	v_mfma_f32_16x16x32_bf16 v[38:41], v[168:171], v[192:195], v[38:41]
	v_mfma_f32_16x16x32_bf16 v[34:37], v[176:179], v[192:195], v[34:37]
	v_mfma_f32_16x16x32_bf16 v[22:25], v[168:171], v[202:205], v[22:25]
	v_mfma_f32_16x16x32_bf16 v[18:21], v[176:179], v[202:205], v[18:21]
	v_mfma_f32_16x16x32_bf16 v[6:9], v[168:171], v[210:213], v[6:9]
	v_mfma_f32_16x16x32_bf16 v[2:5], v[176:179], v[210:213], v[2:5]
	v_mfma_f32_16x16x32_bf16 v[54:57], v[172:175], v[188:191], v[54:57]
	v_mfma_f32_16x16x32_bf16 v[50:53], v[180:183], v[188:191], v[50:53]
	v_mfma_f32_16x16x32_bf16 v[38:41], v[172:175], v[198:201], v[38:41]
	v_mfma_f32_16x16x32_bf16 v[34:37], v[180:183], v[198:201], v[34:37]
	v_mfma_f32_16x16x32_bf16 v[22:25], v[172:175], v[206:209], v[22:25]
	v_mfma_f32_16x16x32_bf16 v[18:21], v[180:183], v[206:209], v[18:21]
	v_mfma_f32_16x16x32_bf16 v[6:9], v[172:175], v[214:217], v[6:9]
	v_mfma_f32_16x16x32_bf16 v[2:5], v[180:183], v[214:217], v[2:5]
	s_barrier
	s_add_i32 s68, 0, 0x18000
	s_add_i32 s69, 0, 0x1c000
	v_add_u32_e32 v164, s68, v154
	v_add_u32_e32 v180, s69, v154
	ds_read_b128 v[146:149], v164
	ds_read_b128 v[150:153], v164 offset:1024
	ds_read_b128 v[160:163], v164 offset:2048
	ds_read_b128 v[164:167], v164 offset:3072
	ds_read_b128 v[168:171], v180
	ds_read_b128 v[172:175], v180 offset:1024
	ds_read_b128 v[176:179], v180 offset:2048
	ds_read_b128 v[180:183], v180 offset:3072
	s_add_u32 s46, s46, 0x400000
	s_addc_u32 s47, s47, 0
	s_mov_b32 m0, s50
	ds_read_b128 v[184:187], v158 offset:32768
	ds_read_b128 v[188:191], v158 offset:33792
	ds_read_b128 v[192:195], v158 offset:34816
	ds_read_b128 v[198:201], v158 offset:35840
	ds_read_b128 v[202:205], v158 offset:36864
	ds_read_b128 v[206:209], v158 offset:37888
	ds_read_b128 v[210:213], v158 offset:38912
	ds_read_b128 v[214:217], v158 offset:39936
	global_load_lds_dwordx4 v130, s[46:47]
	s_mov_b32 m0, s51
	s_nop 0
	global_load_lds_dwordx4 v134, s[46:47]
	s_waitcnt vmcnt(8)
	s_waitcnt lgkmcnt(0)
	s_barrier
	v_mfma_f32_16x16x32_bf16 v[126:129], v[146:149], v[184:187], v[126:129]
	v_mfma_f32_16x16x32_bf16 v[122:125], v[160:163], v[184:187], v[122:125]
	v_mfma_f32_16x16x32_bf16 v[110:113], v[146:149], v[192:195], v[110:113]
	v_mfma_f32_16x16x32_bf16 v[106:109], v[160:163], v[192:195], v[106:109]
	v_mfma_f32_16x16x32_bf16 v[94:97], v[146:149], v[202:205], v[94:97]
	v_mfma_f32_16x16x32_bf16 v[90:93], v[160:163], v[202:205], v[90:93]
	v_mfma_f32_16x16x32_bf16 v[78:81], v[146:149], v[210:213], v[78:81]
	v_mfma_f32_16x16x32_bf16 v[74:77], v[160:163], v[210:213], v[74:77]
	v_mfma_f32_16x16x32_bf16 v[126:129], v[150:153], v[188:191], v[126:129]
	v_mfma_f32_16x16x32_bf16 v[122:125], v[164:167], v[188:191], v[122:125]
	v_mfma_f32_16x16x32_bf16 v[110:113], v[150:153], v[198:201], v[110:113]
	v_mfma_f32_16x16x32_bf16 v[106:109], v[164:167], v[198:201], v[106:109]
	v_mfma_f32_16x16x32_bf16 v[94:97], v[150:153], v[206:209], v[94:97]
	v_mfma_f32_16x16x32_bf16 v[90:93], v[164:167], v[206:209], v[90:93]
	v_mfma_f32_16x16x32_bf16 v[78:81], v[150:153], v[214:217], v[78:81]
	v_mfma_f32_16x16x32_bf16 v[74:77], v[164:167], v[214:217], v[74:77]
	v_mfma_f32_16x16x32_bf16 v[118:121], v[168:171], v[184:187], v[118:121]
	v_mfma_f32_16x16x32_bf16 v[114:117], v[176:179], v[184:187], v[114:117]
	v_mfma_f32_16x16x32_bf16 v[102:105], v[168:171], v[192:195], v[102:105]
	v_mfma_f32_16x16x32_bf16 v[98:101], v[176:179], v[192:195], v[98:101]
	v_mfma_f32_16x16x32_bf16 v[86:89], v[168:171], v[202:205], v[86:89]
	v_mfma_f32_16x16x32_bf16 v[82:85], v[176:179], v[202:205], v[82:85]
	v_mfma_f32_16x16x32_bf16 v[70:73], v[168:171], v[210:213], v[70:73]
	v_mfma_f32_16x16x32_bf16 v[66:69], v[176:179], v[210:213], v[66:69]
	v_mfma_f32_16x16x32_bf16 v[118:121], v[172:175], v[188:191], v[118:121]
	v_mfma_f32_16x16x32_bf16 v[114:117], v[180:183], v[188:191], v[114:117]
	v_mfma_f32_16x16x32_bf16 v[102:105], v[172:175], v[198:201], v[102:105]
	v_mfma_f32_16x16x32_bf16 v[98:101], v[180:183], v[198:201], v[98:101]
	v_mfma_f32_16x16x32_bf16 v[86:89], v[172:175], v[206:209], v[86:89]
	v_mfma_f32_16x16x32_bf16 v[82:85], v[180:183], v[206:209], v[82:85]
	v_mfma_f32_16x16x32_bf16 v[70:73], v[172:175], v[214:217], v[70:73]
	v_mfma_f32_16x16x32_bf16 v[66:69], v[180:183], v[214:217], v[66:69]
	s_barrier
	s_add_u32 s44, s44, 0x80
	s_addc_u32 s45, s45, 0
	s_add_i32 m0, s48, 0x18000
	ds_read_b128 v[184:187], v158 offset:49152
	ds_read_b128 v[188:191], v158 offset:50176
	ds_read_b128 v[192:195], v158 offset:51200
	ds_read_b128 v[198:201], v158 offset:52224
	ds_read_b128 v[202:205], v158 offset:53248
	ds_read_b128 v[206:209], v158 offset:54272
	ds_read_b128 v[210:213], v158 offset:55296
	ds_read_b128 v[214:217], v158 offset:56320
	global_load_lds_dwordx4 v132, s[44:45]
	s_add_i32 m0, s48, 0x1a000
	s_add_u32 s46, s46, 0xffc00080
	global_load_lds_dwordx4 v136, s[44:45]
	s_addc_u32 s47, s47, -1
	s_add_u32 s44, s44, 0x400000
	s_addc_u32 s45, s45, 0
	s_add_i32 m0, s48, 0x1c000
	s_nop 0
	global_load_lds_dwordx4 v132, s[44:45]
	s_add_i32 m0, s48, 0x1e000
	s_nop 0
	global_load_lds_dwordx4 v136, s[44:45]
	s_mov_b32 m0, s53
	s_nop 0
	global_load_lds_dwordx4 v130, s[46:47]
	s_mov_b32 m0, s54
	s_nop 0
	global_load_lds_dwordx4 v134, s[46:47]
	s_waitcnt vmcnt(8)
	s_waitcnt lgkmcnt(0)
	s_barrier
	v_mfma_f32_16x16x32_bf16 v[62:65], v[146:149], v[184:187], v[62:65]
	v_mfma_f32_16x16x32_bf16 v[58:61], v[160:163], v[184:187], v[58:61]
	v_mfma_f32_16x16x32_bf16 v[46:49], v[146:149], v[192:195], v[46:49]
	v_mfma_f32_16x16x32_bf16 v[42:45], v[160:163], v[192:195], v[42:45]
	v_mfma_f32_16x16x32_bf16 v[30:33], v[146:149], v[202:205], v[30:33]
	v_mfma_f32_16x16x32_bf16 v[26:29], v[160:163], v[202:205], v[26:29]
	v_mfma_f32_16x16x32_bf16 v[14:17], v[146:149], v[210:213], v[14:17]
	v_mfma_f32_16x16x32_bf16 v[10:13], v[160:163], v[210:213], v[10:13]
	v_mfma_f32_16x16x32_bf16 v[62:65], v[150:153], v[188:191], v[62:65]
	v_mfma_f32_16x16x32_bf16 v[58:61], v[164:167], v[188:191], v[58:61]
	v_mfma_f32_16x16x32_bf16 v[46:49], v[150:153], v[198:201], v[46:49]
	v_mfma_f32_16x16x32_bf16 v[42:45], v[164:167], v[198:201], v[42:45]
	v_mfma_f32_16x16x32_bf16 v[30:33], v[150:153], v[206:209], v[30:33]
	v_mfma_f32_16x16x32_bf16 v[26:29], v[164:167], v[206:209], v[26:29]
	v_mfma_f32_16x16x32_bf16 v[14:17], v[150:153], v[214:217], v[14:17]
	v_mfma_f32_16x16x32_bf16 v[10:13], v[164:167], v[214:217], v[10:13]
	v_mfma_f32_16x16x32_bf16 v[54:57], v[168:171], v[184:187], v[54:57]
	v_mfma_f32_16x16x32_bf16 v[50:53], v[176:179], v[184:187], v[50:53]
	v_mfma_f32_16x16x32_bf16 v[38:41], v[168:171], v[192:195], v[38:41]
	v_mfma_f32_16x16x32_bf16 v[34:37], v[176:179], v[192:195], v[34:37]
	v_mfma_f32_16x16x32_bf16 v[22:25], v[168:171], v[202:205], v[22:25]
	v_mfma_f32_16x16x32_bf16 v[18:21], v[176:179], v[202:205], v[18:21]
	v_mfma_f32_16x16x32_bf16 v[6:9], v[168:171], v[210:213], v[6:9]
	v_mfma_f32_16x16x32_bf16 v[2:5], v[176:179], v[210:213], v[2:5]
	v_mfma_f32_16x16x32_bf16 v[54:57], v[172:175], v[188:191], v[54:57]
	v_mfma_f32_16x16x32_bf16 v[50:53], v[180:183], v[188:191], v[50:53]
	v_mfma_f32_16x16x32_bf16 v[38:41], v[172:175], v[198:201], v[38:41]
	v_mfma_f32_16x16x32_bf16 v[34:37], v[180:183], v[198:201], v[34:37]
	v_mfma_f32_16x16x32_bf16 v[22:25], v[172:175], v[206:209], v[22:25]
	v_mfma_f32_16x16x32_bf16 v[18:21], v[180:183], v[206:209], v[18:21]
	v_mfma_f32_16x16x32_bf16 v[6:9], v[172:175], v[214:217], v[6:9]
	v_mfma_f32_16x16x32_bf16 v[2:5], v[180:183], v[214:217], v[2:5]
	s_barrier
	s_add_i32 s67, s67, 2
	s_add_u32 s42, s42, 0x100
	s_addc_u32 s43, s43, 0
	s_add_u32 s65, s65, 0x100
	s_addc_u32 s66, s66, 0
	s_cmpk_gt_u32 s67, 0xfd
	s_cbranch_scc0 .LBB0_897
	s_and_b64 vcc, exec, s[14:15]
	s_cbranch_vccz .LBB0_900
	s_barrier

.LBB0_1104:
	s_or_b64 exec, exec, s[24:25]
	v_mov_b32_e32 v0, s93
	s_waitcnt lgkmcnt(0)
	s_barrier
	ds_read_b32 v0, v0
	s_waitcnt lgkmcnt(0)
	s_barrier
	s_waitcnt lgkmcnt(0)
	s_setprio 0
	v_readfirstlane_b32 s0, v0
	s_cmp_eq_u32 s0, -1
	s_cbranch_scc1 .LBB0_971
	s_lshl_b32 s1, s0, 3
	s_lshl_b32 s0, s0, 4
	s_and_b32 s0, s0, 0xff0
	v_readlane_b32 s2, v249, 38
	s_and_b32 s1, s1, 0xfffff800
	s_add_i32 s0, s0, s2
	s_add_i32 s24, s0, s1
	s_ashr_i32 s25, s24, 31
	s_lshl_b64 s[0:1], s[24:25], 13
	v_lshl_add_u64 v[0:1], v[20:21], 0, s[0:1]
	global_load_dwordx2 v[2:3], v[0:1], off
	global_load_dwordx2 v[4:5], v[0:1], off offset:512
	global_load_dwordx2 v[6:7], v[0:1], off offset:1024
	global_load_dwordx2 v[8:9], v[0:1], off offset:1536
	global_load_dwordx2 v[10:11], v[0:1], off offset:2048
	global_load_dwordx2 v[12:13], v[0:1], off offset:2560
	global_load_dwordx2 v[14:15], v[0:1], off offset:3072
	global_load_dwordx2 v[50:51], v[0:1], off offset:3584
	v_add_co_u32_e32 v0, vcc, s90, v0
	s_lshl_b64 s[46:47], s[24:25], 12
	s_nop 0
	v_addc_co_u32_e32 v1, vcc, 0, v1, vcc
	global_load_dwordx2 v[52:53], v[0:1], off
	global_load_dwordx2 v[54:55], v[0:1], off offset:512
	global_load_dwordx2 v[56:57], v[0:1], off offset:1024
	global_load_dwordx2 v[58:59], v[0:1], off offset:1536
	global_load_dwordx2 v[60:61], v[0:1], off offset:2048
	global_load_dwordx2 v[118:119], v[0:1], off offset:2560
	global_load_dwordx2 v[120:121], v[0:1], off offset:3072
	s_nop 0
	global_load_dwordx2 v[0:1], v[0:1], off offset:3584
	s_cmpk_lt_i32 s24, 0x4000
	s_waitcnt vmcnt(0)
	v_lshlrev_b32_e32 v110, 16, v2
	v_and_b32_e32 v111, 0xffff0000, v2
	v_lshlrev_b32_e32 v112, 16, v3
	v_and_b32_e32 v113, 0xffff0000, v3
	v_lshlrev_b32_e32 v106, 16, v4
	v_and_b32_e32 v107, 0xffff0000, v4
	v_lshlrev_b32_e32 v108, 16, v5
	v_and_b32_e32 v109, 0xffff0000, v5
	v_lshlrev_b32_e32 v102, 16, v6
	v_and_b32_e32 v103, 0xffff0000, v6
	v_lshlrev_b32_e32 v104, 16, v7
	v_and_b32_e32 v105, 0xffff0000, v7
	v_lshlrev_b32_e32 v98, 16, v8
	v_and_b32_e32 v99, 0xffff0000, v8
	v_lshlrev_b32_e32 v100, 16, v9
	v_and_b32_e32 v101, 0xffff0000, v9
	v_lshlrev_b32_e32 v94, 16, v10
	v_and_b32_e32 v95, 0xffff0000, v10
	v_lshlrev_b32_e32 v96, 16, v11
	v_and_b32_e32 v97, 0xffff0000, v11
	v_lshlrev_b32_e32 v90, 16, v12
	v_and_b32_e32 v91, 0xffff0000, v12
	v_lshlrev_b32_e32 v92, 16, v13
	v_and_b32_e32 v93, 0xffff0000, v13
	v_lshlrev_b32_e32 v86, 16, v14
	v_and_b32_e32 v87, 0xffff0000, v14
	v_lshlrev_b32_e32 v88, 16, v15
	v_and_b32_e32 v89, 0xffff0000, v15
	v_lshlrev_b32_e32 v82, 16, v50
	v_and_b32_e32 v83, 0xffff0000, v50
	v_lshlrev_b32_e32 v84, 16, v51
	v_and_b32_e32 v85, 0xffff0000, v51
	v_lshlrev_b32_e32 v78, 16, v52
	v_and_b32_e32 v79, 0xffff0000, v52
	v_lshlrev_b32_e32 v80, 16, v53
	v_and_b32_e32 v81, 0xffff0000, v53
	v_lshlrev_b32_e32 v74, 16, v54
	v_and_b32_e32 v75, 0xffff0000, v54
	v_lshlrev_b32_e32 v76, 16, v55
	v_and_b32_e32 v77, 0xffff0000, v55
	v_lshlrev_b32_e32 v70, 16, v56
	v_and_b32_e32 v71, 0xffff0000, v56
	v_lshlrev_b32_e32 v72, 16, v57
	v_and_b32_e32 v73, 0xffff0000, v57
	v_lshlrev_b32_e32 v66, 16, v58
	v_and_b32_e32 v67, 0xffff0000, v58
	v_lshlrev_b32_e32 v68, 16, v59
	v_and_b32_e32 v69, 0xffff0000, v59
	v_lshlrev_b32_e32 v62, 16, v60
	v_and_b32_e32 v63, 0xffff0000, v60
	v_lshlrev_b32_e32 v64, 16, v61
	v_and_b32_e32 v65, 0xffff0000, v61
	v_lshlrev_b32_e32 v58, 16, v118
	v_and_b32_e32 v59, 0xffff0000, v118
	v_lshlrev_b32_e32 v60, 16, v119
	v_and_b32_e32 v61, 0xffff0000, v119
	v_lshlrev_b32_e32 v54, 16, v120
	v_and_b32_e32 v55, 0xffff0000, v120
	v_lshlrev_b32_e32 v56, 16, v121
	v_and_b32_e32 v57, 0xffff0000, v121
	v_lshlrev_b32_e32 v50, 16, v0
	v_and_b32_e32 v51, 0xffff0000, v0
	v_lshlrev_b32_e32 v52, 16, v1
	v_and_b32_e32 v53, 0xffff0000, v1
	s_cbranch_scc1 .LBB0_1107
	s_add_i32 s2, s24, 0xffffc000
	s_lshl_b64 s[0:1], s[2:3], 14
	v_lshl_add_u64 v[198:199], v[22:23], 0, s[0:1]
	v_add_co_u32_e32 v158, vcc, s90, v198
	s_add_i32 s2, s24, 0xffffc800
	s_nop 0
	v_addc_co_u32_e32 v159, vcc, 0, v199, vcc
	s_lshl_b64 s[0:1], s[2:3], 14
	v_add_co_u32_e32 v186, vcc, s87, v198
	v_lshl_add_u64 v[202:203], v[22:23], 0, s[0:1]
	s_nop 0
	v_addc_co_u32_e32 v187, vcc, 0, v199, vcc
	global_load_dwordx4 v[0:3], v[198:199], off
	global_load_dwordx4 v[8:11], v[198:199], off offset:1024
	global_load_dwordx4 v[4:7], v[202:203], off
	global_load_dwordx4 v[12:15], v[202:203], off offset:1024
	global_load_dwordx4 v[118:121], v[198:199], off offset:2048
	global_load_dwordx4 v[122:125], v[198:199], off offset:3072
	global_load_dwordx4 v[126:129], v[202:203], off offset:2048
	global_load_dwordx4 v[130:133], v[202:203], off offset:3072
	global_load_dwordx4 v[134:137], v[186:187], off offset:-4096
	v_add_co_u32_e32 v194, vcc, s87, v202
	s_waitcnt vmcnt(8)
	v_pk_add_f32 v[2:3], v[2:3], v[112:113]
	v_addc_co_u32_e32 v195, vcc, 0, v203, vcc
	global_load_dwordx4 v[138:141], v[194:195], off offset:-4096
	global_load_dwordx4 v[142:145], v[158:159], off offset:1024
	v_add_co_u32_e32 v162, vcc, s90, v202
	v_pk_add_f32 v[0:1], v[0:1], v[110:111]
	s_nop 0
	v_addc_co_u32_e32 v163, vcc, 0, v203, vcc
	v_add_co_u32_e32 v222, vcc, s84, v198
	global_load_dwordx4 v[146:149], v[162:163], off offset:1024
	global_load_dwordx4 v[150:153], v[158:159], off offset:2048
	global_load_dwordx4 v[154:157], v[162:163], off offset:2048
	s_nop 0
	global_load_dwordx4 v[158:161], v[158:159], off offset:3072
	s_nop 0
	global_load_dwordx4 v[162:165], v[162:163], off offset:3072
	s_nop 0
	global_load_dwordx4 v[166:169], v[186:187], off
	global_load_dwordx4 v[170:173], v[194:195], off
	global_load_dwordx4 v[174:177], v[194:195], off offset:1024
	global_load_dwordx4 v[178:181], v[186:187], off offset:1024
	global_load_dwordx4 v[182:185], v[186:187], off offset:2048
	s_nop 0
	global_load_dwordx4 v[186:189], v[186:187], off offset:3072
	s_nop 0
	global_load_dwordx4 v[190:193], v[194:195], off offset:2048
	s_nop 0
	global_load_dwordx4 v[194:197], v[194:195], off offset:3072
	v_addc_co_u32_e32 v223, vcc, 0, v199, vcc
	global_load_dwordx4 v[198:201], v[222:223], off
	v_add_co_u32_e32 v226, vcc, s84, v202
	s_waitcnt vmcnt(22)
	v_pk_add_f32 v[112:113], v[2:3], v[6:7]
	v_addc_co_u32_e32 v227, vcc, 0, v203, vcc
	global_load_dwordx4 v[202:205], v[226:227], off
	global_load_dwordx4 v[206:209], v[222:223], off offset:1024
	global_load_dwordx4 v[210:213], v[226:227], off offset:1024
	global_load_dwordx4 v[214:217], v[222:223], off offset:2048
	global_load_dwordx4 v[218:221], v[226:227], off offset:2048
	s_nop 0
	global_load_dwordx4 v[222:225], v[222:223], off offset:3072
	s_nop 0
	global_load_dwordx4 v[226:229], v[226:227], off offset:3072
	v_pk_add_f32 v[110:111], v[0:1], v[4:5]
	s_waitcnt vmcnt(23)
	v_pk_add_f32 v[0:1], v[136:137], v[96:97]
	v_pk_add_f32 v[2:3], v[134:135], v[94:95]
	v_pk_add_f32 v[10:11], v[10:11], v[108:109]
	v_pk_add_f32 v[8:9], v[8:9], v[106:107]
	v_pk_add_f32 v[104:105], v[120:121], v[104:105]
	v_pk_add_f32 v[102:103], v[118:119], v[102:103]
	v_pk_add_f32 v[100:101], v[124:125], v[100:101]
	v_pk_add_f32 v[98:99], v[122:123], v[98:99]
	v_pk_add_f32 v[108:109], v[10:11], v[14:15]
	v_pk_add_f32 v[106:107], v[8:9], v[12:13]
	v_pk_add_f32 v[104:105], v[104:105], v[128:129]
	v_pk_add_f32 v[102:103], v[102:103], v[126:127]
	v_pk_add_f32 v[100:101], v[100:101], v[132:133]
	v_pk_add_f32 v[98:99], v[98:99], v[130:131]
	s_waitcnt vmcnt(22)
	v_pk_add_f32 v[96:97], v[0:1], v[140:141]
	v_pk_add_f32 v[94:95], v[2:3], v[138:139]
	s_waitcnt vmcnt(19)
	v_pk_add_f32 v[0:1], v[152:153], v[88:89]
	v_pk_add_f32 v[2:3], v[150:151], v[86:87]
	s_waitcnt vmcnt(18)
	v_pk_add_f32 v[88:89], v[0:1], v[156:157]
	v_pk_add_f32 v[86:87], v[2:3], v[154:155]
	s_waitcnt vmcnt(17)
	v_pk_add_f32 v[0:1], v[160:161], v[84:85]
	v_pk_add_f32 v[2:3], v[158:159], v[82:83]
	s_waitcnt vmcnt(16)
	v_pk_add_f32 v[84:85], v[0:1], v[164:165]
	v_pk_add_f32 v[82:83], v[2:3], v[162:163]
	s_waitcnt vmcnt(15)
	v_pk_add_f32 v[0:1], v[168:169], v[80:81]
	v_pk_add_f32 v[2:3], v[166:167], v[78:79]
	s_waitcnt vmcnt(14)
	v_pk_add_f32 v[80:81], v[0:1], v[172:173]
	v_pk_add_f32 v[78:79], v[2:3], v[170:171]
	s_waitcnt vmcnt(12)
	v_pk_add_f32 v[0:1], v[180:181], v[76:77]
	v_pk_add_f32 v[2:3], v[178:179], v[74:75]
	v_pk_add_f32 v[76:77], v[0:1], v[176:177]
	v_pk_add_f32 v[74:75], v[2:3], v[174:175]
	s_waitcnt vmcnt(11)
	v_pk_add_f32 v[0:1], v[184:185], v[72:73]
	v_pk_add_f32 v[2:3], v[182:183], v[70:71]
	s_waitcnt vmcnt(9)
	v_pk_add_f32 v[72:73], v[0:1], v[192:193]
	v_pk_add_f32 v[70:71], v[2:3], v[190:191]
	v_pk_add_f32 v[0:1], v[188:189], v[68:69]
	v_pk_add_f32 v[2:3], v[186:187], v[66:67]
	s_waitcnt vmcnt(8)
	v_pk_add_f32 v[68:69], v[0:1], v[196:197]
	v_pk_add_f32 v[66:67], v[2:3], v[194:195]
	s_waitcnt vmcnt(7)
	v_pk_add_f32 v[0:1], v[200:201], v[64:65]
	v_pk_add_f32 v[2:3], v[198:199], v[62:63]
	s_waitcnt vmcnt(6)
	v_pk_add_f32 v[64:65], v[0:1], v[204:205]
	v_pk_add_f32 v[62:63], v[2:3], v[202:203]
	s_waitcnt vmcnt(5)
	v_pk_add_f32 v[0:1], v[208:209], v[60:61]
	v_pk_add_f32 v[2:3], v[206:207], v[58:59]
	s_waitcnt vmcnt(4)
	v_pk_add_f32 v[60:61], v[0:1], v[212:213]
	v_pk_add_f32 v[58:59], v[2:3], v[210:211]
	s_waitcnt vmcnt(3)
	v_pk_add_f32 v[0:1], v[216:217], v[56:57]
	v_pk_add_f32 v[2:3], v[214:215], v[54:55]
	v_pk_add_f32 v[4:5], v[144:145], v[92:93]
	v_pk_add_f32 v[6:7], v[142:143], v[90:91]
	s_waitcnt vmcnt(2)
	v_pk_add_f32 v[56:57], v[0:1], v[220:221]
	v_pk_add_f32 v[54:55], v[2:3], v[218:219]
	s_waitcnt vmcnt(1)
	v_pk_add_f32 v[0:1], v[224:225], v[52:53]
	v_pk_add_f32 v[2:3], v[222:223], v[50:51]
	v_pk_add_f32 v[92:93], v[4:5], v[148:149]
	v_pk_add_f32 v[90:91], v[6:7], v[146:147]
	s_waitcnt vmcnt(0)
	v_pk_add_f32 v[52:53], v[0:1], v[228:229]
	v_pk_add_f32 v[50:51], v[2:3], v[226:227]
